# K-loops: leading waves defer the second B half (wait in front of the next post-read barrier, read behind it) and trailing waves defer the A low rows, so only half of each segment's DMAs must land by t
# baseline (speedup 1.0000x reference)
.LBB0_165:
	s_add_u32 s16, s14, 0xfff80080
	s_addc_u32 s17, s15, -1
	s_cmp_eq_u32 s64, 28
	s_cselect_b32 s19, s1, s17
	s_cselect_b32 s18, s4, s16
	s_cselect_b32 s17, s11, s21
	s_cselect_b32 s16, s13, s20
	s_and_b64 vcc, exec, s[36:37]
	s_cbranch_vccz .Lk64_trail_p1
	s_sub_u32 vcc_lo, s20, 0x80
	s_subb_u32 vcc_hi, s21, 0
	s_add_i32 m0, s23, 0x18000
	s_nop 0
	global_load_lds_dwordx4 v130, vcc
	s_add_i32 m0, s23, 0x1a000
	s_nop 0
	global_load_lds_dwordx4 v134, vcc
	s_add_u32 vcc_lo, vcc_lo, 0x20000
	s_addc_u32 vcc_hi, vcc_hi, 0
	s_add_i32 m0, s23, 0x19000
	s_nop 0
	global_load_lds_dwordx4 v130, vcc
	s_add_i32 m0, s23, 0x1b000
	s_nop 0
	global_load_lds_dwordx4 v134, vcc
	s_add_u32 vcc_lo, vcc_lo, 0x60000
	s_addc_u32 vcc_hi, vcc_hi, 0
	s_add_i32 m0, s23, 0x1c000
	s_nop 0
	global_load_lds_dwordx4 v130, vcc
	s_add_i32 m0, s23, 0x1e000
	s_nop 0
	global_load_lds_dwordx4 v134, vcc
	s_add_u32 vcc_lo, vcc_lo, 0x20000
	s_addc_u32 vcc_hi, vcc_hi, 0
	s_add_i32 m0, s23, 0x1d000
	s_nop 0
	global_load_lds_dwordx4 v130, vcc
	s_add_i32 m0, s23, 0x1f000
	s_nop 0
	global_load_lds_dwordx4 v134, vcc
	ds_read_b128 v[148:151], v168 offset:0
	ds_read_b128 v[152:155], v168 offset:1024
	ds_read_b128 v[156:159], v168 offset:2048
	ds_read_b128 v[172:175], v168 offset:3072
	ds_read_b128 v[192:195], v170 offset:0
	ds_read_b128 v[196:199], v170 offset:1024
	ds_read_b128 v[200:203], v170 offset:2048
	ds_read_b128 v[204:207], v170 offset:3072
	ds_read_b128 v[208:211], v170 offset:4096
	ds_read_b128 v[212:215], v170 offset:5120
	ds_read_b128 v[216:219], v170 offset:6144
	ds_read_b128 v[220:223], v170 offset:7168
	ds_read_b128 v[142:145], v170 offset:16384
	ds_read_b128 v[224:227], v170 offset:17408
	ds_read_b128 v[228:231], v170 offset:18432
	ds_read_b128 v[232:235], v170 offset:19456
	ds_read_b128 v[236:239], v170 offset:20480
	ds_read_b128 v[240:243], v170 offset:21504
	ds_read_b128 v[244:247], v170 offset:22528
	ds_read_b128 v[248:251], v170 offset:23552
	s_nop 15
	s_nop 15
	s_waitcnt vmcnt(8) lgkmcnt(0)
	s_barrier
	ds_read_b128 v[176:179], v169 offset:0
	ds_read_b128 v[180:183], v169 offset:1024
	ds_read_b128 v[184:187], v169 offset:2048
	ds_read_b128 v[188:191], v169 offset:3072
	s_setprio 1
	v_mfma_f32_16x16x32_bf16 v[124:127], v[148:151], v[192:195], v[124:127]
	v_mfma_f32_16x16x32_bf16 v[120:123], v[156:159], v[192:195], v[120:123]
	v_mfma_f32_16x16x32_bf16 v[116:119], v[148:151], v[200:203], v[116:119]
	v_mfma_f32_16x16x32_bf16 v[112:115], v[156:159], v[200:203], v[112:115]
	v_mfma_f32_16x16x32_bf16 v[100:103], v[148:151], v[208:211], v[100:103]
	v_mfma_f32_16x16x32_bf16 v[96:99], v[156:159], v[208:211], v[96:99]
	v_mfma_f32_16x16x32_bf16 v[84:87], v[148:151], v[216:219], v[84:87]
	v_mfma_f32_16x16x32_bf16 v[80:83], v[156:159], v[216:219], v[80:83]
	v_mfma_f32_16x16x32_bf16 v[124:127], v[152:155], v[196:199], v[124:127]
	v_mfma_f32_16x16x32_bf16 v[120:123], v[172:175], v[196:199], v[120:123]
	v_mfma_f32_16x16x32_bf16 v[116:119], v[152:155], v[204:207], v[116:119]
	v_mfma_f32_16x16x32_bf16 v[112:115], v[172:175], v[204:207], v[112:115]
	v_mfma_f32_16x16x32_bf16 v[100:103], v[152:155], v[212:215], v[100:103]
	v_mfma_f32_16x16x32_bf16 v[96:99], v[172:175], v[212:215], v[96:99]
	v_mfma_f32_16x16x32_bf16 v[84:87], v[152:155], v[220:223], v[84:87]
	v_mfma_f32_16x16x32_bf16 v[80:83], v[172:175], v[220:223], v[80:83]
	s_setprio 0
	s_waitcnt lgkmcnt(0)
	s_setprio 1
	v_mfma_f32_16x16x32_bf16 v[108:111], v[176:179], v[192:195], v[108:111]
	v_mfma_f32_16x16x32_bf16 v[104:107], v[184:187], v[192:195], v[104:107]
	v_mfma_f32_16x16x32_bf16 v[92:95], v[176:179], v[200:203], v[92:95]
	v_mfma_f32_16x16x32_bf16 v[88:91], v[184:187], v[200:203], v[88:91]
	v_mfma_f32_16x16x32_bf16 v[76:79], v[176:179], v[208:211], v[76:79]
	v_mfma_f32_16x16x32_bf16 v[72:75], v[184:187], v[208:211], v[72:75]
	v_mfma_f32_16x16x32_bf16 v[68:71], v[176:179], v[216:219], v[68:71]
	v_mfma_f32_16x16x32_bf16 v[64:67], v[184:187], v[216:219], v[64:67]
	v_mfma_f32_16x16x32_bf16 v[108:111], v[180:183], v[196:199], v[108:111]
	v_mfma_f32_16x16x32_bf16 v[104:107], v[188:191], v[196:199], v[104:107]
	v_mfma_f32_16x16x32_bf16 v[92:95], v[180:183], v[204:207], v[92:95]
	v_mfma_f32_16x16x32_bf16 v[88:91], v[188:191], v[204:207], v[88:91]
	v_mfma_f32_16x16x32_bf16 v[76:79], v[180:183], v[212:215], v[76:79]
	v_mfma_f32_16x16x32_bf16 v[72:75], v[188:191], v[212:215], v[72:75]
	v_mfma_f32_16x16x32_bf16 v[68:71], v[180:183], v[220:223], v[68:71]
	v_mfma_f32_16x16x32_bf16 v[64:67], v[188:191], v[220:223], v[64:67]
	s_setprio 0
	s_setprio 1
	v_mfma_f32_16x16x32_bf16 v[60:63], v[148:151], v[142:145], v[60:63]
	v_mfma_f32_16x16x32_bf16 v[56:59], v[156:159], v[142:145], v[56:59]
	v_mfma_f32_16x16x32_bf16 v[52:55], v[148:151], v[228:231], v[52:55]
	v_mfma_f32_16x16x32_bf16 v[48:51], v[156:159], v[228:231], v[48:51]
	v_mfma_f32_16x16x32_bf16 v[36:39], v[148:151], v[236:239], v[36:39]
	v_mfma_f32_16x16x32_bf16 v[32:35], v[156:159], v[236:239], v[32:35]
	v_mfma_f32_16x16x32_bf16 v[20:23], v[148:151], v[244:247], v[20:23]
	v_mfma_f32_16x16x32_bf16 v[16:19], v[156:159], v[244:247], v[16:19]
	v_mfma_f32_16x16x32_bf16 v[60:63], v[152:155], v[224:227], v[60:63]
	v_mfma_f32_16x16x32_bf16 v[56:59], v[172:175], v[224:227], v[56:59]
	v_mfma_f32_16x16x32_bf16 v[52:55], v[152:155], v[232:235], v[52:55]
	v_mfma_f32_16x16x32_bf16 v[48:51], v[172:175], v[232:235], v[48:51]
	v_mfma_f32_16x16x32_bf16 v[36:39], v[152:155], v[240:243], v[36:39]
	v_mfma_f32_16x16x32_bf16 v[32:35], v[172:175], v[240:243], v[32:35]
	v_mfma_f32_16x16x32_bf16 v[20:23], v[152:155], v[248:251], v[20:23]
	v_mfma_f32_16x16x32_bf16 v[16:19], v[172:175], v[248:251], v[16:19]
	s_setprio 0
	s_setprio 1
	v_mfma_f32_16x16x32_bf16 v[44:47], v[176:179], v[142:145], v[44:47]
	v_mfma_f32_16x16x32_bf16 v[40:43], v[184:187], v[142:145], v[40:43]
	v_mfma_f32_16x16x32_bf16 v[28:31], v[176:179], v[228:231], v[28:31]
	v_mfma_f32_16x16x32_bf16 v[24:27], v[184:187], v[228:231], v[24:27]
	v_mfma_f32_16x16x32_bf16 v[12:15], v[176:179], v[236:239], v[12:15]
	v_mfma_f32_16x16x32_bf16 v[8:11], v[184:187], v[236:239], v[8:11]
	v_mfma_f32_16x16x32_bf16 v[4:7], v[176:179], v[244:247], v[4:7]
	v_mfma_f32_16x16x32_bf16 v[0:3], v[184:187], v[244:247], v[0:3]
	v_mfma_f32_16x16x32_bf16 v[44:47], v[180:183], v[224:227], v[44:47]
	v_mfma_f32_16x16x32_bf16 v[40:43], v[188:191], v[224:227], v[40:43]
	v_mfma_f32_16x16x32_bf16 v[28:31], v[180:183], v[232:235], v[28:31]
	v_mfma_f32_16x16x32_bf16 v[24:27], v[188:191], v[232:235], v[24:27]
	v_mfma_f32_16x16x32_bf16 v[12:15], v[180:183], v[240:243], v[12:15]
	v_mfma_f32_16x16x32_bf16 v[8:11], v[188:191], v[240:243], v[8:11]
	v_mfma_f32_16x16x32_bf16 v[4:7], v[180:183], v[248:251], v[4:7]
	v_mfma_f32_16x16x32_bf16 v[0:3], v[188:191], v[248:251], v[0:3]
	s_setprio 0
	s_waitcnt vmcnt(4)
	s_barrier
	s_add_u32 vcc_lo, s16, 0x0
	s_addc_u32 vcc_hi, s17, 0
	s_add_i32 m0, s23, 0x10000
	s_nop 0
	global_load_lds_dwordx4 v130, vcc
	s_add_i32 m0, s23, 0x12000
	s_nop 0
	global_load_lds_dwordx4 v134, vcc
	s_add_u32 vcc_lo, vcc_lo, 0x20000
	s_addc_u32 vcc_hi, vcc_hi, 0
	s_add_i32 m0, s23, 0x11000
	s_nop 0
	global_load_lds_dwordx4 v130, vcc
	s_add_i32 m0, s23, 0x13000
	s_nop 0
	global_load_lds_dwordx4 v134, vcc
	s_add_u32 vcc_lo, vcc_lo, 0x60000
	s_addc_u32 vcc_hi, vcc_hi, 0
	s_add_i32 m0, s23, 0x14000
	s_nop 0
	global_load_lds_dwordx4 v130, vcc
	s_add_i32 m0, s23, 0x16000
	s_nop 0
	global_load_lds_dwordx4 v134, vcc
	s_add_u32 vcc_lo, vcc_lo, 0x20000
	s_addc_u32 vcc_hi, vcc_hi, 0
	s_add_i32 m0, s23, 0x15000
	s_nop 0
	global_load_lds_dwordx4 v130, vcc
	s_add_i32 m0, s23, 0x17000
	s_nop 0
	global_load_lds_dwordx4 v134, vcc
	ds_read_b128 v[148:151], v168 offset:32768
	ds_read_b128 v[152:155], v168 offset:33792
	ds_read_b128 v[156:159], v168 offset:34816
	ds_read_b128 v[172:175], v168 offset:35840
	ds_read_b128 v[192:195], v170 offset:32768
	ds_read_b128 v[196:199], v170 offset:33792
	ds_read_b128 v[200:203], v170 offset:34816
	ds_read_b128 v[204:207], v170 offset:35840
	ds_read_b128 v[208:211], v170 offset:36864
	ds_read_b128 v[212:215], v170 offset:37888
	ds_read_b128 v[216:219], v170 offset:38912
	ds_read_b128 v[220:223], v170 offset:39936
	ds_read_b128 v[142:145], v170 offset:49152
	ds_read_b128 v[224:227], v170 offset:50176
	ds_read_b128 v[228:231], v170 offset:51200
	ds_read_b128 v[232:235], v170 offset:52224
	ds_read_b128 v[236:239], v170 offset:53248
	ds_read_b128 v[240:243], v170 offset:54272
	ds_read_b128 v[244:247], v170 offset:55296
	ds_read_b128 v[248:251], v170 offset:56320
	s_nop 15
	s_nop 15
	s_waitcnt vmcnt(8) lgkmcnt(0)
	s_barrier
	ds_read_b128 v[176:179], v169 offset:32768
	ds_read_b128 v[180:183], v169 offset:33792
	ds_read_b128 v[184:187], v169 offset:34816
	ds_read_b128 v[188:191], v169 offset:35840
	s_setprio 1
	v_mfma_f32_16x16x32_bf16 v[124:127], v[148:151], v[192:195], v[124:127]
	v_mfma_f32_16x16x32_bf16 v[120:123], v[156:159], v[192:195], v[120:123]
	v_mfma_f32_16x16x32_bf16 v[116:119], v[148:151], v[200:203], v[116:119]
	v_mfma_f32_16x16x32_bf16 v[112:115], v[156:159], v[200:203], v[112:115]
	v_mfma_f32_16x16x32_bf16 v[100:103], v[148:151], v[208:211], v[100:103]
	v_mfma_f32_16x16x32_bf16 v[96:99], v[156:159], v[208:211], v[96:99]
	v_mfma_f32_16x16x32_bf16 v[84:87], v[148:151], v[216:219], v[84:87]
	v_mfma_f32_16x16x32_bf16 v[80:83], v[156:159], v[216:219], v[80:83]
	v_mfma_f32_16x16x32_bf16 v[124:127], v[152:155], v[196:199], v[124:127]
	v_mfma_f32_16x16x32_bf16 v[120:123], v[172:175], v[196:199], v[120:123]
	v_mfma_f32_16x16x32_bf16 v[116:119], v[152:155], v[204:207], v[116:119]
	v_mfma_f32_16x16x32_bf16 v[112:115], v[172:175], v[204:207], v[112:115]
	v_mfma_f32_16x16x32_bf16 v[100:103], v[152:155], v[212:215], v[100:103]
	v_mfma_f32_16x16x32_bf16 v[96:99], v[172:175], v[212:215], v[96:99]
	v_mfma_f32_16x16x32_bf16 v[84:87], v[152:155], v[220:223], v[84:87]
	v_mfma_f32_16x16x32_bf16 v[80:83], v[172:175], v[220:223], v[80:83]
	s_setprio 0
	s_waitcnt lgkmcnt(0)
	s_setprio 1
	v_mfma_f32_16x16x32_bf16 v[108:111], v[176:179], v[192:195], v[108:111]
	v_mfma_f32_16x16x32_bf16 v[104:107], v[184:187], v[192:195], v[104:107]
	v_mfma_f32_16x16x32_bf16 v[92:95], v[176:179], v[200:203], v[92:95]
	v_mfma_f32_16x16x32_bf16 v[88:91], v[184:187], v[200:203], v[88:91]
	v_mfma_f32_16x16x32_bf16 v[76:79], v[176:179], v[208:211], v[76:79]
	v_mfma_f32_16x16x32_bf16 v[72:75], v[184:187], v[208:211], v[72:75]
	v_mfma_f32_16x16x32_bf16 v[68:71], v[176:179], v[216:219], v[68:71]
	v_mfma_f32_16x16x32_bf16 v[64:67], v[184:187], v[216:219], v[64:67]
	v_mfma_f32_16x16x32_bf16 v[108:111], v[180:183], v[196:199], v[108:111]
	v_mfma_f32_16x16x32_bf16 v[104:107], v[188:191], v[196:199], v[104:107]
	v_mfma_f32_16x16x32_bf16 v[92:95], v[180:183], v[204:207], v[92:95]
	v_mfma_f32_16x16x32_bf16 v[88:91], v[188:191], v[204:207], v[88:91]
	v_mfma_f32_16x16x32_bf16 v[76:79], v[180:183], v[212:215], v[76:79]
	v_mfma_f32_16x16x32_bf16 v[72:75], v[188:191], v[212:215], v[72:75]
	v_mfma_f32_16x16x32_bf16 v[68:71], v[180:183], v[220:223], v[68:71]
	v_mfma_f32_16x16x32_bf16 v[64:67], v[188:191], v[220:223], v[64:67]
	s_setprio 0
	s_setprio 1
	v_mfma_f32_16x16x32_bf16 v[60:63], v[148:151], v[142:145], v[60:63]
	v_mfma_f32_16x16x32_bf16 v[56:59], v[156:159], v[142:145], v[56:59]
	v_mfma_f32_16x16x32_bf16 v[52:55], v[148:151], v[228:231], v[52:55]
	v_mfma_f32_16x16x32_bf16 v[48:51], v[156:159], v[228:231], v[48:51]
	v_mfma_f32_16x16x32_bf16 v[36:39], v[148:151], v[236:239], v[36:39]
	v_mfma_f32_16x16x32_bf16 v[32:35], v[156:159], v[236:239], v[32:35]
	v_mfma_f32_16x16x32_bf16 v[20:23], v[148:151], v[244:247], v[20:23]
	v_mfma_f32_16x16x32_bf16 v[16:19], v[156:159], v[244:247], v[16:19]
	v_mfma_f32_16x16x32_bf16 v[60:63], v[152:155], v[224:227], v[60:63]
	v_mfma_f32_16x16x32_bf16 v[56:59], v[172:175], v[224:227], v[56:59]
	v_mfma_f32_16x16x32_bf16 v[52:55], v[152:155], v[232:235], v[52:55]
	v_mfma_f32_16x16x32_bf16 v[48:51], v[172:175], v[232:235], v[48:51]
	v_mfma_f32_16x16x32_bf16 v[36:39], v[152:155], v[240:243], v[36:39]
	v_mfma_f32_16x16x32_bf16 v[32:35], v[172:175], v[240:243], v[32:35]
	v_mfma_f32_16x16x32_bf16 v[20:23], v[152:155], v[248:251], v[20:23]
	v_mfma_f32_16x16x32_bf16 v[16:19], v[172:175], v[248:251], v[16:19]
	s_setprio 0
	s_setprio 1
	v_mfma_f32_16x16x32_bf16 v[44:47], v[176:179], v[142:145], v[44:47]
	v_mfma_f32_16x16x32_bf16 v[40:43], v[184:187], v[142:145], v[40:43]
	v_mfma_f32_16x16x32_bf16 v[28:31], v[176:179], v[228:231], v[28:31]
	v_mfma_f32_16x16x32_bf16 v[24:27], v[184:187], v[228:231], v[24:27]
	v_mfma_f32_16x16x32_bf16 v[12:15], v[176:179], v[236:239], v[12:15]
	v_mfma_f32_16x16x32_bf16 v[8:11], v[184:187], v[236:239], v[8:11]
	v_mfma_f32_16x16x32_bf16 v[4:7], v[176:179], v[244:247], v[4:7]
	v_mfma_f32_16x16x32_bf16 v[0:3], v[184:187], v[244:247], v[0:3]
	v_mfma_f32_16x16x32_bf16 v[44:47], v[180:183], v[224:227], v[44:47]
	v_mfma_f32_16x16x32_bf16 v[40:43], v[188:191], v[224:227], v[40:43]
	v_mfma_f32_16x16x32_bf16 v[28:31], v[180:183], v[232:235], v[28:31]
	v_mfma_f32_16x16x32_bf16 v[24:27], v[188:191], v[232:235], v[24:27]
	v_mfma_f32_16x16x32_bf16 v[12:15], v[180:183], v[240:243], v[12:15]
	v_mfma_f32_16x16x32_bf16 v[8:11], v[188:191], v[240:243], v[8:11]
	v_mfma_f32_16x16x32_bf16 v[4:7], v[180:183], v[248:251], v[4:7]
	v_mfma_f32_16x16x32_bf16 v[0:3], v[188:191], v[248:251], v[0:3]
	s_setprio 0
	s_waitcnt vmcnt(4)
	s_barrier
	s_add_i32 s64, s64, 2
	s_add_u32 s14, s14, 0x100
	s_addc_u32 s15, s15, 0
	s_add_u32 s20, s20, 0x100
	s_addc_u32 s21, s21, 0
	s_cmp_gt_u32 s64, 29
	s_cbranch_scc0 .LBB0_165
	s_branch .Lk64_done_p1
.Lk64_trail_p1:
	s_sub_u32 vcc_lo, s14, 0x80000
	s_subb_u32 vcc_hi, s15, 0
	s_add_i32 m0, s23, 0xa000
	s_nop 0
	global_load_lds_dwordx4 v132, vcc
	s_add_u32 vcc_lo, vcc_lo, 0x20000
	s_addc_u32 vcc_hi, vcc_hi, 0
	s_add_i32 m0, s23, 0x9000
	s_nop 0
	global_load_lds_dwordx4 v128, vcc
	s_add_u32 vcc_lo, vcc_lo, 0x60000
	s_addc_u32 vcc_hi, vcc_hi, 0
	s_add_i32 m0, s23, 0xe000
	s_nop 0
	global_load_lds_dwordx4 v132, vcc
	s_add_u32 vcc_lo, vcc_lo, 0x20000
	s_addc_u32 vcc_hi, vcc_hi, 0
	s_add_i32 m0, s23, 0xd000
	s_nop 0
	global_load_lds_dwordx4 v128, vcc
	s_add_u32 vcc_lo, s18, 0x0
	s_addc_u32 vcc_hi, s19, 0
	s_mov_b32 m0, s23
	s_nop 0
	global_load_lds_dwordx4 v128, vcc
	s_sub_u32 vcc_lo, vcc_lo, 0x20000
	s_subb_u32 vcc_hi, vcc_hi, 0
	s_sub_i32 m0, s23, 0x1000
	s_nop 0
	global_load_lds_dwordx4 v128, vcc
	s_add_u32 vcc_lo, vcc_lo, 0xa0000
	s_addc_u32 vcc_hi, vcc_hi, 0
	s_add_i32 m0, s23, 0x4000
	s_nop 0
	global_load_lds_dwordx4 v128, vcc
	s_sub_u32 vcc_lo, vcc_lo, 0x20000
	s_subb_u32 vcc_hi, vcc_hi, 0
	s_add_i32 m0, s23, 0x3000
	s_nop 0
	global_load_lds_dwordx4 v128, vcc
	ds_read_b128 v[148:151], v168 offset:0
	ds_read_b128 v[152:155], v168 offset:1024
	ds_read_b128 v[156:159], v168 offset:2048
	ds_read_b128 v[172:175], v168 offset:3072
	ds_read_b128 v[176:179], v169 offset:0
	ds_read_b128 v[180:183], v169 offset:1024
	ds_read_b128 v[184:187], v169 offset:2048
	ds_read_b128 v[188:191], v169 offset:3072
	ds_read_b128 v[192:195], v170 offset:0
	ds_read_b128 v[196:199], v170 offset:1024
	ds_read_b128 v[200:203], v170 offset:2048
	ds_read_b128 v[204:207], v170 offset:3072
	ds_read_b128 v[208:211], v170 offset:4096
	ds_read_b128 v[212:215], v170 offset:5120
	ds_read_b128 v[216:219], v170 offset:6144
	ds_read_b128 v[220:223], v170 offset:7168
	ds_read_b128 v[142:145], v170 offset:16384
	ds_read_b128 v[224:227], v170 offset:17408
	ds_read_b128 v[228:231], v170 offset:18432
	ds_read_b128 v[232:235], v170 offset:19456
	ds_read_b128 v[236:239], v170 offset:20480
	ds_read_b128 v[240:243], v170 offset:21504
	ds_read_b128 v[244:247], v170 offset:22528
	ds_read_b128 v[248:251], v170 offset:23552
	s_nop 15
	s_nop 15
	s_waitcnt vmcnt(8) lgkmcnt(0)
	s_barrier
	s_setprio 1
	v_mfma_f32_16x16x32_bf16 v[124:127], v[148:151], v[192:195], v[124:127]
	v_mfma_f32_16x16x32_bf16 v[120:123], v[156:159], v[192:195], v[120:123]
	v_mfma_f32_16x16x32_bf16 v[116:119], v[148:151], v[200:203], v[116:119]
	v_mfma_f32_16x16x32_bf16 v[112:115], v[156:159], v[200:203], v[112:115]
	v_mfma_f32_16x16x32_bf16 v[100:103], v[148:151], v[208:211], v[100:103]
	v_mfma_f32_16x16x32_bf16 v[96:99], v[156:159], v[208:211], v[96:99]
	v_mfma_f32_16x16x32_bf16 v[84:87], v[148:151], v[216:219], v[84:87]
	v_mfma_f32_16x16x32_bf16 v[80:83], v[156:159], v[216:219], v[80:83]
	v_mfma_f32_16x16x32_bf16 v[124:127], v[152:155], v[196:199], v[124:127]
	v_mfma_f32_16x16x32_bf16 v[120:123], v[172:175], v[196:199], v[120:123]
	v_mfma_f32_16x16x32_bf16 v[116:119], v[152:155], v[204:207], v[116:119]
	v_mfma_f32_16x16x32_bf16 v[112:115], v[172:175], v[204:207], v[112:115]
	v_mfma_f32_16x16x32_bf16 v[100:103], v[152:155], v[212:215], v[100:103]
	v_mfma_f32_16x16x32_bf16 v[96:99], v[172:175], v[212:215], v[96:99]
	v_mfma_f32_16x16x32_bf16 v[84:87], v[152:155], v[220:223], v[84:87]
	v_mfma_f32_16x16x32_bf16 v[80:83], v[172:175], v[220:223], v[80:83]
	s_setprio 0
	s_setprio 1
	v_mfma_f32_16x16x32_bf16 v[108:111], v[176:179], v[192:195], v[108:111]
	v_mfma_f32_16x16x32_bf16 v[104:107], v[184:187], v[192:195], v[104:107]
	v_mfma_f32_16x16x32_bf16 v[92:95], v[176:179], v[200:203], v[92:95]
	v_mfma_f32_16x16x32_bf16 v[88:91], v[184:187], v[200:203], v[88:91]
	v_mfma_f32_16x16x32_bf16 v[76:79], v[176:179], v[208:211], v[76:79]
	v_mfma_f32_16x16x32_bf16 v[72:75], v[184:187], v[208:211], v[72:75]
	v_mfma_f32_16x16x32_bf16 v[68:71], v[176:179], v[216:219], v[68:71]
	v_mfma_f32_16x16x32_bf16 v[64:67], v[184:187], v[216:219], v[64:67]
	v_mfma_f32_16x16x32_bf16 v[108:111], v[180:183], v[196:199], v[108:111]
	v_mfma_f32_16x16x32_bf16 v[104:107], v[188:191], v[196:199], v[104:107]
	v_mfma_f32_16x16x32_bf16 v[92:95], v[180:183], v[204:207], v[92:95]
	v_mfma_f32_16x16x32_bf16 v[88:91], v[188:191], v[204:207], v[88:91]
	v_mfma_f32_16x16x32_bf16 v[76:79], v[180:183], v[212:215], v[76:79]
	v_mfma_f32_16x16x32_bf16 v[72:75], v[188:191], v[212:215], v[72:75]
	v_mfma_f32_16x16x32_bf16 v[68:71], v[180:183], v[220:223], v[68:71]
	v_mfma_f32_16x16x32_bf16 v[64:67], v[188:191], v[220:223], v[64:67]
	s_setprio 0
	s_setprio 1
	v_mfma_f32_16x16x32_bf16 v[60:63], v[148:151], v[142:145], v[60:63]
	v_mfma_f32_16x16x32_bf16 v[56:59], v[156:159], v[142:145], v[56:59]
	v_mfma_f32_16x16x32_bf16 v[52:55], v[148:151], v[228:231], v[52:55]
	v_mfma_f32_16x16x32_bf16 v[48:51], v[156:159], v[228:231], v[48:51]
	v_mfma_f32_16x16x32_bf16 v[36:39], v[148:151], v[236:239], v[36:39]
	v_mfma_f32_16x16x32_bf16 v[32:35], v[156:159], v[236:239], v[32:35]
	v_mfma_f32_16x16x32_bf16 v[20:23], v[148:151], v[244:247], v[20:23]
	v_mfma_f32_16x16x32_bf16 v[16:19], v[156:159], v[244:247], v[16:19]
	v_mfma_f32_16x16x32_bf16 v[60:63], v[152:155], v[224:227], v[60:63]
	v_mfma_f32_16x16x32_bf16 v[56:59], v[172:175], v[224:227], v[56:59]
	v_mfma_f32_16x16x32_bf16 v[52:55], v[152:155], v[232:235], v[52:55]
	v_mfma_f32_16x16x32_bf16 v[48:51], v[172:175], v[232:235], v[48:51]
	v_mfma_f32_16x16x32_bf16 v[36:39], v[152:155], v[240:243], v[36:39]
	v_mfma_f32_16x16x32_bf16 v[32:35], v[172:175], v[240:243], v[32:35]
	v_mfma_f32_16x16x32_bf16 v[20:23], v[152:155], v[248:251], v[20:23]
	v_mfma_f32_16x16x32_bf16 v[16:19], v[172:175], v[248:251], v[16:19]
	s_setprio 0
	s_setprio 1
	v_mfma_f32_16x16x32_bf16 v[44:47], v[176:179], v[142:145], v[44:47]
	v_mfma_f32_16x16x32_bf16 v[40:43], v[184:187], v[142:145], v[40:43]
	v_mfma_f32_16x16x32_bf16 v[28:31], v[176:179], v[228:231], v[28:31]
	v_mfma_f32_16x16x32_bf16 v[24:27], v[184:187], v[228:231], v[24:27]
	v_mfma_f32_16x16x32_bf16 v[12:15], v[176:179], v[236:239], v[12:15]
	v_mfma_f32_16x16x32_bf16 v[8:11], v[184:187], v[236:239], v[8:11]
	v_mfma_f32_16x16x32_bf16 v[4:7], v[176:179], v[244:247], v[4:7]
	v_mfma_f32_16x16x32_bf16 v[0:3], v[184:187], v[244:247], v[0:3]
	v_mfma_f32_16x16x32_bf16 v[44:47], v[180:183], v[224:227], v[44:47]
	v_mfma_f32_16x16x32_bf16 v[40:43], v[188:191], v[224:227], v[40:43]
	v_mfma_f32_16x16x32_bf16 v[28:31], v[180:183], v[232:235], v[28:31]
	v_mfma_f32_16x16x32_bf16 v[24:27], v[188:191], v[232:235], v[24:27]
	v_mfma_f32_16x16x32_bf16 v[12:15], v[180:183], v[240:243], v[12:15]
	v_mfma_f32_16x16x32_bf16 v[8:11], v[188:191], v[240:243], v[8:11]
	v_mfma_f32_16x16x32_bf16 v[4:7], v[180:183], v[248:251], v[4:7]
	v_mfma_f32_16x16x32_bf16 v[0:3], v[188:191], v[248:251], v[0:3]
	s_setprio 0
	s_waitcnt vmcnt(4)
	s_barrier
	s_add_u32 vcc_lo, s18, 0x0
	s_addc_u32 vcc_hi, s19, 0
	s_add_i32 m0, s23, 0x2000
	s_nop 0
	global_load_lds_dwordx4 v132, vcc
	s_add_u32 vcc_lo, vcc_lo, 0x20000
	s_addc_u32 vcc_hi, vcc_hi, 0
	s_add_i32 m0, s23, 0x1000
	s_nop 0
	global_load_lds_dwordx4 v128, vcc
	s_add_u32 vcc_lo, vcc_lo, 0x60000
	s_addc_u32 vcc_hi, vcc_hi, 0
	s_add_i32 m0, s23, 0x6000
	s_nop 0
	global_load_lds_dwordx4 v132, vcc
	s_add_u32 vcc_lo, vcc_lo, 0x20000
	s_addc_u32 vcc_hi, vcc_hi, 0
	s_add_i32 m0, s23, 0x5000
	s_nop 0
	global_load_lds_dwordx4 v128, vcc
	s_add_u32 vcc_lo, s18, 0x80
	s_addc_u32 vcc_hi, s19, 0
	s_add_i32 m0, s23, 0x8000
	s_nop 0
	global_load_lds_dwordx4 v128, vcc
	s_sub_u32 vcc_lo, vcc_lo, 0x20000
	s_subb_u32 vcc_hi, vcc_hi, 0
	s_add_i32 m0, s23, 0x7000
	s_nop 0
	global_load_lds_dwordx4 v128, vcc
	s_add_u32 vcc_lo, vcc_lo, 0xa0000
	s_addc_u32 vcc_hi, vcc_hi, 0
	s_add_i32 m0, s23, 0xc000
	s_nop 0
	global_load_lds_dwordx4 v128, vcc
	s_sub_u32 vcc_lo, vcc_lo, 0x20000
	s_subb_u32 vcc_hi, vcc_hi, 0
	s_add_i32 m0, s23, 0xb000
	s_nop 0
	global_load_lds_dwordx4 v128, vcc
	ds_read_b128 v[148:151], v168 offset:32768
	ds_read_b128 v[152:155], v168 offset:33792
	ds_read_b128 v[156:159], v168 offset:34816
	ds_read_b128 v[172:175], v168 offset:35840
	ds_read_b128 v[176:179], v169 offset:32768
	ds_read_b128 v[180:183], v169 offset:33792
	ds_read_b128 v[184:187], v169 offset:34816
	ds_read_b128 v[188:191], v169 offset:35840
	ds_read_b128 v[192:195], v170 offset:32768
	ds_read_b128 v[196:199], v170 offset:33792
	ds_read_b128 v[200:203], v170 offset:34816
	ds_read_b128 v[204:207], v170 offset:35840
	ds_read_b128 v[208:211], v170 offset:36864
	ds_read_b128 v[212:215], v170 offset:37888
	ds_read_b128 v[216:219], v170 offset:38912
	ds_read_b128 v[220:223], v170 offset:39936
	ds_read_b128 v[142:145], v170 offset:49152
	ds_read_b128 v[224:227], v170 offset:50176
	ds_read_b128 v[228:231], v170 offset:51200
	ds_read_b128 v[232:235], v170 offset:52224
	ds_read_b128 v[236:239], v170 offset:53248
	ds_read_b128 v[240:243], v170 offset:54272
	ds_read_b128 v[244:247], v170 offset:55296
	ds_read_b128 v[248:251], v170 offset:56320
	s_nop 15
	s_nop 15
	s_waitcnt vmcnt(8) lgkmcnt(0)
	s_barrier
	s_setprio 1
	v_mfma_f32_16x16x32_bf16 v[124:127], v[148:151], v[192:195], v[124:127]
	v_mfma_f32_16x16x32_bf16 v[120:123], v[156:159], v[192:195], v[120:123]
	v_mfma_f32_16x16x32_bf16 v[116:119], v[148:151], v[200:203], v[116:119]
	v_mfma_f32_16x16x32_bf16 v[112:115], v[156:159], v[200:203], v[112:115]
	v_mfma_f32_16x16x32_bf16 v[100:103], v[148:151], v[208:211], v[100:103]
	v_mfma_f32_16x16x32_bf16 v[96:99], v[156:159], v[208:211], v[96:99]
	v_mfma_f32_16x16x32_bf16 v[84:87], v[148:151], v[216:219], v[84:87]
	v_mfma_f32_16x16x32_bf16 v[80:83], v[156:159], v[216:219], v[80:83]
	v_mfma_f32_16x16x32_bf16 v[124:127], v[152:155], v[196:199], v[124:127]
	v_mfma_f32_16x16x32_bf16 v[120:123], v[172:175], v[196:199], v[120:123]
	v_mfma_f32_16x16x32_bf16 v[116:119], v[152:155], v[204:207], v[116:119]
	v_mfma_f32_16x16x32_bf16 v[112:115], v[172:175], v[204:207], v[112:115]
	v_mfma_f32_16x16x32_bf16 v[100:103], v[152:155], v[212:215], v[100:103]
	v_mfma_f32_16x16x32_bf16 v[96:99], v[172:175], v[212:215], v[96:99]
	v_mfma_f32_16x16x32_bf16 v[84:87], v[152:155], v[220:223], v[84:87]
	v_mfma_f32_16x16x32_bf16 v[80:83], v[172:175], v[220:223], v[80:83]
	s_setprio 0
	s_setprio 1
	v_mfma_f32_16x16x32_bf16 v[108:111], v[176:179], v[192:195], v[108:111]
	v_mfma_f32_16x16x32_bf16 v[104:107], v[184:187], v[192:195], v[104:107]
	v_mfma_f32_16x16x32_bf16 v[92:95], v[176:179], v[200:203], v[92:95]
	v_mfma_f32_16x16x32_bf16 v[88:91], v[184:187], v[200:203], v[88:91]
	v_mfma_f32_16x16x32_bf16 v[76:79], v[176:179], v[208:211], v[76:79]
	v_mfma_f32_16x16x32_bf16 v[72:75], v[184:187], v[208:211], v[72:75]
	v_mfma_f32_16x16x32_bf16 v[68:71], v[176:179], v[216:219], v[68:71]
	v_mfma_f32_16x16x32_bf16 v[64:67], v[184:187], v[216:219], v[64:67]
	v_mfma_f32_16x16x32_bf16 v[108:111], v[180:183], v[196:199], v[108:111]
	v_mfma_f32_16x16x32_bf16 v[104:107], v[188:191], v[196:199], v[104:107]
	v_mfma_f32_16x16x32_bf16 v[92:95], v[180:183], v[204:207], v[92:95]
	v_mfma_f32_16x16x32_bf16 v[88:91], v[188:191], v[204:207], v[88:91]
	v_mfma_f32_16x16x32_bf16 v[76:79], v[180:183], v[212:215], v[76:79]
	v_mfma_f32_16x16x32_bf16 v[72:75], v[188:191], v[212:215], v[72:75]
	v_mfma_f32_16x16x32_bf16 v[68:71], v[180:183], v[220:223], v[68:71]
	v_mfma_f32_16x16x32_bf16 v[64:67], v[188:191], v[220:223], v[64:67]
	s_setprio 0
	s_setprio 1
	v_mfma_f32_16x16x32_bf16 v[60:63], v[148:151], v[142:145], v[60:63]
	v_mfma_f32_16x16x32_bf16 v[56:59], v[156:159], v[142:145], v[56:59]
	v_mfma_f32_16x16x32_bf16 v[52:55], v[148:151], v[228:231], v[52:55]
	v_mfma_f32_16x16x32_bf16 v[48:51], v[156:159], v[228:231], v[48:51]
	v_mfma_f32_16x16x32_bf16 v[36:39], v[148:151], v[236:239], v[36:39]
	v_mfma_f32_16x16x32_bf16 v[32:35], v[156:159], v[236:239], v[32:35]
	v_mfma_f32_16x16x32_bf16 v[20:23], v[148:151], v[244:247], v[20:23]
	v_mfma_f32_16x16x32_bf16 v[16:19], v[156:159], v[244:247], v[16:19]
	v_mfma_f32_16x16x32_bf16 v[60:63], v[152:155], v[224:227], v[60:63]
	v_mfma_f32_16x16x32_bf16 v[56:59], v[172:175], v[224:227], v[56:59]
	v_mfma_f32_16x16x32_bf16 v[52:55], v[152:155], v[232:235], v[52:55]
	v_mfma_f32_16x16x32_bf16 v[48:51], v[172:175], v[232:235], v[48:51]
	v_mfma_f32_16x16x32_bf16 v[36:39], v[152:155], v[240:243], v[36:39]
	v_mfma_f32_16x16x32_bf16 v[32:35], v[172:175], v[240:243], v[32:35]
	v_mfma_f32_16x16x32_bf16 v[20:23], v[152:155], v[248:251], v[20:23]
	v_mfma_f32_16x16x32_bf16 v[16:19], v[172:175], v[248:251], v[16:19]
	s_setprio 0
	s_setprio 1
	v_mfma_f32_16x16x32_bf16 v[44:47], v[176:179], v[142:145], v[44:47]
	v_mfma_f32_16x16x32_bf16 v[40:43], v[184:187], v[142:145], v[40:43]
	v_mfma_f32_16x16x32_bf16 v[28:31], v[176:179], v[228:231], v[28:31]
	v_mfma_f32_16x16x32_bf16 v[24:27], v[184:187], v[228:231], v[24:27]
	v_mfma_f32_16x16x32_bf16 v[12:15], v[176:179], v[236:239], v[12:15]
	v_mfma_f32_16x16x32_bf16 v[8:11], v[184:187], v[236:239], v[8:11]
	v_mfma_f32_16x16x32_bf16 v[4:7], v[176:179], v[244:247], v[4:7]
	v_mfma_f32_16x16x32_bf16 v[0:3], v[184:187], v[244:247], v[0:3]
	v_mfma_f32_16x16x32_bf16 v[44:47], v[180:183], v[224:227], v[44:47]
	v_mfma_f32_16x16x32_bf16 v[40:43], v[188:191], v[224:227], v[40:43]
	v_mfma_f32_16x16x32_bf16 v[28:31], v[180:183], v[232:235], v[28:31]
	v_mfma_f32_16x16x32_bf16 v[24:27], v[188:191], v[232:235], v[24:27]
	v_mfma_f32_16x16x32_bf16 v[12:15], v[180:183], v[240:243], v[12:15]
	v_mfma_f32_16x16x32_bf16 v[8:11], v[188:191], v[240:243], v[8:11]
	v_mfma_f32_16x16x32_bf16 v[4:7], v[180:183], v[248:251], v[4:7]
	v_mfma_f32_16x16x32_bf16 v[0:3], v[188:191], v[248:251], v[0:3]
	s_setprio 0
	s_waitcnt vmcnt(4)
	s_barrier
	s_add_i32 s64, s64, 2
	s_add_u32 s14, s14, 0x100
	s_addc_u32 s15, s15, 0
	s_add_u32 s20, s20, 0x100
	s_addc_u32 s21, s21, 0
	s_cmp_gt_u32 s64, 29
	s_cbranch_scc0 .LBB0_165

.LBB0_613:
	s_add_u32 s24, s22, 0xfffc0080
	s_addc_u32 s25, s23, -1
	s_cmp_eq_u32 s49, 12
	s_cselect_b32 s27, s13, s25
	s_cselect_b32 s26, s41, s24
	s_cselect_b32 s25, s11, s48
	s_cselect_b32 s24, s46, s47
	s_and_b64 vcc, exec, s[6:7]
	s_cbranch_vccz .Lk64_trail_glu
	s_sub_u32 vcc_lo, s47, 0x80
	s_subb_u32 vcc_hi, s48, 0
	s_add_i32 m0, s28, 0x18000
	s_nop 0
	global_load_lds_dwordx4 v132, vcc
	s_add_i32 m0, s28, 0x1a000
	s_nop 0
	global_load_lds_dwordx4 v128, vcc
	s_add_u32 vcc_lo, vcc_lo, 0x10000
	s_addc_u32 vcc_hi, vcc_hi, 0
	s_add_i32 m0, s28, 0x19000
	s_nop 0
	global_load_lds_dwordx4 v132, vcc
	s_add_i32 m0, s28, 0x1b000
	s_nop 0
	global_load_lds_dwordx4 v128, vcc
	s_add_u32 vcc_lo, vcc_lo, 0x30000
	s_addc_u32 vcc_hi, vcc_hi, 0
	s_add_i32 m0, s28, 0x1c000
	s_nop 0
	global_load_lds_dwordx4 v132, vcc
	s_add_i32 m0, s28, 0x1e000
	s_nop 0
	global_load_lds_dwordx4 v128, vcc
	s_add_u32 vcc_lo, vcc_lo, 0x10000
	s_addc_u32 vcc_hi, vcc_hi, 0
	s_add_i32 m0, s28, 0x1d000
	s_nop 0
	global_load_lds_dwordx4 v132, vcc
	s_add_i32 m0, s28, 0x1f000
	s_nop 0
	global_load_lds_dwordx4 v128, vcc
	ds_read_b128 v[144:147], v151 offset:0
	ds_read_b128 v[154:157], v151 offset:1024
	ds_read_b128 v[158:161], v151 offset:2048
	ds_read_b128 v[162:165], v151 offset:3072
	ds_read_b128 v[182:185], v153 offset:0
	ds_read_b128 v[186:189], v153 offset:1024
	ds_read_b128 v[190:193], v153 offset:2048
	ds_read_b128 v[194:197], v153 offset:3072
	ds_read_b128 v[198:201], v153 offset:4096
	ds_read_b128 v[202:205], v153 offset:5120
	ds_read_b128 v[206:209], v153 offset:6144
	ds_read_b128 v[210:213], v153 offset:7168
	ds_read_b128 v[220:223], v153 offset:16384
	ds_read_b128 v[224:227], v153 offset:17408
	ds_read_b128 v[228:231], v153 offset:18432
	ds_read_b128 v[232:235], v153 offset:19456
	ds_read_b128 v[236:239], v153 offset:20480
	ds_read_b128 v[240:243], v153 offset:21504
	ds_read_b128 v[244:247], v153 offset:22528
	ds_read_b128 v[248:251], v153 offset:23552
	s_nop 15
	s_nop 15
	s_waitcnt vmcnt(8) lgkmcnt(0)
	s_barrier
	ds_read_b128 v[166:169], v152 offset:0
	ds_read_b128 v[170:173], v152 offset:1024
	ds_read_b128 v[174:177], v152 offset:2048
	ds_read_b128 v[178:181], v152 offset:3072
	s_setprio 1
	v_mfma_f32_16x16x32_bf16 v[124:127], v[144:147], v[182:185], v[124:127]
	v_mfma_f32_16x16x32_bf16 v[120:123], v[158:161], v[182:185], v[120:123]
	v_mfma_f32_16x16x32_bf16 v[108:111], v[144:147], v[190:193], v[108:111]
	v_mfma_f32_16x16x32_bf16 v[104:107], v[158:161], v[190:193], v[104:107]
	v_mfma_f32_16x16x32_bf16 v[92:95], v[144:147], v[198:201], v[92:95]
	v_mfma_f32_16x16x32_bf16 v[88:91], v[158:161], v[198:201], v[88:91]
	v_mfma_f32_16x16x32_bf16 v[76:79], v[144:147], v[206:209], v[76:79]
	v_mfma_f32_16x16x32_bf16 v[72:75], v[158:161], v[206:209], v[72:75]
	v_mfma_f32_16x16x32_bf16 v[124:127], v[154:157], v[186:189], v[124:127]
	v_mfma_f32_16x16x32_bf16 v[120:123], v[162:165], v[186:189], v[120:123]
	v_mfma_f32_16x16x32_bf16 v[108:111], v[154:157], v[194:197], v[108:111]
	v_mfma_f32_16x16x32_bf16 v[104:107], v[162:165], v[194:197], v[104:107]
	v_mfma_f32_16x16x32_bf16 v[92:95], v[154:157], v[202:205], v[92:95]
	v_mfma_f32_16x16x32_bf16 v[88:91], v[162:165], v[202:205], v[88:91]
	v_mfma_f32_16x16x32_bf16 v[76:79], v[154:157], v[210:213], v[76:79]
	v_mfma_f32_16x16x32_bf16 v[72:75], v[162:165], v[210:213], v[72:75]
	s_setprio 0
	s_waitcnt lgkmcnt(0)
	s_setprio 1
	v_mfma_f32_16x16x32_bf16 v[116:119], v[166:169], v[182:185], v[116:119]
	v_mfma_f32_16x16x32_bf16 v[112:115], v[174:177], v[182:185], v[112:115]
	v_mfma_f32_16x16x32_bf16 v[100:103], v[166:169], v[190:193], v[100:103]
	v_mfma_f32_16x16x32_bf16 v[96:99], v[174:177], v[190:193], v[96:99]
	v_mfma_f32_16x16x32_bf16 v[84:87], v[166:169], v[198:201], v[84:87]
	v_mfma_f32_16x16x32_bf16 v[80:83], v[174:177], v[198:201], v[80:83]
	v_mfma_f32_16x16x32_bf16 v[68:71], v[166:169], v[206:209], v[68:71]
	v_mfma_f32_16x16x32_bf16 v[64:67], v[174:177], v[206:209], v[64:67]
	v_mfma_f32_16x16x32_bf16 v[116:119], v[170:173], v[186:189], v[116:119]
	v_mfma_f32_16x16x32_bf16 v[112:115], v[178:181], v[186:189], v[112:115]
	v_mfma_f32_16x16x32_bf16 v[100:103], v[170:173], v[194:197], v[100:103]
	v_mfma_f32_16x16x32_bf16 v[96:99], v[178:181], v[194:197], v[96:99]
	v_mfma_f32_16x16x32_bf16 v[84:87], v[170:173], v[202:205], v[84:87]
	v_mfma_f32_16x16x32_bf16 v[80:83], v[178:181], v[202:205], v[80:83]
	v_mfma_f32_16x16x32_bf16 v[68:71], v[170:173], v[210:213], v[68:71]
	v_mfma_f32_16x16x32_bf16 v[64:67], v[178:181], v[210:213], v[64:67]
	s_setprio 0
	s_setprio 1
	v_mfma_f32_16x16x32_bf16 v[60:63], v[144:147], v[220:223], v[60:63]
	v_mfma_f32_16x16x32_bf16 v[56:59], v[158:161], v[220:223], v[56:59]
	v_mfma_f32_16x16x32_bf16 v[44:47], v[144:147], v[228:231], v[44:47]
	v_mfma_f32_16x16x32_bf16 v[40:43], v[158:161], v[228:231], v[40:43]
	v_mfma_f32_16x16x32_bf16 v[28:31], v[144:147], v[236:239], v[28:31]
	v_mfma_f32_16x16x32_bf16 v[24:27], v[158:161], v[236:239], v[24:27]
	v_mfma_f32_16x16x32_bf16 v[12:15], v[144:147], v[244:247], v[12:15]
	v_mfma_f32_16x16x32_bf16 v[8:11], v[158:161], v[244:247], v[8:11]
	v_mfma_f32_16x16x32_bf16 v[60:63], v[154:157], v[224:227], v[60:63]
	v_mfma_f32_16x16x32_bf16 v[56:59], v[162:165], v[224:227], v[56:59]
	v_mfma_f32_16x16x32_bf16 v[44:47], v[154:157], v[232:235], v[44:47]
	v_mfma_f32_16x16x32_bf16 v[40:43], v[162:165], v[232:235], v[40:43]
	v_mfma_f32_16x16x32_bf16 v[28:31], v[154:157], v[240:243], v[28:31]
	v_mfma_f32_16x16x32_bf16 v[24:27], v[162:165], v[240:243], v[24:27]
	v_mfma_f32_16x16x32_bf16 v[12:15], v[154:157], v[248:251], v[12:15]
	v_mfma_f32_16x16x32_bf16 v[8:11], v[162:165], v[248:251], v[8:11]
	s_setprio 0
	s_setprio 1
	v_mfma_f32_16x16x32_bf16 v[52:55], v[166:169], v[220:223], v[52:55]
	v_mfma_f32_16x16x32_bf16 v[48:51], v[174:177], v[220:223], v[48:51]
	v_mfma_f32_16x16x32_bf16 v[36:39], v[166:169], v[228:231], v[36:39]
	v_mfma_f32_16x16x32_bf16 v[32:35], v[174:177], v[228:231], v[32:35]
	v_mfma_f32_16x16x32_bf16 v[20:23], v[166:169], v[236:239], v[20:23]
	v_mfma_f32_16x16x32_bf16 v[16:19], v[174:177], v[236:239], v[16:19]
	v_mfma_f32_16x16x32_bf16 v[4:7], v[166:169], v[244:247], v[4:7]
	v_mfma_f32_16x16x32_bf16 v[0:3], v[174:177], v[244:247], v[0:3]
	v_mfma_f32_16x16x32_bf16 v[52:55], v[170:173], v[224:227], v[52:55]
	v_mfma_f32_16x16x32_bf16 v[48:51], v[178:181], v[224:227], v[48:51]
	v_mfma_f32_16x16x32_bf16 v[36:39], v[170:173], v[232:235], v[36:39]
	v_mfma_f32_16x16x32_bf16 v[32:35], v[178:181], v[232:235], v[32:35]
	v_mfma_f32_16x16x32_bf16 v[20:23], v[170:173], v[240:243], v[20:23]
	v_mfma_f32_16x16x32_bf16 v[16:19], v[178:181], v[240:243], v[16:19]
	v_mfma_f32_16x16x32_bf16 v[4:7], v[170:173], v[248:251], v[4:7]
	v_mfma_f32_16x16x32_bf16 v[0:3], v[178:181], v[248:251], v[0:3]
	s_setprio 0
	s_waitcnt vmcnt(4)
	s_barrier
	s_add_u32 vcc_lo, s24, 0x0
	s_addc_u32 vcc_hi, s25, 0
	s_add_i32 m0, s28, 0x10000
	s_nop 0
	global_load_lds_dwordx4 v132, vcc
	s_add_i32 m0, s28, 0x12000
	s_nop 0
	global_load_lds_dwordx4 v128, vcc
	s_add_u32 vcc_lo, vcc_lo, 0x10000
	s_addc_u32 vcc_hi, vcc_hi, 0
	s_add_i32 m0, s28, 0x11000
	s_nop 0
	global_load_lds_dwordx4 v132, vcc
	s_add_i32 m0, s28, 0x13000
	s_nop 0
	global_load_lds_dwordx4 v128, vcc
	s_add_u32 vcc_lo, vcc_lo, 0x30000
	s_addc_u32 vcc_hi, vcc_hi, 0
	s_add_i32 m0, s28, 0x14000
	s_nop 0
	global_load_lds_dwordx4 v132, vcc
	s_add_i32 m0, s28, 0x16000
	s_nop 0
	global_load_lds_dwordx4 v128, vcc
	s_add_u32 vcc_lo, vcc_lo, 0x10000
	s_addc_u32 vcc_hi, vcc_hi, 0
	s_add_i32 m0, s28, 0x15000
	s_nop 0
	global_load_lds_dwordx4 v132, vcc
	s_add_i32 m0, s28, 0x17000
	s_nop 0
	global_load_lds_dwordx4 v128, vcc
	ds_read_b128 v[144:147], v151 offset:32768
	ds_read_b128 v[154:157], v151 offset:33792
	ds_read_b128 v[158:161], v151 offset:34816
	ds_read_b128 v[162:165], v151 offset:35840
	ds_read_b128 v[182:185], v153 offset:32768
	ds_read_b128 v[186:189], v153 offset:33792
	ds_read_b128 v[190:193], v153 offset:34816
	ds_read_b128 v[194:197], v153 offset:35840
	ds_read_b128 v[198:201], v153 offset:36864
	ds_read_b128 v[202:205], v153 offset:37888
	ds_read_b128 v[206:209], v153 offset:38912
	ds_read_b128 v[210:213], v153 offset:39936
	ds_read_b128 v[220:223], v153 offset:49152
	ds_read_b128 v[224:227], v153 offset:50176
	ds_read_b128 v[228:231], v153 offset:51200
	ds_read_b128 v[232:235], v153 offset:52224
	ds_read_b128 v[236:239], v153 offset:53248
	ds_read_b128 v[240:243], v153 offset:54272
	ds_read_b128 v[244:247], v153 offset:55296
	ds_read_b128 v[248:251], v153 offset:56320
	s_nop 15
	s_nop 15
	s_waitcnt vmcnt(8) lgkmcnt(0)
	s_barrier
	ds_read_b128 v[166:169], v152 offset:32768
	ds_read_b128 v[170:173], v152 offset:33792
	ds_read_b128 v[174:177], v152 offset:34816
	ds_read_b128 v[178:181], v152 offset:35840
	s_setprio 1
	v_mfma_f32_16x16x32_bf16 v[124:127], v[144:147], v[182:185], v[124:127]
	v_mfma_f32_16x16x32_bf16 v[120:123], v[158:161], v[182:185], v[120:123]
	v_mfma_f32_16x16x32_bf16 v[108:111], v[144:147], v[190:193], v[108:111]
	v_mfma_f32_16x16x32_bf16 v[104:107], v[158:161], v[190:193], v[104:107]
	v_mfma_f32_16x16x32_bf16 v[92:95], v[144:147], v[198:201], v[92:95]
	v_mfma_f32_16x16x32_bf16 v[88:91], v[158:161], v[198:201], v[88:91]
	v_mfma_f32_16x16x32_bf16 v[76:79], v[144:147], v[206:209], v[76:79]
	v_mfma_f32_16x16x32_bf16 v[72:75], v[158:161], v[206:209], v[72:75]
	v_mfma_f32_16x16x32_bf16 v[124:127], v[154:157], v[186:189], v[124:127]
	v_mfma_f32_16x16x32_bf16 v[120:123], v[162:165], v[186:189], v[120:123]
	v_mfma_f32_16x16x32_bf16 v[108:111], v[154:157], v[194:197], v[108:111]
	v_mfma_f32_16x16x32_bf16 v[104:107], v[162:165], v[194:197], v[104:107]
	v_mfma_f32_16x16x32_bf16 v[92:95], v[154:157], v[202:205], v[92:95]
	v_mfma_f32_16x16x32_bf16 v[88:91], v[162:165], v[202:205], v[88:91]
	v_mfma_f32_16x16x32_bf16 v[76:79], v[154:157], v[210:213], v[76:79]
	v_mfma_f32_16x16x32_bf16 v[72:75], v[162:165], v[210:213], v[72:75]
	s_setprio 0
	s_waitcnt lgkmcnt(0)
	s_setprio 1
	v_mfma_f32_16x16x32_bf16 v[116:119], v[166:169], v[182:185], v[116:119]
	v_mfma_f32_16x16x32_bf16 v[112:115], v[174:177], v[182:185], v[112:115]
	v_mfma_f32_16x16x32_bf16 v[100:103], v[166:169], v[190:193], v[100:103]
	v_mfma_f32_16x16x32_bf16 v[96:99], v[174:177], v[190:193], v[96:99]
	v_mfma_f32_16x16x32_bf16 v[84:87], v[166:169], v[198:201], v[84:87]
	v_mfma_f32_16x16x32_bf16 v[80:83], v[174:177], v[198:201], v[80:83]
	v_mfma_f32_16x16x32_bf16 v[68:71], v[166:169], v[206:209], v[68:71]
	v_mfma_f32_16x16x32_bf16 v[64:67], v[174:177], v[206:209], v[64:67]
	v_mfma_f32_16x16x32_bf16 v[116:119], v[170:173], v[186:189], v[116:119]
	v_mfma_f32_16x16x32_bf16 v[112:115], v[178:181], v[186:189], v[112:115]
	v_mfma_f32_16x16x32_bf16 v[100:103], v[170:173], v[194:197], v[100:103]
	v_mfma_f32_16x16x32_bf16 v[96:99], v[178:181], v[194:197], v[96:99]
	v_mfma_f32_16x16x32_bf16 v[84:87], v[170:173], v[202:205], v[84:87]
	v_mfma_f32_16x16x32_bf16 v[80:83], v[178:181], v[202:205], v[80:83]
	v_mfma_f32_16x16x32_bf16 v[68:71], v[170:173], v[210:213], v[68:71]
	v_mfma_f32_16x16x32_bf16 v[64:67], v[178:181], v[210:213], v[64:67]
	s_setprio 0
	s_setprio 1
	v_mfma_f32_16x16x32_bf16 v[60:63], v[144:147], v[220:223], v[60:63]
	v_mfma_f32_16x16x32_bf16 v[56:59], v[158:161], v[220:223], v[56:59]
	v_mfma_f32_16x16x32_bf16 v[44:47], v[144:147], v[228:231], v[44:47]
	v_mfma_f32_16x16x32_bf16 v[40:43], v[158:161], v[228:231], v[40:43]
	v_mfma_f32_16x16x32_bf16 v[28:31], v[144:147], v[236:239], v[28:31]
	v_mfma_f32_16x16x32_bf16 v[24:27], v[158:161], v[236:239], v[24:27]
	v_mfma_f32_16x16x32_bf16 v[12:15], v[144:147], v[244:247], v[12:15]
	v_mfma_f32_16x16x32_bf16 v[8:11], v[158:161], v[244:247], v[8:11]
	v_mfma_f32_16x16x32_bf16 v[60:63], v[154:157], v[224:227], v[60:63]
	v_mfma_f32_16x16x32_bf16 v[56:59], v[162:165], v[224:227], v[56:59]
	v_mfma_f32_16x16x32_bf16 v[44:47], v[154:157], v[232:235], v[44:47]
	v_mfma_f32_16x16x32_bf16 v[40:43], v[162:165], v[232:235], v[40:43]
	v_mfma_f32_16x16x32_bf16 v[28:31], v[154:157], v[240:243], v[28:31]
	v_mfma_f32_16x16x32_bf16 v[24:27], v[162:165], v[240:243], v[24:27]
	v_mfma_f32_16x16x32_bf16 v[12:15], v[154:157], v[248:251], v[12:15]
	v_mfma_f32_16x16x32_bf16 v[8:11], v[162:165], v[248:251], v[8:11]
	s_setprio 0
	s_setprio 1
	v_mfma_f32_16x16x32_bf16 v[52:55], v[166:169], v[220:223], v[52:55]
	v_mfma_f32_16x16x32_bf16 v[48:51], v[174:177], v[220:223], v[48:51]
	v_mfma_f32_16x16x32_bf16 v[36:39], v[166:169], v[228:231], v[36:39]
	v_mfma_f32_16x16x32_bf16 v[32:35], v[174:177], v[228:231], v[32:35]
	v_mfma_f32_16x16x32_bf16 v[20:23], v[166:169], v[236:239], v[20:23]
	v_mfma_f32_16x16x32_bf16 v[16:19], v[174:177], v[236:239], v[16:19]
	v_mfma_f32_16x16x32_bf16 v[4:7], v[166:169], v[244:247], v[4:7]
	v_mfma_f32_16x16x32_bf16 v[0:3], v[174:177], v[244:247], v[0:3]
	v_mfma_f32_16x16x32_bf16 v[52:55], v[170:173], v[224:227], v[52:55]
	v_mfma_f32_16x16x32_bf16 v[48:51], v[178:181], v[224:227], v[48:51]
	v_mfma_f32_16x16x32_bf16 v[36:39], v[170:173], v[232:235], v[36:39]
	v_mfma_f32_16x16x32_bf16 v[32:35], v[178:181], v[232:235], v[32:35]
	v_mfma_f32_16x16x32_bf16 v[20:23], v[170:173], v[240:243], v[20:23]
	v_mfma_f32_16x16x32_bf16 v[16:19], v[178:181], v[240:243], v[16:19]
	v_mfma_f32_16x16x32_bf16 v[4:7], v[170:173], v[248:251], v[4:7]
	v_mfma_f32_16x16x32_bf16 v[0:3], v[178:181], v[248:251], v[0:3]
	s_setprio 0
	s_waitcnt vmcnt(4)
	s_barrier
	s_add_i32 s49, s49, 2
	s_add_u32 s22, s22, 0x100
	s_addc_u32 s23, s23, 0
	s_add_u32 s47, s47, 0x100
	s_addc_u32 s48, s48, 0
	s_cmp_gt_u32 s49, 13
	s_cbranch_scc0 .LBB0_613
	s_branch .Lk64_done_glu
.Lk64_trail_glu:
	s_sub_u32 vcc_lo, s22, 0x40000
	s_subb_u32 vcc_hi, s23, 0
	s_add_i32 m0, s28, 0xa000
	s_nop 0
	global_load_lds_dwordx4 v130, vcc
	s_add_u32 vcc_lo, vcc_lo, 0x10000
	s_addc_u32 vcc_hi, vcc_hi, 0
	s_add_i32 m0, s28, 0x9000
	s_nop 0
	global_load_lds_dwordx4 v134, vcc
	s_add_u32 vcc_lo, vcc_lo, 0x30000
	s_addc_u32 vcc_hi, vcc_hi, 0
	s_add_i32 m0, s28, 0xe000
	s_nop 0
	global_load_lds_dwordx4 v130, vcc
	s_add_u32 vcc_lo, vcc_lo, 0x10000
	s_addc_u32 vcc_hi, vcc_hi, 0
	s_add_i32 m0, s28, 0xd000
	s_nop 0
	global_load_lds_dwordx4 v134, vcc
	s_add_u32 vcc_lo, s26, 0x0
	s_addc_u32 vcc_hi, s27, 0
	s_mov_b32 m0, s28
	s_nop 0
	global_load_lds_dwordx4 v134, vcc
	s_sub_u32 vcc_lo, vcc_lo, 0x10000
	s_subb_u32 vcc_hi, vcc_hi, 0
	s_sub_i32 m0, s28, 0x1000
	s_nop 0
	global_load_lds_dwordx4 v134, vcc
	s_add_u32 vcc_lo, vcc_lo, 0x50000
	s_addc_u32 vcc_hi, vcc_hi, 0
	s_add_i32 m0, s28, 0x4000
	s_nop 0
	global_load_lds_dwordx4 v134, vcc
	s_sub_u32 vcc_lo, vcc_lo, 0x10000
	s_subb_u32 vcc_hi, vcc_hi, 0
	s_add_i32 m0, s28, 0x3000
	s_nop 0
	global_load_lds_dwordx4 v134, vcc
	ds_read_b128 v[144:147], v151 offset:0
	ds_read_b128 v[154:157], v151 offset:1024
	ds_read_b128 v[158:161], v151 offset:2048
	ds_read_b128 v[162:165], v151 offset:3072
	ds_read_b128 v[166:169], v152 offset:0
	ds_read_b128 v[170:173], v152 offset:1024
	ds_read_b128 v[174:177], v152 offset:2048
	ds_read_b128 v[178:181], v152 offset:3072
	ds_read_b128 v[182:185], v153 offset:0
	ds_read_b128 v[186:189], v153 offset:1024
	ds_read_b128 v[190:193], v153 offset:2048
	ds_read_b128 v[194:197], v153 offset:3072
	ds_read_b128 v[198:201], v153 offset:4096
	ds_read_b128 v[202:205], v153 offset:5120
	ds_read_b128 v[206:209], v153 offset:6144
	ds_read_b128 v[210:213], v153 offset:7168
	ds_read_b128 v[220:223], v153 offset:16384
	ds_read_b128 v[224:227], v153 offset:17408
	ds_read_b128 v[228:231], v153 offset:18432
	ds_read_b128 v[232:235], v153 offset:19456
	ds_read_b128 v[236:239], v153 offset:20480
	ds_read_b128 v[240:243], v153 offset:21504
	ds_read_b128 v[244:247], v153 offset:22528
	ds_read_b128 v[248:251], v153 offset:23552
	s_nop 15
	s_nop 15
	s_waitcnt vmcnt(8) lgkmcnt(0)
	s_barrier
	s_setprio 1
	v_mfma_f32_16x16x32_bf16 v[124:127], v[144:147], v[182:185], v[124:127]
	v_mfma_f32_16x16x32_bf16 v[120:123], v[158:161], v[182:185], v[120:123]
	v_mfma_f32_16x16x32_bf16 v[108:111], v[144:147], v[190:193], v[108:111]
	v_mfma_f32_16x16x32_bf16 v[104:107], v[158:161], v[190:193], v[104:107]
	v_mfma_f32_16x16x32_bf16 v[92:95], v[144:147], v[198:201], v[92:95]
	v_mfma_f32_16x16x32_bf16 v[88:91], v[158:161], v[198:201], v[88:91]
	v_mfma_f32_16x16x32_bf16 v[76:79], v[144:147], v[206:209], v[76:79]
	v_mfma_f32_16x16x32_bf16 v[72:75], v[158:161], v[206:209], v[72:75]
	v_mfma_f32_16x16x32_bf16 v[124:127], v[154:157], v[186:189], v[124:127]
	v_mfma_f32_16x16x32_bf16 v[120:123], v[162:165], v[186:189], v[120:123]
	v_mfma_f32_16x16x32_bf16 v[108:111], v[154:157], v[194:197], v[108:111]
	v_mfma_f32_16x16x32_bf16 v[104:107], v[162:165], v[194:197], v[104:107]
	v_mfma_f32_16x16x32_bf16 v[92:95], v[154:157], v[202:205], v[92:95]
	v_mfma_f32_16x16x32_bf16 v[88:91], v[162:165], v[202:205], v[88:91]
	v_mfma_f32_16x16x32_bf16 v[76:79], v[154:157], v[210:213], v[76:79]
	v_mfma_f32_16x16x32_bf16 v[72:75], v[162:165], v[210:213], v[72:75]
	s_setprio 0
	s_setprio 1
	v_mfma_f32_16x16x32_bf16 v[116:119], v[166:169], v[182:185], v[116:119]
	v_mfma_f32_16x16x32_bf16 v[112:115], v[174:177], v[182:185], v[112:115]
	v_mfma_f32_16x16x32_bf16 v[100:103], v[166:169], v[190:193], v[100:103]
	v_mfma_f32_16x16x32_bf16 v[96:99], v[174:177], v[190:193], v[96:99]
	v_mfma_f32_16x16x32_bf16 v[84:87], v[166:169], v[198:201], v[84:87]
	v_mfma_f32_16x16x32_bf16 v[80:83], v[174:177], v[198:201], v[80:83]
	v_mfma_f32_16x16x32_bf16 v[68:71], v[166:169], v[206:209], v[68:71]
	v_mfma_f32_16x16x32_bf16 v[64:67], v[174:177], v[206:209], v[64:67]
	v_mfma_f32_16x16x32_bf16 v[116:119], v[170:173], v[186:189], v[116:119]
	v_mfma_f32_16x16x32_bf16 v[112:115], v[178:181], v[186:189], v[112:115]
	v_mfma_f32_16x16x32_bf16 v[100:103], v[170:173], v[194:197], v[100:103]
	v_mfma_f32_16x16x32_bf16 v[96:99], v[178:181], v[194:197], v[96:99]
	v_mfma_f32_16x16x32_bf16 v[84:87], v[170:173], v[202:205], v[84:87]
	v_mfma_f32_16x16x32_bf16 v[80:83], v[178:181], v[202:205], v[80:83]
	v_mfma_f32_16x16x32_bf16 v[68:71], v[170:173], v[210:213], v[68:71]
	v_mfma_f32_16x16x32_bf16 v[64:67], v[178:181], v[210:213], v[64:67]
	s_setprio 0
	s_setprio 1
	v_mfma_f32_16x16x32_bf16 v[60:63], v[144:147], v[220:223], v[60:63]
	v_mfma_f32_16x16x32_bf16 v[56:59], v[158:161], v[220:223], v[56:59]
	v_mfma_f32_16x16x32_bf16 v[44:47], v[144:147], v[228:231], v[44:47]
	v_mfma_f32_16x16x32_bf16 v[40:43], v[158:161], v[228:231], v[40:43]
	v_mfma_f32_16x16x32_bf16 v[28:31], v[144:147], v[236:239], v[28:31]
	v_mfma_f32_16x16x32_bf16 v[24:27], v[158:161], v[236:239], v[24:27]
	v_mfma_f32_16x16x32_bf16 v[12:15], v[144:147], v[244:247], v[12:15]
	v_mfma_f32_16x16x32_bf16 v[8:11], v[158:161], v[244:247], v[8:11]
	v_mfma_f32_16x16x32_bf16 v[60:63], v[154:157], v[224:227], v[60:63]
	v_mfma_f32_16x16x32_bf16 v[56:59], v[162:165], v[224:227], v[56:59]
	v_mfma_f32_16x16x32_bf16 v[44:47], v[154:157], v[232:235], v[44:47]
	v_mfma_f32_16x16x32_bf16 v[40:43], v[162:165], v[232:235], v[40:43]
	v_mfma_f32_16x16x32_bf16 v[28:31], v[154:157], v[240:243], v[28:31]
	v_mfma_f32_16x16x32_bf16 v[24:27], v[162:165], v[240:243], v[24:27]
	v_mfma_f32_16x16x32_bf16 v[12:15], v[154:157], v[248:251], v[12:15]
	v_mfma_f32_16x16x32_bf16 v[8:11], v[162:165], v[248:251], v[8:11]
	s_setprio 0
	s_setprio 1
	v_mfma_f32_16x16x32_bf16 v[52:55], v[166:169], v[220:223], v[52:55]
	v_mfma_f32_16x16x32_bf16 v[48:51], v[174:177], v[220:223], v[48:51]
	v_mfma_f32_16x16x32_bf16 v[36:39], v[166:169], v[228:231], v[36:39]
	v_mfma_f32_16x16x32_bf16 v[32:35], v[174:177], v[228:231], v[32:35]
	v_mfma_f32_16x16x32_bf16 v[20:23], v[166:169], v[236:239], v[20:23]
	v_mfma_f32_16x16x32_bf16 v[16:19], v[174:177], v[236:239], v[16:19]
	v_mfma_f32_16x16x32_bf16 v[4:7], v[166:169], v[244:247], v[4:7]
	v_mfma_f32_16x16x32_bf16 v[0:3], v[174:177], v[244:247], v[0:3]
	v_mfma_f32_16x16x32_bf16 v[52:55], v[170:173], v[224:227], v[52:55]
	v_mfma_f32_16x16x32_bf16 v[48:51], v[178:181], v[224:227], v[48:51]
	v_mfma_f32_16x16x32_bf16 v[36:39], v[170:173], v[232:235], v[36:39]
	v_mfma_f32_16x16x32_bf16 v[32:35], v[178:181], v[232:235], v[32:35]
	v_mfma_f32_16x16x32_bf16 v[20:23], v[170:173], v[240:243], v[20:23]
	v_mfma_f32_16x16x32_bf16 v[16:19], v[178:181], v[240:243], v[16:19]
	v_mfma_f32_16x16x32_bf16 v[4:7], v[170:173], v[248:251], v[4:7]
	v_mfma_f32_16x16x32_bf16 v[0:3], v[178:181], v[248:251], v[0:3]
	s_setprio 0
	s_waitcnt vmcnt(4)
	s_barrier
	s_add_u32 vcc_lo, s26, 0x0
	s_addc_u32 vcc_hi, s27, 0
	s_add_i32 m0, s28, 0x2000
	s_nop 0
	global_load_lds_dwordx4 v130, vcc
	s_add_u32 vcc_lo, vcc_lo, 0x10000
	s_addc_u32 vcc_hi, vcc_hi, 0
	s_add_i32 m0, s28, 0x1000
	s_nop 0
	global_load_lds_dwordx4 v134, vcc
	s_add_u32 vcc_lo, vcc_lo, 0x30000
	s_addc_u32 vcc_hi, vcc_hi, 0
	s_add_i32 m0, s28, 0x6000
	s_nop 0
	global_load_lds_dwordx4 v130, vcc
	s_add_u32 vcc_lo, vcc_lo, 0x10000
	s_addc_u32 vcc_hi, vcc_hi, 0
	s_add_i32 m0, s28, 0x5000
	s_nop 0
	global_load_lds_dwordx4 v134, vcc
	s_add_u32 vcc_lo, s26, 0x80
	s_addc_u32 vcc_hi, s27, 0
	s_add_i32 m0, s28, 0x8000
	s_nop 0
	global_load_lds_dwordx4 v134, vcc
	s_sub_u32 vcc_lo, vcc_lo, 0x10000
	s_subb_u32 vcc_hi, vcc_hi, 0
	s_add_i32 m0, s28, 0x7000
	s_nop 0
	global_load_lds_dwordx4 v134, vcc
	s_add_u32 vcc_lo, vcc_lo, 0x50000
	s_addc_u32 vcc_hi, vcc_hi, 0
	s_add_i32 m0, s28, 0xc000
	s_nop 0
	global_load_lds_dwordx4 v134, vcc
	s_sub_u32 vcc_lo, vcc_lo, 0x10000
	s_subb_u32 vcc_hi, vcc_hi, 0
	s_add_i32 m0, s28, 0xb000
	s_nop 0
	global_load_lds_dwordx4 v134, vcc
	ds_read_b128 v[144:147], v151 offset:32768
	ds_read_b128 v[154:157], v151 offset:33792
	ds_read_b128 v[158:161], v151 offset:34816
	ds_read_b128 v[162:165], v151 offset:35840
	ds_read_b128 v[166:169], v152 offset:32768
	ds_read_b128 v[170:173], v152 offset:33792
	ds_read_b128 v[174:177], v152 offset:34816
	ds_read_b128 v[178:181], v152 offset:35840
	ds_read_b128 v[182:185], v153 offset:32768
	ds_read_b128 v[186:189], v153 offset:33792
	ds_read_b128 v[190:193], v153 offset:34816
	ds_read_b128 v[194:197], v153 offset:35840
	ds_read_b128 v[198:201], v153 offset:36864
	ds_read_b128 v[202:205], v153 offset:37888
	ds_read_b128 v[206:209], v153 offset:38912
	ds_read_b128 v[210:213], v153 offset:39936
	ds_read_b128 v[220:223], v153 offset:49152
	ds_read_b128 v[224:227], v153 offset:50176
	ds_read_b128 v[228:231], v153 offset:51200
	ds_read_b128 v[232:235], v153 offset:52224
	ds_read_b128 v[236:239], v153 offset:53248
	ds_read_b128 v[240:243], v153 offset:54272
	ds_read_b128 v[244:247], v153 offset:55296
	ds_read_b128 v[248:251], v153 offset:56320
	s_nop 15
	s_nop 15
	s_waitcnt vmcnt(8) lgkmcnt(0)
	s_barrier
	s_setprio 1
	v_mfma_f32_16x16x32_bf16 v[124:127], v[144:147], v[182:185], v[124:127]
	v_mfma_f32_16x16x32_bf16 v[120:123], v[158:161], v[182:185], v[120:123]
	v_mfma_f32_16x16x32_bf16 v[108:111], v[144:147], v[190:193], v[108:111]
	v_mfma_f32_16x16x32_bf16 v[104:107], v[158:161], v[190:193], v[104:107]
	v_mfma_f32_16x16x32_bf16 v[92:95], v[144:147], v[198:201], v[92:95]
	v_mfma_f32_16x16x32_bf16 v[88:91], v[158:161], v[198:201], v[88:91]
	v_mfma_f32_16x16x32_bf16 v[76:79], v[144:147], v[206:209], v[76:79]
	v_mfma_f32_16x16x32_bf16 v[72:75], v[158:161], v[206:209], v[72:75]
	v_mfma_f32_16x16x32_bf16 v[124:127], v[154:157], v[186:189], v[124:127]
	v_mfma_f32_16x16x32_bf16 v[120:123], v[162:165], v[186:189], v[120:123]
	v_mfma_f32_16x16x32_bf16 v[108:111], v[154:157], v[194:197], v[108:111]
	v_mfma_f32_16x16x32_bf16 v[104:107], v[162:165], v[194:197], v[104:107]
	v_mfma_f32_16x16x32_bf16 v[92:95], v[154:157], v[202:205], v[92:95]
	v_mfma_f32_16x16x32_bf16 v[88:91], v[162:165], v[202:205], v[88:91]
	v_mfma_f32_16x16x32_bf16 v[76:79], v[154:157], v[210:213], v[76:79]
	v_mfma_f32_16x16x32_bf16 v[72:75], v[162:165], v[210:213], v[72:75]
	s_setprio 0
	s_setprio 1
	v_mfma_f32_16x16x32_bf16 v[116:119], v[166:169], v[182:185], v[116:119]
	v_mfma_f32_16x16x32_bf16 v[112:115], v[174:177], v[182:185], v[112:115]
	v_mfma_f32_16x16x32_bf16 v[100:103], v[166:169], v[190:193], v[100:103]
	v_mfma_f32_16x16x32_bf16 v[96:99], v[174:177], v[190:193], v[96:99]
	v_mfma_f32_16x16x32_bf16 v[84:87], v[166:169], v[198:201], v[84:87]
	v_mfma_f32_16x16x32_bf16 v[80:83], v[174:177], v[198:201], v[80:83]
	v_mfma_f32_16x16x32_bf16 v[68:71], v[166:169], v[206:209], v[68:71]
	v_mfma_f32_16x16x32_bf16 v[64:67], v[174:177], v[206:209], v[64:67]
	v_mfma_f32_16x16x32_bf16 v[116:119], v[170:173], v[186:189], v[116:119]
	v_mfma_f32_16x16x32_bf16 v[112:115], v[178:181], v[186:189], v[112:115]
	v_mfma_f32_16x16x32_bf16 v[100:103], v[170:173], v[194:197], v[100:103]
	v_mfma_f32_16x16x32_bf16 v[96:99], v[178:181], v[194:197], v[96:99]
	v_mfma_f32_16x16x32_bf16 v[84:87], v[170:173], v[202:205], v[84:87]
	v_mfma_f32_16x16x32_bf16 v[80:83], v[178:181], v[202:205], v[80:83]
	v_mfma_f32_16x16x32_bf16 v[68:71], v[170:173], v[210:213], v[68:71]
	v_mfma_f32_16x16x32_bf16 v[64:67], v[178:181], v[210:213], v[64:67]
	s_setprio 0
	s_setprio 1
	v_mfma_f32_16x16x32_bf16 v[60:63], v[144:147], v[220:223], v[60:63]
	v_mfma_f32_16x16x32_bf16 v[56:59], v[158:161], v[220:223], v[56:59]
	v_mfma_f32_16x16x32_bf16 v[44:47], v[144:147], v[228:231], v[44:47]
	v_mfma_f32_16x16x32_bf16 v[40:43], v[158:161], v[228:231], v[40:43]
	v_mfma_f32_16x16x32_bf16 v[28:31], v[144:147], v[236:239], v[28:31]
	v_mfma_f32_16x16x32_bf16 v[24:27], v[158:161], v[236:239], v[24:27]
	v_mfma_f32_16x16x32_bf16 v[12:15], v[144:147], v[244:247], v[12:15]
	v_mfma_f32_16x16x32_bf16 v[8:11], v[158:161], v[244:247], v[8:11]
	v_mfma_f32_16x16x32_bf16 v[60:63], v[154:157], v[224:227], v[60:63]
	v_mfma_f32_16x16x32_bf16 v[56:59], v[162:165], v[224:227], v[56:59]
	v_mfma_f32_16x16x32_bf16 v[44:47], v[154:157], v[232:235], v[44:47]
	v_mfma_f32_16x16x32_bf16 v[40:43], v[162:165], v[232:235], v[40:43]
	v_mfma_f32_16x16x32_bf16 v[28:31], v[154:157], v[240:243], v[28:31]
	v_mfma_f32_16x16x32_bf16 v[24:27], v[162:165], v[240:243], v[24:27]
	v_mfma_f32_16x16x32_bf16 v[12:15], v[154:157], v[248:251], v[12:15]
	v_mfma_f32_16x16x32_bf16 v[8:11], v[162:165], v[248:251], v[8:11]
	s_setprio 0
	s_setprio 1
	v_mfma_f32_16x16x32_bf16 v[52:55], v[166:169], v[220:223], v[52:55]
	v_mfma_f32_16x16x32_bf16 v[48:51], v[174:177], v[220:223], v[48:51]
	v_mfma_f32_16x16x32_bf16 v[36:39], v[166:169], v[228:231], v[36:39]
	v_mfma_f32_16x16x32_bf16 v[32:35], v[174:177], v[228:231], v[32:35]
	v_mfma_f32_16x16x32_bf16 v[20:23], v[166:169], v[236:239], v[20:23]
	v_mfma_f32_16x16x32_bf16 v[16:19], v[174:177], v[236:239], v[16:19]
	v_mfma_f32_16x16x32_bf16 v[4:7], v[166:169], v[244:247], v[4:7]
	v_mfma_f32_16x16x32_bf16 v[0:3], v[174:177], v[244:247], v[0:3]
	v_mfma_f32_16x16x32_bf16 v[52:55], v[170:173], v[224:227], v[52:55]
	v_mfma_f32_16x16x32_bf16 v[48:51], v[178:181], v[224:227], v[48:51]
	v_mfma_f32_16x16x32_bf16 v[36:39], v[170:173], v[232:235], v[36:39]
	v_mfma_f32_16x16x32_bf16 v[32:35], v[178:181], v[232:235], v[32:35]
	v_mfma_f32_16x16x32_bf16 v[20:23], v[170:173], v[240:243], v[20:23]
	v_mfma_f32_16x16x32_bf16 v[16:19], v[178:181], v[240:243], v[16:19]
	v_mfma_f32_16x16x32_bf16 v[4:7], v[170:173], v[248:251], v[4:7]
	v_mfma_f32_16x16x32_bf16 v[0:3], v[178:181], v[248:251], v[0:3]
	s_setprio 0
	s_waitcnt vmcnt(4)
	s_barrier
	s_add_i32 s49, s49, 2
	s_add_u32 s22, s22, 0x100
	s_addc_u32 s23, s23, 0
	s_add_u32 s47, s47, 0x100
	s_addc_u32 s48, s48, 0
	s_cmp_gt_u32 s49, 13
	s_cbranch_scc0 .LBB0_613

.LBB0_686:
	s_add_u32 s30, s12, 0xfffc0080
	s_addc_u32 s31, s13, -1
	s_cmp_eq_u32 s56, 12
	s_cselect_b32 s35, s25, s31
	s_cselect_b32 s34, s49, s30
	s_cselect_b32 s31, s23, s55
	s_cselect_b32 s30, s51, s54
	s_and_b64 vcc, exec, s[4:5]
	s_cbranch_vccz .Lk64_trail_p4
	s_sub_u32 vcc_lo, s54, 0x80
	s_subb_u32 vcc_hi, s55, 0
	s_add_i32 m0, s36, 0x18000
	s_nop 0
	global_load_lds_dwordx4 v132, vcc
	s_add_i32 m0, s36, 0x1a000
	s_nop 0
	global_load_lds_dwordx4 v128, vcc
	s_add_u32 vcc_lo, vcc_lo, 0x10000
	s_addc_u32 vcc_hi, vcc_hi, 0
	s_add_i32 m0, s36, 0x19000
	s_nop 0
	global_load_lds_dwordx4 v132, vcc
	s_add_i32 m0, s36, 0x1b000
	s_nop 0
	global_load_lds_dwordx4 v128, vcc
	s_add_u32 vcc_lo, vcc_lo, 0x30000
	s_addc_u32 vcc_hi, vcc_hi, 0
	s_add_i32 m0, s36, 0x1c000
	s_nop 0
	global_load_lds_dwordx4 v132, vcc
	s_add_i32 m0, s36, 0x1e000
	s_nop 0
	global_load_lds_dwordx4 v128, vcc
	s_add_u32 vcc_lo, vcc_lo, 0x10000
	s_addc_u32 vcc_hi, vcc_hi, 0
	s_add_i32 m0, s36, 0x1d000
	s_nop 0
	global_load_lds_dwordx4 v132, vcc
	s_add_i32 m0, s36, 0x1f000
	s_nop 0
	global_load_lds_dwordx4 v128, vcc
	ds_read_b128 v[144:147], v151 offset:0
	ds_read_b128 v[154:157], v151 offset:1024
	ds_read_b128 v[158:161], v151 offset:2048
	ds_read_b128 v[162:165], v151 offset:3072
	ds_read_b128 v[182:185], v153 offset:0
	ds_read_b128 v[186:189], v153 offset:1024
	ds_read_b128 v[190:193], v153 offset:2048
	ds_read_b128 v[194:197], v153 offset:3072
	ds_read_b128 v[198:201], v153 offset:4096
	ds_read_b128 v[202:205], v153 offset:5120
	ds_read_b128 v[206:209], v153 offset:6144
	ds_read_b128 v[210:213], v153 offset:7168
	ds_read_b128 v[220:223], v153 offset:16384
	ds_read_b128 v[224:227], v153 offset:17408
	ds_read_b128 v[228:231], v153 offset:18432
	ds_read_b128 v[232:235], v153 offset:19456
	ds_read_b128 v[236:239], v153 offset:20480
	ds_read_b128 v[240:243], v153 offset:21504
	ds_read_b128 v[244:247], v153 offset:22528
	ds_read_b128 v[248:251], v153 offset:23552
	s_nop 15
	s_nop 15
	s_waitcnt vmcnt(8) lgkmcnt(0)
	s_barrier
	ds_read_b128 v[166:169], v152 offset:0
	ds_read_b128 v[170:173], v152 offset:1024
	ds_read_b128 v[174:177], v152 offset:2048
	ds_read_b128 v[178:181], v152 offset:3072
	s_setprio 1
	v_mfma_f32_16x16x32_bf16 v[124:127], v[144:147], v[182:185], v[124:127]
	v_mfma_f32_16x16x32_bf16 v[120:123], v[158:161], v[182:185], v[120:123]
	v_mfma_f32_16x16x32_bf16 v[108:111], v[144:147], v[190:193], v[108:111]
	v_mfma_f32_16x16x32_bf16 v[104:107], v[158:161], v[190:193], v[104:107]
	v_mfma_f32_16x16x32_bf16 v[92:95], v[144:147], v[198:201], v[92:95]
	v_mfma_f32_16x16x32_bf16 v[88:91], v[158:161], v[198:201], v[88:91]
	v_mfma_f32_16x16x32_bf16 v[76:79], v[144:147], v[206:209], v[76:79]
	v_mfma_f32_16x16x32_bf16 v[72:75], v[158:161], v[206:209], v[72:75]
	v_mfma_f32_16x16x32_bf16 v[124:127], v[154:157], v[186:189], v[124:127]
	v_mfma_f32_16x16x32_bf16 v[120:123], v[162:165], v[186:189], v[120:123]
	v_mfma_f32_16x16x32_bf16 v[108:111], v[154:157], v[194:197], v[108:111]
	v_mfma_f32_16x16x32_bf16 v[104:107], v[162:165], v[194:197], v[104:107]
	v_mfma_f32_16x16x32_bf16 v[92:95], v[154:157], v[202:205], v[92:95]
	v_mfma_f32_16x16x32_bf16 v[88:91], v[162:165], v[202:205], v[88:91]
	v_mfma_f32_16x16x32_bf16 v[76:79], v[154:157], v[210:213], v[76:79]
	v_mfma_f32_16x16x32_bf16 v[72:75], v[162:165], v[210:213], v[72:75]
	s_setprio 0
	s_waitcnt lgkmcnt(0)
	s_setprio 1
	v_mfma_f32_16x16x32_bf16 v[116:119], v[166:169], v[182:185], v[116:119]
	v_mfma_f32_16x16x32_bf16 v[112:115], v[174:177], v[182:185], v[112:115]
	v_mfma_f32_16x16x32_bf16 v[100:103], v[166:169], v[190:193], v[100:103]
	v_mfma_f32_16x16x32_bf16 v[96:99], v[174:177], v[190:193], v[96:99]
	v_mfma_f32_16x16x32_bf16 v[84:87], v[166:169], v[198:201], v[84:87]
	v_mfma_f32_16x16x32_bf16 v[80:83], v[174:177], v[198:201], v[80:83]
	v_mfma_f32_16x16x32_bf16 v[68:71], v[166:169], v[206:209], v[68:71]
	v_mfma_f32_16x16x32_bf16 v[64:67], v[174:177], v[206:209], v[64:67]
	v_mfma_f32_16x16x32_bf16 v[116:119], v[170:173], v[186:189], v[116:119]
	v_mfma_f32_16x16x32_bf16 v[112:115], v[178:181], v[186:189], v[112:115]
	v_mfma_f32_16x16x32_bf16 v[100:103], v[170:173], v[194:197], v[100:103]
	v_mfma_f32_16x16x32_bf16 v[96:99], v[178:181], v[194:197], v[96:99]
	v_mfma_f32_16x16x32_bf16 v[84:87], v[170:173], v[202:205], v[84:87]
	v_mfma_f32_16x16x32_bf16 v[80:83], v[178:181], v[202:205], v[80:83]
	v_mfma_f32_16x16x32_bf16 v[68:71], v[170:173], v[210:213], v[68:71]
	v_mfma_f32_16x16x32_bf16 v[64:67], v[178:181], v[210:213], v[64:67]
	s_setprio 0
	s_setprio 1
	v_mfma_f32_16x16x32_bf16 v[60:63], v[144:147], v[220:223], v[60:63]
	v_mfma_f32_16x16x32_bf16 v[56:59], v[158:161], v[220:223], v[56:59]
	v_mfma_f32_16x16x32_bf16 v[44:47], v[144:147], v[228:231], v[44:47]
	v_mfma_f32_16x16x32_bf16 v[40:43], v[158:161], v[228:231], v[40:43]
	v_mfma_f32_16x16x32_bf16 v[28:31], v[144:147], v[236:239], v[28:31]
	v_mfma_f32_16x16x32_bf16 v[24:27], v[158:161], v[236:239], v[24:27]
	v_mfma_f32_16x16x32_bf16 v[12:15], v[144:147], v[244:247], v[12:15]
	v_mfma_f32_16x16x32_bf16 v[8:11], v[158:161], v[244:247], v[8:11]
	v_mfma_f32_16x16x32_bf16 v[60:63], v[154:157], v[224:227], v[60:63]
	v_mfma_f32_16x16x32_bf16 v[56:59], v[162:165], v[224:227], v[56:59]
	v_mfma_f32_16x16x32_bf16 v[44:47], v[154:157], v[232:235], v[44:47]
	v_mfma_f32_16x16x32_bf16 v[40:43], v[162:165], v[232:235], v[40:43]
	v_mfma_f32_16x16x32_bf16 v[28:31], v[154:157], v[240:243], v[28:31]
	v_mfma_f32_16x16x32_bf16 v[24:27], v[162:165], v[240:243], v[24:27]
	v_mfma_f32_16x16x32_bf16 v[12:15], v[154:157], v[248:251], v[12:15]
	v_mfma_f32_16x16x32_bf16 v[8:11], v[162:165], v[248:251], v[8:11]
	s_setprio 0
	s_setprio 1
	v_mfma_f32_16x16x32_bf16 v[52:55], v[166:169], v[220:223], v[52:55]
	v_mfma_f32_16x16x32_bf16 v[48:51], v[174:177], v[220:223], v[48:51]
	v_mfma_f32_16x16x32_bf16 v[36:39], v[166:169], v[228:231], v[36:39]
	v_mfma_f32_16x16x32_bf16 v[32:35], v[174:177], v[228:231], v[32:35]
	v_mfma_f32_16x16x32_bf16 v[20:23], v[166:169], v[236:239], v[20:23]
	v_mfma_f32_16x16x32_bf16 v[16:19], v[174:177], v[236:239], v[16:19]
	v_mfma_f32_16x16x32_bf16 v[4:7], v[166:169], v[244:247], v[4:7]
	v_mfma_f32_16x16x32_bf16 v[0:3], v[174:177], v[244:247], v[0:3]
	v_mfma_f32_16x16x32_bf16 v[52:55], v[170:173], v[224:227], v[52:55]
	v_mfma_f32_16x16x32_bf16 v[48:51], v[178:181], v[224:227], v[48:51]
	v_mfma_f32_16x16x32_bf16 v[36:39], v[170:173], v[232:235], v[36:39]
	v_mfma_f32_16x16x32_bf16 v[32:35], v[178:181], v[232:235], v[32:35]
	v_mfma_f32_16x16x32_bf16 v[20:23], v[170:173], v[240:243], v[20:23]
	v_mfma_f32_16x16x32_bf16 v[16:19], v[178:181], v[240:243], v[16:19]
	v_mfma_f32_16x16x32_bf16 v[4:7], v[170:173], v[248:251], v[4:7]
	v_mfma_f32_16x16x32_bf16 v[0:3], v[178:181], v[248:251], v[0:3]
	s_setprio 0
	s_waitcnt vmcnt(4)
	s_barrier
	s_add_u32 vcc_lo, s30, 0x0
	s_addc_u32 vcc_hi, s31, 0
	s_add_i32 m0, s36, 0x10000
	s_nop 0
	global_load_lds_dwordx4 v132, vcc
	s_add_i32 m0, s36, 0x12000
	s_nop 0
	global_load_lds_dwordx4 v128, vcc
	s_add_u32 vcc_lo, vcc_lo, 0x10000
	s_addc_u32 vcc_hi, vcc_hi, 0
	s_add_i32 m0, s36, 0x11000
	s_nop 0
	global_load_lds_dwordx4 v132, vcc
	s_add_i32 m0, s36, 0x13000
	s_nop 0
	global_load_lds_dwordx4 v128, vcc
	s_add_u32 vcc_lo, vcc_lo, 0x30000
	s_addc_u32 vcc_hi, vcc_hi, 0
	s_add_i32 m0, s36, 0x14000
	s_nop 0
	global_load_lds_dwordx4 v132, vcc
	s_add_i32 m0, s36, 0x16000
	s_nop 0
	global_load_lds_dwordx4 v128, vcc
	s_add_u32 vcc_lo, vcc_lo, 0x10000
	s_addc_u32 vcc_hi, vcc_hi, 0
	s_add_i32 m0, s36, 0x15000
	s_nop 0
	global_load_lds_dwordx4 v132, vcc
	s_add_i32 m0, s36, 0x17000
	s_nop 0
	global_load_lds_dwordx4 v128, vcc
	ds_read_b128 v[144:147], v151 offset:32768
	ds_read_b128 v[154:157], v151 offset:33792
	ds_read_b128 v[158:161], v151 offset:34816
	ds_read_b128 v[162:165], v151 offset:35840
	ds_read_b128 v[182:185], v153 offset:32768
	ds_read_b128 v[186:189], v153 offset:33792
	ds_read_b128 v[190:193], v153 offset:34816
	ds_read_b128 v[194:197], v153 offset:35840
	ds_read_b128 v[198:201], v153 offset:36864
	ds_read_b128 v[202:205], v153 offset:37888
	ds_read_b128 v[206:209], v153 offset:38912
	ds_read_b128 v[210:213], v153 offset:39936
	ds_read_b128 v[220:223], v153 offset:49152
	ds_read_b128 v[224:227], v153 offset:50176
	ds_read_b128 v[228:231], v153 offset:51200
	ds_read_b128 v[232:235], v153 offset:52224
	ds_read_b128 v[236:239], v153 offset:53248
	ds_read_b128 v[240:243], v153 offset:54272
	ds_read_b128 v[244:247], v153 offset:55296
	ds_read_b128 v[248:251], v153 offset:56320
	s_nop 15
	s_nop 15
	s_waitcnt vmcnt(8) lgkmcnt(0)
	s_barrier
	ds_read_b128 v[166:169], v152 offset:32768
	ds_read_b128 v[170:173], v152 offset:33792
	ds_read_b128 v[174:177], v152 offset:34816
	ds_read_b128 v[178:181], v152 offset:35840
	s_setprio 1
	v_mfma_f32_16x16x32_bf16 v[124:127], v[144:147], v[182:185], v[124:127]
	v_mfma_f32_16x16x32_bf16 v[120:123], v[158:161], v[182:185], v[120:123]
	v_mfma_f32_16x16x32_bf16 v[108:111], v[144:147], v[190:193], v[108:111]
	v_mfma_f32_16x16x32_bf16 v[104:107], v[158:161], v[190:193], v[104:107]
	v_mfma_f32_16x16x32_bf16 v[92:95], v[144:147], v[198:201], v[92:95]
	v_mfma_f32_16x16x32_bf16 v[88:91], v[158:161], v[198:201], v[88:91]
	v_mfma_f32_16x16x32_bf16 v[76:79], v[144:147], v[206:209], v[76:79]
	v_mfma_f32_16x16x32_bf16 v[72:75], v[158:161], v[206:209], v[72:75]
	v_mfma_f32_16x16x32_bf16 v[124:127], v[154:157], v[186:189], v[124:127]
	v_mfma_f32_16x16x32_bf16 v[120:123], v[162:165], v[186:189], v[120:123]
	v_mfma_f32_16x16x32_bf16 v[108:111], v[154:157], v[194:197], v[108:111]
	v_mfma_f32_16x16x32_bf16 v[104:107], v[162:165], v[194:197], v[104:107]
	v_mfma_f32_16x16x32_bf16 v[92:95], v[154:157], v[202:205], v[92:95]
	v_mfma_f32_16x16x32_bf16 v[88:91], v[162:165], v[202:205], v[88:91]
	v_mfma_f32_16x16x32_bf16 v[76:79], v[154:157], v[210:213], v[76:79]
	v_mfma_f32_16x16x32_bf16 v[72:75], v[162:165], v[210:213], v[72:75]
	s_setprio 0
	s_waitcnt lgkmcnt(0)
	s_setprio 1
	v_mfma_f32_16x16x32_bf16 v[116:119], v[166:169], v[182:185], v[116:119]
	v_mfma_f32_16x16x32_bf16 v[112:115], v[174:177], v[182:185], v[112:115]
	v_mfma_f32_16x16x32_bf16 v[100:103], v[166:169], v[190:193], v[100:103]
	v_mfma_f32_16x16x32_bf16 v[96:99], v[174:177], v[190:193], v[96:99]
	v_mfma_f32_16x16x32_bf16 v[84:87], v[166:169], v[198:201], v[84:87]
	v_mfma_f32_16x16x32_bf16 v[80:83], v[174:177], v[198:201], v[80:83]
	v_mfma_f32_16x16x32_bf16 v[68:71], v[166:169], v[206:209], v[68:71]
	v_mfma_f32_16x16x32_bf16 v[64:67], v[174:177], v[206:209], v[64:67]
	v_mfma_f32_16x16x32_bf16 v[116:119], v[170:173], v[186:189], v[116:119]
	v_mfma_f32_16x16x32_bf16 v[112:115], v[178:181], v[186:189], v[112:115]
	v_mfma_f32_16x16x32_bf16 v[100:103], v[170:173], v[194:197], v[100:103]
	v_mfma_f32_16x16x32_bf16 v[96:99], v[178:181], v[194:197], v[96:99]
	v_mfma_f32_16x16x32_bf16 v[84:87], v[170:173], v[202:205], v[84:87]
	v_mfma_f32_16x16x32_bf16 v[80:83], v[178:181], v[202:205], v[80:83]
	v_mfma_f32_16x16x32_bf16 v[68:71], v[170:173], v[210:213], v[68:71]
	v_mfma_f32_16x16x32_bf16 v[64:67], v[178:181], v[210:213], v[64:67]
	s_setprio 0
	s_setprio 1
	v_mfma_f32_16x16x32_bf16 v[60:63], v[144:147], v[220:223], v[60:63]
	v_mfma_f32_16x16x32_bf16 v[56:59], v[158:161], v[220:223], v[56:59]
	v_mfma_f32_16x16x32_bf16 v[44:47], v[144:147], v[228:231], v[44:47]
	v_mfma_f32_16x16x32_bf16 v[40:43], v[158:161], v[228:231], v[40:43]
	v_mfma_f32_16x16x32_bf16 v[28:31], v[144:147], v[236:239], v[28:31]
	v_mfma_f32_16x16x32_bf16 v[24:27], v[158:161], v[236:239], v[24:27]
	v_mfma_f32_16x16x32_bf16 v[12:15], v[144:147], v[244:247], v[12:15]
	v_mfma_f32_16x16x32_bf16 v[8:11], v[158:161], v[244:247], v[8:11]
	v_mfma_f32_16x16x32_bf16 v[60:63], v[154:157], v[224:227], v[60:63]
	v_mfma_f32_16x16x32_bf16 v[56:59], v[162:165], v[224:227], v[56:59]
	v_mfma_f32_16x16x32_bf16 v[44:47], v[154:157], v[232:235], v[44:47]
	v_mfma_f32_16x16x32_bf16 v[40:43], v[162:165], v[232:235], v[40:43]
	v_mfma_f32_16x16x32_bf16 v[28:31], v[154:157], v[240:243], v[28:31]
	v_mfma_f32_16x16x32_bf16 v[24:27], v[162:165], v[240:243], v[24:27]
	v_mfma_f32_16x16x32_bf16 v[12:15], v[154:157], v[248:251], v[12:15]
	v_mfma_f32_16x16x32_bf16 v[8:11], v[162:165], v[248:251], v[8:11]
	s_setprio 0
	s_setprio 1
	v_mfma_f32_16x16x32_bf16 v[52:55], v[166:169], v[220:223], v[52:55]
	v_mfma_f32_16x16x32_bf16 v[48:51], v[174:177], v[220:223], v[48:51]
	v_mfma_f32_16x16x32_bf16 v[36:39], v[166:169], v[228:231], v[36:39]
	v_mfma_f32_16x16x32_bf16 v[32:35], v[174:177], v[228:231], v[32:35]
	v_mfma_f32_16x16x32_bf16 v[20:23], v[166:169], v[236:239], v[20:23]
	v_mfma_f32_16x16x32_bf16 v[16:19], v[174:177], v[236:239], v[16:19]
	v_mfma_f32_16x16x32_bf16 v[4:7], v[166:169], v[244:247], v[4:7]
	v_mfma_f32_16x16x32_bf16 v[0:3], v[174:177], v[244:247], v[0:3]
	v_mfma_f32_16x16x32_bf16 v[52:55], v[170:173], v[224:227], v[52:55]
	v_mfma_f32_16x16x32_bf16 v[48:51], v[178:181], v[224:227], v[48:51]
	v_mfma_f32_16x16x32_bf16 v[36:39], v[170:173], v[232:235], v[36:39]
	v_mfma_f32_16x16x32_bf16 v[32:35], v[178:181], v[232:235], v[32:35]
	v_mfma_f32_16x16x32_bf16 v[20:23], v[170:173], v[240:243], v[20:23]
	v_mfma_f32_16x16x32_bf16 v[16:19], v[178:181], v[240:243], v[16:19]
	v_mfma_f32_16x16x32_bf16 v[4:7], v[170:173], v[248:251], v[4:7]
	v_mfma_f32_16x16x32_bf16 v[0:3], v[178:181], v[248:251], v[0:3]
	s_setprio 0
	s_waitcnt vmcnt(4)
	s_barrier
	s_add_i32 s56, s56, 2
	s_add_u32 s12, s12, 0x100
	s_addc_u32 s13, s13, 0
	s_add_u32 s54, s54, 0x100
	s_addc_u32 s55, s55, 0
	s_cmp_gt_u32 s56, 13
	s_cbranch_scc0 .LBB0_686
	s_branch .Lk64_done_p4
.Lk64_trail_p4:
	s_sub_u32 vcc_lo, s12, 0x40000
	s_subb_u32 vcc_hi, s13, 0
	s_add_i32 m0, s36, 0xa000
	s_nop 0
	global_load_lds_dwordx4 v130, vcc
	s_add_u32 vcc_lo, vcc_lo, 0x10000
	s_addc_u32 vcc_hi, vcc_hi, 0
	s_add_i32 m0, s36, 0x9000
	s_nop 0
	global_load_lds_dwordx4 v134, vcc
	s_add_u32 vcc_lo, vcc_lo, 0x30000
	s_addc_u32 vcc_hi, vcc_hi, 0
	s_add_i32 m0, s36, 0xe000
	s_nop 0
	global_load_lds_dwordx4 v130, vcc
	s_add_u32 vcc_lo, vcc_lo, 0x10000
	s_addc_u32 vcc_hi, vcc_hi, 0
	s_add_i32 m0, s36, 0xd000
	s_nop 0
	global_load_lds_dwordx4 v134, vcc
	s_add_u32 vcc_lo, s34, 0x0
	s_addc_u32 vcc_hi, s35, 0
	s_mov_b32 m0, s36
	s_nop 0
	global_load_lds_dwordx4 v134, vcc
	s_sub_u32 vcc_lo, vcc_lo, 0x10000
	s_subb_u32 vcc_hi, vcc_hi, 0
	s_sub_i32 m0, s36, 0x1000
	s_nop 0
	global_load_lds_dwordx4 v134, vcc
	s_add_u32 vcc_lo, vcc_lo, 0x50000
	s_addc_u32 vcc_hi, vcc_hi, 0
	s_add_i32 m0, s36, 0x4000
	s_nop 0
	global_load_lds_dwordx4 v134, vcc
	s_sub_u32 vcc_lo, vcc_lo, 0x10000
	s_subb_u32 vcc_hi, vcc_hi, 0
	s_add_i32 m0, s36, 0x3000
	s_nop 0
	global_load_lds_dwordx4 v134, vcc
	ds_read_b128 v[144:147], v151 offset:0
	ds_read_b128 v[154:157], v151 offset:1024
	ds_read_b128 v[158:161], v151 offset:2048
	ds_read_b128 v[162:165], v151 offset:3072
	ds_read_b128 v[166:169], v152 offset:0
	ds_read_b128 v[170:173], v152 offset:1024
	ds_read_b128 v[174:177], v152 offset:2048
	ds_read_b128 v[178:181], v152 offset:3072
	ds_read_b128 v[182:185], v153 offset:0
	ds_read_b128 v[186:189], v153 offset:1024
	ds_read_b128 v[190:193], v153 offset:2048
	ds_read_b128 v[194:197], v153 offset:3072
	ds_read_b128 v[198:201], v153 offset:4096
	ds_read_b128 v[202:205], v153 offset:5120
	ds_read_b128 v[206:209], v153 offset:6144
	ds_read_b128 v[210:213], v153 offset:7168
	ds_read_b128 v[220:223], v153 offset:16384
	ds_read_b128 v[224:227], v153 offset:17408
	ds_read_b128 v[228:231], v153 offset:18432
	ds_read_b128 v[232:235], v153 offset:19456
	ds_read_b128 v[236:239], v153 offset:20480
	ds_read_b128 v[240:243], v153 offset:21504
	ds_read_b128 v[244:247], v153 offset:22528
	ds_read_b128 v[248:251], v153 offset:23552
	s_nop 15
	s_nop 15
	s_waitcnt vmcnt(8) lgkmcnt(0)
	s_barrier
	s_setprio 1
	v_mfma_f32_16x16x32_bf16 v[124:127], v[144:147], v[182:185], v[124:127]
	v_mfma_f32_16x16x32_bf16 v[120:123], v[158:161], v[182:185], v[120:123]
	v_mfma_f32_16x16x32_bf16 v[108:111], v[144:147], v[190:193], v[108:111]
	v_mfma_f32_16x16x32_bf16 v[104:107], v[158:161], v[190:193], v[104:107]
	v_mfma_f32_16x16x32_bf16 v[92:95], v[144:147], v[198:201], v[92:95]
	v_mfma_f32_16x16x32_bf16 v[88:91], v[158:161], v[198:201], v[88:91]
	v_mfma_f32_16x16x32_bf16 v[76:79], v[144:147], v[206:209], v[76:79]
	v_mfma_f32_16x16x32_bf16 v[72:75], v[158:161], v[206:209], v[72:75]
	v_mfma_f32_16x16x32_bf16 v[124:127], v[154:157], v[186:189], v[124:127]
	v_mfma_f32_16x16x32_bf16 v[120:123], v[162:165], v[186:189], v[120:123]
	v_mfma_f32_16x16x32_bf16 v[108:111], v[154:157], v[194:197], v[108:111]
	v_mfma_f32_16x16x32_bf16 v[104:107], v[162:165], v[194:197], v[104:107]
	v_mfma_f32_16x16x32_bf16 v[92:95], v[154:157], v[202:205], v[92:95]
	v_mfma_f32_16x16x32_bf16 v[88:91], v[162:165], v[202:205], v[88:91]
	v_mfma_f32_16x16x32_bf16 v[76:79], v[154:157], v[210:213], v[76:79]
	v_mfma_f32_16x16x32_bf16 v[72:75], v[162:165], v[210:213], v[72:75]
	s_setprio 0
	s_setprio 1
	v_mfma_f32_16x16x32_bf16 v[116:119], v[166:169], v[182:185], v[116:119]
	v_mfma_f32_16x16x32_bf16 v[112:115], v[174:177], v[182:185], v[112:115]
	v_mfma_f32_16x16x32_bf16 v[100:103], v[166:169], v[190:193], v[100:103]
	v_mfma_f32_16x16x32_bf16 v[96:99], v[174:177], v[190:193], v[96:99]
	v_mfma_f32_16x16x32_bf16 v[84:87], v[166:169], v[198:201], v[84:87]
	v_mfma_f32_16x16x32_bf16 v[80:83], v[174:177], v[198:201], v[80:83]
	v_mfma_f32_16x16x32_bf16 v[68:71], v[166:169], v[206:209], v[68:71]
	v_mfma_f32_16x16x32_bf16 v[64:67], v[174:177], v[206:209], v[64:67]
	v_mfma_f32_16x16x32_bf16 v[116:119], v[170:173], v[186:189], v[116:119]
	v_mfma_f32_16x16x32_bf16 v[112:115], v[178:181], v[186:189], v[112:115]
	v_mfma_f32_16x16x32_bf16 v[100:103], v[170:173], v[194:197], v[100:103]
	v_mfma_f32_16x16x32_bf16 v[96:99], v[178:181], v[194:197], v[96:99]
	v_mfma_f32_16x16x32_bf16 v[84:87], v[170:173], v[202:205], v[84:87]
	v_mfma_f32_16x16x32_bf16 v[80:83], v[178:181], v[202:205], v[80:83]
	v_mfma_f32_16x16x32_bf16 v[68:71], v[170:173], v[210:213], v[68:71]
	v_mfma_f32_16x16x32_bf16 v[64:67], v[178:181], v[210:213], v[64:67]
	s_setprio 0
	s_setprio 1
	v_mfma_f32_16x16x32_bf16 v[60:63], v[144:147], v[220:223], v[60:63]
	v_mfma_f32_16x16x32_bf16 v[56:59], v[158:161], v[220:223], v[56:59]
	v_mfma_f32_16x16x32_bf16 v[44:47], v[144:147], v[228:231], v[44:47]
	v_mfma_f32_16x16x32_bf16 v[40:43], v[158:161], v[228:231], v[40:43]
	v_mfma_f32_16x16x32_bf16 v[28:31], v[144:147], v[236:239], v[28:31]
	v_mfma_f32_16x16x32_bf16 v[24:27], v[158:161], v[236:239], v[24:27]
	v_mfma_f32_16x16x32_bf16 v[12:15], v[144:147], v[244:247], v[12:15]
	v_mfma_f32_16x16x32_bf16 v[8:11], v[158:161], v[244:247], v[8:11]
	v_mfma_f32_16x16x32_bf16 v[60:63], v[154:157], v[224:227], v[60:63]
	v_mfma_f32_16x16x32_bf16 v[56:59], v[162:165], v[224:227], v[56:59]
	v_mfma_f32_16x16x32_bf16 v[44:47], v[154:157], v[232:235], v[44:47]
	v_mfma_f32_16x16x32_bf16 v[40:43], v[162:165], v[232:235], v[40:43]
	v_mfma_f32_16x16x32_bf16 v[28:31], v[154:157], v[240:243], v[28:31]
	v_mfma_f32_16x16x32_bf16 v[24:27], v[162:165], v[240:243], v[24:27]
	v_mfma_f32_16x16x32_bf16 v[12:15], v[154:157], v[248:251], v[12:15]
	v_mfma_f32_16x16x32_bf16 v[8:11], v[162:165], v[248:251], v[8:11]
	s_setprio 0
	s_setprio 1
	v_mfma_f32_16x16x32_bf16 v[52:55], v[166:169], v[220:223], v[52:55]
	v_mfma_f32_16x16x32_bf16 v[48:51], v[174:177], v[220:223], v[48:51]
	v_mfma_f32_16x16x32_bf16 v[36:39], v[166:169], v[228:231], v[36:39]
	v_mfma_f32_16x16x32_bf16 v[32:35], v[174:177], v[228:231], v[32:35]
	v_mfma_f32_16x16x32_bf16 v[20:23], v[166:169], v[236:239], v[20:23]
	v_mfma_f32_16x16x32_bf16 v[16:19], v[174:177], v[236:239], v[16:19]
	v_mfma_f32_16x16x32_bf16 v[4:7], v[166:169], v[244:247], v[4:7]
	v_mfma_f32_16x16x32_bf16 v[0:3], v[174:177], v[244:247], v[0:3]
	v_mfma_f32_16x16x32_bf16 v[52:55], v[170:173], v[224:227], v[52:55]
	v_mfma_f32_16x16x32_bf16 v[48:51], v[178:181], v[224:227], v[48:51]
	v_mfma_f32_16x16x32_bf16 v[36:39], v[170:173], v[232:235], v[36:39]
	v_mfma_f32_16x16x32_bf16 v[32:35], v[178:181], v[232:235], v[32:35]
	v_mfma_f32_16x16x32_bf16 v[20:23], v[170:173], v[240:243], v[20:23]
	v_mfma_f32_16x16x32_bf16 v[16:19], v[178:181], v[240:243], v[16:19]
	v_mfma_f32_16x16x32_bf16 v[4:7], v[170:173], v[248:251], v[4:7]
	v_mfma_f32_16x16x32_bf16 v[0:3], v[178:181], v[248:251], v[0:3]
	s_setprio 0
	s_waitcnt vmcnt(4)
	s_barrier
	s_add_u32 vcc_lo, s34, 0x0
	s_addc_u32 vcc_hi, s35, 0
	s_add_i32 m0, s36, 0x2000
	s_nop 0
	global_load_lds_dwordx4 v130, vcc
	s_add_u32 vcc_lo, vcc_lo, 0x10000
	s_addc_u32 vcc_hi, vcc_hi, 0
	s_add_i32 m0, s36, 0x1000
	s_nop 0
	global_load_lds_dwordx4 v134, vcc
	s_add_u32 vcc_lo, vcc_lo, 0x30000
	s_addc_u32 vcc_hi, vcc_hi, 0
	s_add_i32 m0, s36, 0x6000
	s_nop 0
	global_load_lds_dwordx4 v130, vcc
	s_add_u32 vcc_lo, vcc_lo, 0x10000
	s_addc_u32 vcc_hi, vcc_hi, 0
	s_add_i32 m0, s36, 0x5000
	s_nop 0
	global_load_lds_dwordx4 v134, vcc
	s_add_u32 vcc_lo, s34, 0x80
	s_addc_u32 vcc_hi, s35, 0
	s_add_i32 m0, s36, 0x8000
	s_nop 0
	global_load_lds_dwordx4 v134, vcc
	s_sub_u32 vcc_lo, vcc_lo, 0x10000
	s_subb_u32 vcc_hi, vcc_hi, 0
	s_add_i32 m0, s36, 0x7000
	s_nop 0
	global_load_lds_dwordx4 v134, vcc
	s_add_u32 vcc_lo, vcc_lo, 0x50000
	s_addc_u32 vcc_hi, vcc_hi, 0
	s_add_i32 m0, s36, 0xc000
	s_nop 0
	global_load_lds_dwordx4 v134, vcc
	s_sub_u32 vcc_lo, vcc_lo, 0x10000
	s_subb_u32 vcc_hi, vcc_hi, 0
	s_add_i32 m0, s36, 0xb000
	s_nop 0
	global_load_lds_dwordx4 v134, vcc
	ds_read_b128 v[144:147], v151 offset:32768
	ds_read_b128 v[154:157], v151 offset:33792
	ds_read_b128 v[158:161], v151 offset:34816
	ds_read_b128 v[162:165], v151 offset:35840
	ds_read_b128 v[166:169], v152 offset:32768
	ds_read_b128 v[170:173], v152 offset:33792
	ds_read_b128 v[174:177], v152 offset:34816
	ds_read_b128 v[178:181], v152 offset:35840
	ds_read_b128 v[182:185], v153 offset:32768
	ds_read_b128 v[186:189], v153 offset:33792
	ds_read_b128 v[190:193], v153 offset:34816
	ds_read_b128 v[194:197], v153 offset:35840
	ds_read_b128 v[198:201], v153 offset:36864
	ds_read_b128 v[202:205], v153 offset:37888
	ds_read_b128 v[206:209], v153 offset:38912
	ds_read_b128 v[210:213], v153 offset:39936
	ds_read_b128 v[220:223], v153 offset:49152
	ds_read_b128 v[224:227], v153 offset:50176
	ds_read_b128 v[228:231], v153 offset:51200
	ds_read_b128 v[232:235], v153 offset:52224
	ds_read_b128 v[236:239], v153 offset:53248
	ds_read_b128 v[240:243], v153 offset:54272
	ds_read_b128 v[244:247], v153 offset:55296
	ds_read_b128 v[248:251], v153 offset:56320
	s_nop 15
	s_nop 15
	s_waitcnt vmcnt(8) lgkmcnt(0)
	s_barrier
	s_setprio 1
	v_mfma_f32_16x16x32_bf16 v[124:127], v[144:147], v[182:185], v[124:127]
	v_mfma_f32_16x16x32_bf16 v[120:123], v[158:161], v[182:185], v[120:123]
	v_mfma_f32_16x16x32_bf16 v[108:111], v[144:147], v[190:193], v[108:111]
	v_mfma_f32_16x16x32_bf16 v[104:107], v[158:161], v[190:193], v[104:107]
	v_mfma_f32_16x16x32_bf16 v[92:95], v[144:147], v[198:201], v[92:95]
	v_mfma_f32_16x16x32_bf16 v[88:91], v[158:161], v[198:201], v[88:91]
	v_mfma_f32_16x16x32_bf16 v[76:79], v[144:147], v[206:209], v[76:79]
	v_mfma_f32_16x16x32_bf16 v[72:75], v[158:161], v[206:209], v[72:75]
	v_mfma_f32_16x16x32_bf16 v[124:127], v[154:157], v[186:189], v[124:127]
	v_mfma_f32_16x16x32_bf16 v[120:123], v[162:165], v[186:189], v[120:123]
	v_mfma_f32_16x16x32_bf16 v[108:111], v[154:157], v[194:197], v[108:111]
	v_mfma_f32_16x16x32_bf16 v[104:107], v[162:165], v[194:197], v[104:107]
	v_mfma_f32_16x16x32_bf16 v[92:95], v[154:157], v[202:205], v[92:95]
	v_mfma_f32_16x16x32_bf16 v[88:91], v[162:165], v[202:205], v[88:91]
	v_mfma_f32_16x16x32_bf16 v[76:79], v[154:157], v[210:213], v[76:79]
	v_mfma_f32_16x16x32_bf16 v[72:75], v[162:165], v[210:213], v[72:75]
	s_setprio 0
	s_setprio 1
	v_mfma_f32_16x16x32_bf16 v[116:119], v[166:169], v[182:185], v[116:119]
	v_mfma_f32_16x16x32_bf16 v[112:115], v[174:177], v[182:185], v[112:115]
	v_mfma_f32_16x16x32_bf16 v[100:103], v[166:169], v[190:193], v[100:103]
	v_mfma_f32_16x16x32_bf16 v[96:99], v[174:177], v[190:193], v[96:99]
	v_mfma_f32_16x16x32_bf16 v[84:87], v[166:169], v[198:201], v[84:87]
	v_mfma_f32_16x16x32_bf16 v[80:83], v[174:177], v[198:201], v[80:83]
	v_mfma_f32_16x16x32_bf16 v[68:71], v[166:169], v[206:209], v[68:71]
	v_mfma_f32_16x16x32_bf16 v[64:67], v[174:177], v[206:209], v[64:67]
	v_mfma_f32_16x16x32_bf16 v[116:119], v[170:173], v[186:189], v[116:119]
	v_mfma_f32_16x16x32_bf16 v[112:115], v[178:181], v[186:189], v[112:115]
	v_mfma_f32_16x16x32_bf16 v[100:103], v[170:173], v[194:197], v[100:103]
	v_mfma_f32_16x16x32_bf16 v[96:99], v[178:181], v[194:197], v[96:99]
	v_mfma_f32_16x16x32_bf16 v[84:87], v[170:173], v[202:205], v[84:87]
	v_mfma_f32_16x16x32_bf16 v[80:83], v[178:181], v[202:205], v[80:83]
	v_mfma_f32_16x16x32_bf16 v[68:71], v[170:173], v[210:213], v[68:71]
	v_mfma_f32_16x16x32_bf16 v[64:67], v[178:181], v[210:213], v[64:67]
	s_setprio 0
	s_setprio 1
	v_mfma_f32_16x16x32_bf16 v[60:63], v[144:147], v[220:223], v[60:63]
	v_mfma_f32_16x16x32_bf16 v[56:59], v[158:161], v[220:223], v[56:59]
	v_mfma_f32_16x16x32_bf16 v[44:47], v[144:147], v[228:231], v[44:47]
	v_mfma_f32_16x16x32_bf16 v[40:43], v[158:161], v[228:231], v[40:43]
	v_mfma_f32_16x16x32_bf16 v[28:31], v[144:147], v[236:239], v[28:31]
	v_mfma_f32_16x16x32_bf16 v[24:27], v[158:161], v[236:239], v[24:27]
	v_mfma_f32_16x16x32_bf16 v[12:15], v[144:147], v[244:247], v[12:15]
	v_mfma_f32_16x16x32_bf16 v[8:11], v[158:161], v[244:247], v[8:11]
	v_mfma_f32_16x16x32_bf16 v[60:63], v[154:157], v[224:227], v[60:63]
	v_mfma_f32_16x16x32_bf16 v[56:59], v[162:165], v[224:227], v[56:59]
	v_mfma_f32_16x16x32_bf16 v[44:47], v[154:157], v[232:235], v[44:47]
	v_mfma_f32_16x16x32_bf16 v[40:43], v[162:165], v[232:235], v[40:43]
	v_mfma_f32_16x16x32_bf16 v[28:31], v[154:157], v[240:243], v[28:31]
	v_mfma_f32_16x16x32_bf16 v[24:27], v[162:165], v[240:243], v[24:27]
	v_mfma_f32_16x16x32_bf16 v[12:15], v[154:157], v[248:251], v[12:15]
	v_mfma_f32_16x16x32_bf16 v[8:11], v[162:165], v[248:251], v[8:11]
	s_setprio 0
	s_setprio 1
	v_mfma_f32_16x16x32_bf16 v[52:55], v[166:169], v[220:223], v[52:55]
	v_mfma_f32_16x16x32_bf16 v[48:51], v[174:177], v[220:223], v[48:51]
	v_mfma_f32_16x16x32_bf16 v[36:39], v[166:169], v[228:231], v[36:39]
	v_mfma_f32_16x16x32_bf16 v[32:35], v[174:177], v[228:231], v[32:35]
	v_mfma_f32_16x16x32_bf16 v[20:23], v[166:169], v[236:239], v[20:23]
	v_mfma_f32_16x16x32_bf16 v[16:19], v[174:177], v[236:239], v[16:19]
	v_mfma_f32_16x16x32_bf16 v[4:7], v[166:169], v[244:247], v[4:7]
	v_mfma_f32_16x16x32_bf16 v[0:3], v[174:177], v[244:247], v[0:3]
	v_mfma_f32_16x16x32_bf16 v[52:55], v[170:173], v[224:227], v[52:55]
	v_mfma_f32_16x16x32_bf16 v[48:51], v[178:181], v[224:227], v[48:51]
	v_mfma_f32_16x16x32_bf16 v[36:39], v[170:173], v[232:235], v[36:39]
	v_mfma_f32_16x16x32_bf16 v[32:35], v[178:181], v[232:235], v[32:35]
	v_mfma_f32_16x16x32_bf16 v[20:23], v[170:173], v[240:243], v[20:23]
	v_mfma_f32_16x16x32_bf16 v[16:19], v[178:181], v[240:243], v[16:19]
	v_mfma_f32_16x16x32_bf16 v[4:7], v[170:173], v[248:251], v[4:7]
	v_mfma_f32_16x16x32_bf16 v[0:3], v[178:181], v[248:251], v[0:3]
	s_setprio 0
	s_waitcnt vmcnt(4)
	s_barrier
	s_add_i32 s56, s56, 2
	s_add_u32 s12, s12, 0x100
	s_addc_u32 s13, s13, 0
	s_add_u32 s54, s54, 0x100
	s_addc_u32 s55, s55, 0
	s_cmp_gt_u32 s56, 13
	s_cbranch_scc0 .LBB0_686

.LBB0_761:
	s_add_u32 s36, s34, 0xfff80080
	s_addc_u32 s37, s35, -1
	s_cmp_eq_u32 s58, 28
	s_cselect_b32 s43, s23, s37
	s_cselect_b32 s42, s29, s36
	s_cselect_b32 s37, s13, s57
	s_cselect_b32 s36, s31, s56
	s_and_b64 vcc, exec, s[10:11]
	s_cbranch_vccz .Lk64_trail_p5
	s_sub_u32 vcc_lo, s56, 0x80
	s_subb_u32 vcc_hi, s57, 0
	s_add_i32 m0, s44, 0x18000
	s_nop 0
	global_load_lds_dwordx4 v130, vcc
	s_add_i32 m0, s44, 0x1a000
	s_nop 0
	global_load_lds_dwordx4 v134, vcc
	s_add_u32 vcc_lo, vcc_lo, 0x20000
	s_addc_u32 vcc_hi, vcc_hi, 0
	s_add_i32 m0, s44, 0x19000
	s_nop 0
	global_load_lds_dwordx4 v130, vcc
	s_add_i32 m0, s44, 0x1b000
	s_nop 0
	global_load_lds_dwordx4 v134, vcc
	s_add_u32 vcc_lo, vcc_lo, 0x60000
	s_addc_u32 vcc_hi, vcc_hi, 0
	s_add_i32 m0, s44, 0x1c000
	s_nop 0
	global_load_lds_dwordx4 v130, vcc
	s_add_i32 m0, s44, 0x1e000
	s_nop 0
	global_load_lds_dwordx4 v134, vcc
	s_add_u32 vcc_lo, vcc_lo, 0x20000
	s_addc_u32 vcc_hi, vcc_hi, 0
	s_add_i32 m0, s44, 0x1d000
	s_nop 0
	global_load_lds_dwordx4 v130, vcc
	s_add_i32 m0, s44, 0x1f000
	s_nop 0
	global_load_lds_dwordx4 v134, vcc
	ds_read_b128 v[144:147], v153 offset:0
	ds_read_b128 v[158:161], v153 offset:1024
	ds_read_b128 v[162:165], v153 offset:2048
	ds_read_b128 v[166:169], v153 offset:3072
	ds_read_b128 v[186:189], v155 offset:0
	ds_read_b128 v[190:193], v155 offset:1024
	ds_read_b128 v[194:197], v155 offset:2048
	ds_read_b128 v[198:201], v155 offset:3072
	ds_read_b128 v[202:205], v155 offset:4096
	ds_read_b128 v[206:209], v155 offset:5120
	ds_read_b128 v[210:213], v155 offset:6144
	ds_read_b128 v[214:217], v155 offset:7168
	ds_read_b128 v[220:223], v155 offset:16384
	ds_read_b128 v[224:227], v155 offset:17408
	ds_read_b128 v[228:231], v155 offset:18432
	ds_read_b128 v[232:235], v155 offset:19456
	ds_read_b128 v[236:239], v155 offset:20480
	ds_read_b128 v[240:243], v155 offset:21504
	ds_read_b128 v[244:247], v155 offset:22528
	ds_read_b128 v[248:251], v155 offset:23552
	s_nop 15
	s_nop 15
	s_waitcnt vmcnt(8) lgkmcnt(0)
	s_barrier
	ds_read_b128 v[170:173], v154 offset:0
	ds_read_b128 v[174:177], v154 offset:1024
	ds_read_b128 v[178:181], v154 offset:2048
	ds_read_b128 v[182:185], v154 offset:3072
	s_setprio 1
	v_mfma_f32_16x16x32_bf16 v[124:127], v[144:147], v[186:189], v[124:127]
	v_mfma_f32_16x16x32_bf16 v[120:123], v[162:165], v[186:189], v[120:123]
	v_mfma_f32_16x16x32_bf16 v[108:111], v[144:147], v[194:197], v[108:111]
	v_mfma_f32_16x16x32_bf16 v[104:107], v[162:165], v[194:197], v[104:107]
	v_mfma_f32_16x16x32_bf16 v[92:95], v[144:147], v[202:205], v[92:95]
	v_mfma_f32_16x16x32_bf16 v[88:91], v[162:165], v[202:205], v[88:91]
	v_mfma_f32_16x16x32_bf16 v[76:79], v[144:147], v[210:213], v[76:79]
	v_mfma_f32_16x16x32_bf16 v[72:75], v[162:165], v[210:213], v[72:75]
	v_mfma_f32_16x16x32_bf16 v[124:127], v[158:161], v[190:193], v[124:127]
	v_mfma_f32_16x16x32_bf16 v[120:123], v[166:169], v[190:193], v[120:123]
	v_mfma_f32_16x16x32_bf16 v[108:111], v[158:161], v[198:201], v[108:111]
	v_mfma_f32_16x16x32_bf16 v[104:107], v[166:169], v[198:201], v[104:107]
	v_mfma_f32_16x16x32_bf16 v[92:95], v[158:161], v[206:209], v[92:95]
	v_mfma_f32_16x16x32_bf16 v[88:91], v[166:169], v[206:209], v[88:91]
	v_mfma_f32_16x16x32_bf16 v[76:79], v[158:161], v[214:217], v[76:79]
	v_mfma_f32_16x16x32_bf16 v[72:75], v[166:169], v[214:217], v[72:75]
	s_setprio 0
	s_waitcnt lgkmcnt(0)
	s_setprio 1
	v_mfma_f32_16x16x32_bf16 v[116:119], v[170:173], v[186:189], v[116:119]
	v_mfma_f32_16x16x32_bf16 v[112:115], v[178:181], v[186:189], v[112:115]
	v_mfma_f32_16x16x32_bf16 v[100:103], v[170:173], v[194:197], v[100:103]
	v_mfma_f32_16x16x32_bf16 v[96:99], v[178:181], v[194:197], v[96:99]
	v_mfma_f32_16x16x32_bf16 v[84:87], v[170:173], v[202:205], v[84:87]
	v_mfma_f32_16x16x32_bf16 v[80:83], v[178:181], v[202:205], v[80:83]
	v_mfma_f32_16x16x32_bf16 v[68:71], v[170:173], v[210:213], v[68:71]
	v_mfma_f32_16x16x32_bf16 v[64:67], v[178:181], v[210:213], v[64:67]
	v_mfma_f32_16x16x32_bf16 v[116:119], v[174:177], v[190:193], v[116:119]
	v_mfma_f32_16x16x32_bf16 v[112:115], v[182:185], v[190:193], v[112:115]
	v_mfma_f32_16x16x32_bf16 v[100:103], v[174:177], v[198:201], v[100:103]
	v_mfma_f32_16x16x32_bf16 v[96:99], v[182:185], v[198:201], v[96:99]
	v_mfma_f32_16x16x32_bf16 v[84:87], v[174:177], v[206:209], v[84:87]
	v_mfma_f32_16x16x32_bf16 v[80:83], v[182:185], v[206:209], v[80:83]
	v_mfma_f32_16x16x32_bf16 v[68:71], v[174:177], v[214:217], v[68:71]
	v_mfma_f32_16x16x32_bf16 v[64:67], v[182:185], v[214:217], v[64:67]
	s_setprio 0
	s_setprio 1
	v_mfma_f32_16x16x32_bf16 v[60:63], v[144:147], v[220:223], v[60:63]
	v_mfma_f32_16x16x32_bf16 v[56:59], v[162:165], v[220:223], v[56:59]
	v_mfma_f32_16x16x32_bf16 v[44:47], v[144:147], v[228:231], v[44:47]
	v_mfma_f32_16x16x32_bf16 v[40:43], v[162:165], v[228:231], v[40:43]
	v_mfma_f32_16x16x32_bf16 v[28:31], v[144:147], v[236:239], v[28:31]
	v_mfma_f32_16x16x32_bf16 v[24:27], v[162:165], v[236:239], v[24:27]
	v_mfma_f32_16x16x32_bf16 v[12:15], v[144:147], v[244:247], v[12:15]
	v_mfma_f32_16x16x32_bf16 v[8:11], v[162:165], v[244:247], v[8:11]
	v_mfma_f32_16x16x32_bf16 v[60:63], v[158:161], v[224:227], v[60:63]
	v_mfma_f32_16x16x32_bf16 v[56:59], v[166:169], v[224:227], v[56:59]
	v_mfma_f32_16x16x32_bf16 v[44:47], v[158:161], v[232:235], v[44:47]
	v_mfma_f32_16x16x32_bf16 v[40:43], v[166:169], v[232:235], v[40:43]
	v_mfma_f32_16x16x32_bf16 v[28:31], v[158:161], v[240:243], v[28:31]
	v_mfma_f32_16x16x32_bf16 v[24:27], v[166:169], v[240:243], v[24:27]
	v_mfma_f32_16x16x32_bf16 v[12:15], v[158:161], v[248:251], v[12:15]
	v_mfma_f32_16x16x32_bf16 v[8:11], v[166:169], v[248:251], v[8:11]
	s_setprio 0
	s_setprio 1
	v_mfma_f32_16x16x32_bf16 v[52:55], v[170:173], v[220:223], v[52:55]
	v_mfma_f32_16x16x32_bf16 v[48:51], v[178:181], v[220:223], v[48:51]
	v_mfma_f32_16x16x32_bf16 v[36:39], v[170:173], v[228:231], v[36:39]
	v_mfma_f32_16x16x32_bf16 v[32:35], v[178:181], v[228:231], v[32:35]
	v_mfma_f32_16x16x32_bf16 v[20:23], v[170:173], v[236:239], v[20:23]
	v_mfma_f32_16x16x32_bf16 v[16:19], v[178:181], v[236:239], v[16:19]
	v_mfma_f32_16x16x32_bf16 v[4:7], v[170:173], v[244:247], v[4:7]
	v_mfma_f32_16x16x32_bf16 v[0:3], v[178:181], v[244:247], v[0:3]
	v_mfma_f32_16x16x32_bf16 v[52:55], v[174:177], v[224:227], v[52:55]
	v_mfma_f32_16x16x32_bf16 v[48:51], v[182:185], v[224:227], v[48:51]
	v_mfma_f32_16x16x32_bf16 v[36:39], v[174:177], v[232:235], v[36:39]
	v_mfma_f32_16x16x32_bf16 v[32:35], v[182:185], v[232:235], v[32:35]
	v_mfma_f32_16x16x32_bf16 v[20:23], v[174:177], v[240:243], v[20:23]
	v_mfma_f32_16x16x32_bf16 v[16:19], v[182:185], v[240:243], v[16:19]
	v_mfma_f32_16x16x32_bf16 v[4:7], v[174:177], v[248:251], v[4:7]
	v_mfma_f32_16x16x32_bf16 v[0:3], v[182:185], v[248:251], v[0:3]
	s_setprio 0
	s_waitcnt vmcnt(4)
	s_barrier
	s_add_u32 vcc_lo, s36, 0x0
	s_addc_u32 vcc_hi, s37, 0
	s_add_i32 m0, s44, 0x10000
	s_nop 0
	global_load_lds_dwordx4 v130, vcc
	s_add_i32 m0, s44, 0x12000
	s_nop 0
	global_load_lds_dwordx4 v134, vcc
	s_add_u32 vcc_lo, vcc_lo, 0x20000
	s_addc_u32 vcc_hi, vcc_hi, 0
	s_add_i32 m0, s44, 0x11000
	s_nop 0
	global_load_lds_dwordx4 v130, vcc
	s_add_i32 m0, s44, 0x13000
	s_nop 0
	global_load_lds_dwordx4 v134, vcc
	s_add_u32 vcc_lo, vcc_lo, 0x60000
	s_addc_u32 vcc_hi, vcc_hi, 0
	s_add_i32 m0, s44, 0x14000
	s_nop 0
	global_load_lds_dwordx4 v130, vcc
	s_add_i32 m0, s44, 0x16000
	s_nop 0
	global_load_lds_dwordx4 v134, vcc
	s_add_u32 vcc_lo, vcc_lo, 0x20000
	s_addc_u32 vcc_hi, vcc_hi, 0
	s_add_i32 m0, s44, 0x15000
	s_nop 0
	global_load_lds_dwordx4 v130, vcc
	s_add_i32 m0, s44, 0x17000
	s_nop 0
	global_load_lds_dwordx4 v134, vcc
	ds_read_b128 v[144:147], v153 offset:32768
	ds_read_b128 v[158:161], v153 offset:33792
	ds_read_b128 v[162:165], v153 offset:34816
	ds_read_b128 v[166:169], v153 offset:35840
	ds_read_b128 v[186:189], v155 offset:32768
	ds_read_b128 v[190:193], v155 offset:33792
	ds_read_b128 v[194:197], v155 offset:34816
	ds_read_b128 v[198:201], v155 offset:35840
	ds_read_b128 v[202:205], v155 offset:36864
	ds_read_b128 v[206:209], v155 offset:37888
	ds_read_b128 v[210:213], v155 offset:38912
	ds_read_b128 v[214:217], v155 offset:39936
	ds_read_b128 v[220:223], v155 offset:49152
	ds_read_b128 v[224:227], v155 offset:50176
	ds_read_b128 v[228:231], v155 offset:51200
	ds_read_b128 v[232:235], v155 offset:52224
	ds_read_b128 v[236:239], v155 offset:53248
	ds_read_b128 v[240:243], v155 offset:54272
	ds_read_b128 v[244:247], v155 offset:55296
	ds_read_b128 v[248:251], v155 offset:56320
	s_nop 15
	s_nop 15
	s_waitcnt vmcnt(8) lgkmcnt(0)
	s_barrier
	ds_read_b128 v[170:173], v154 offset:32768
	ds_read_b128 v[174:177], v154 offset:33792
	ds_read_b128 v[178:181], v154 offset:34816
	ds_read_b128 v[182:185], v154 offset:35840
	s_setprio 1
	v_mfma_f32_16x16x32_bf16 v[124:127], v[144:147], v[186:189], v[124:127]
	v_mfma_f32_16x16x32_bf16 v[120:123], v[162:165], v[186:189], v[120:123]
	v_mfma_f32_16x16x32_bf16 v[108:111], v[144:147], v[194:197], v[108:111]
	v_mfma_f32_16x16x32_bf16 v[104:107], v[162:165], v[194:197], v[104:107]
	v_mfma_f32_16x16x32_bf16 v[92:95], v[144:147], v[202:205], v[92:95]
	v_mfma_f32_16x16x32_bf16 v[88:91], v[162:165], v[202:205], v[88:91]
	v_mfma_f32_16x16x32_bf16 v[76:79], v[144:147], v[210:213], v[76:79]
	v_mfma_f32_16x16x32_bf16 v[72:75], v[162:165], v[210:213], v[72:75]
	v_mfma_f32_16x16x32_bf16 v[124:127], v[158:161], v[190:193], v[124:127]
	v_mfma_f32_16x16x32_bf16 v[120:123], v[166:169], v[190:193], v[120:123]
	v_mfma_f32_16x16x32_bf16 v[108:111], v[158:161], v[198:201], v[108:111]
	v_mfma_f32_16x16x32_bf16 v[104:107], v[166:169], v[198:201], v[104:107]
	v_mfma_f32_16x16x32_bf16 v[92:95], v[158:161], v[206:209], v[92:95]
	v_mfma_f32_16x16x32_bf16 v[88:91], v[166:169], v[206:209], v[88:91]
	v_mfma_f32_16x16x32_bf16 v[76:79], v[158:161], v[214:217], v[76:79]
	v_mfma_f32_16x16x32_bf16 v[72:75], v[166:169], v[214:217], v[72:75]
	s_setprio 0
	s_waitcnt lgkmcnt(0)
	s_setprio 1
	v_mfma_f32_16x16x32_bf16 v[116:119], v[170:173], v[186:189], v[116:119]
	v_mfma_f32_16x16x32_bf16 v[112:115], v[178:181], v[186:189], v[112:115]
	v_mfma_f32_16x16x32_bf16 v[100:103], v[170:173], v[194:197], v[100:103]
	v_mfma_f32_16x16x32_bf16 v[96:99], v[178:181], v[194:197], v[96:99]
	v_mfma_f32_16x16x32_bf16 v[84:87], v[170:173], v[202:205], v[84:87]
	v_mfma_f32_16x16x32_bf16 v[80:83], v[178:181], v[202:205], v[80:83]
	v_mfma_f32_16x16x32_bf16 v[68:71], v[170:173], v[210:213], v[68:71]
	v_mfma_f32_16x16x32_bf16 v[64:67], v[178:181], v[210:213], v[64:67]
	v_mfma_f32_16x16x32_bf16 v[116:119], v[174:177], v[190:193], v[116:119]
	v_mfma_f32_16x16x32_bf16 v[112:115], v[182:185], v[190:193], v[112:115]
	v_mfma_f32_16x16x32_bf16 v[100:103], v[174:177], v[198:201], v[100:103]
	v_mfma_f32_16x16x32_bf16 v[96:99], v[182:185], v[198:201], v[96:99]
	v_mfma_f32_16x16x32_bf16 v[84:87], v[174:177], v[206:209], v[84:87]
	v_mfma_f32_16x16x32_bf16 v[80:83], v[182:185], v[206:209], v[80:83]
	v_mfma_f32_16x16x32_bf16 v[68:71], v[174:177], v[214:217], v[68:71]
	v_mfma_f32_16x16x32_bf16 v[64:67], v[182:185], v[214:217], v[64:67]
	s_setprio 0
	s_setprio 1
	v_mfma_f32_16x16x32_bf16 v[60:63], v[144:147], v[220:223], v[60:63]
	v_mfma_f32_16x16x32_bf16 v[56:59], v[162:165], v[220:223], v[56:59]
	v_mfma_f32_16x16x32_bf16 v[44:47], v[144:147], v[228:231], v[44:47]
	v_mfma_f32_16x16x32_bf16 v[40:43], v[162:165], v[228:231], v[40:43]
	v_mfma_f32_16x16x32_bf16 v[28:31], v[144:147], v[236:239], v[28:31]
	v_mfma_f32_16x16x32_bf16 v[24:27], v[162:165], v[236:239], v[24:27]
	v_mfma_f32_16x16x32_bf16 v[12:15], v[144:147], v[244:247], v[12:15]
	v_mfma_f32_16x16x32_bf16 v[8:11], v[162:165], v[244:247], v[8:11]
	v_mfma_f32_16x16x32_bf16 v[60:63], v[158:161], v[224:227], v[60:63]
	v_mfma_f32_16x16x32_bf16 v[56:59], v[166:169], v[224:227], v[56:59]
	v_mfma_f32_16x16x32_bf16 v[44:47], v[158:161], v[232:235], v[44:47]
	v_mfma_f32_16x16x32_bf16 v[40:43], v[166:169], v[232:235], v[40:43]
	v_mfma_f32_16x16x32_bf16 v[28:31], v[158:161], v[240:243], v[28:31]
	v_mfma_f32_16x16x32_bf16 v[24:27], v[166:169], v[240:243], v[24:27]
	v_mfma_f32_16x16x32_bf16 v[12:15], v[158:161], v[248:251], v[12:15]
	v_mfma_f32_16x16x32_bf16 v[8:11], v[166:169], v[248:251], v[8:11]
	s_setprio 0
	s_setprio 1
	v_mfma_f32_16x16x32_bf16 v[52:55], v[170:173], v[220:223], v[52:55]
	v_mfma_f32_16x16x32_bf16 v[48:51], v[178:181], v[220:223], v[48:51]
	v_mfma_f32_16x16x32_bf16 v[36:39], v[170:173], v[228:231], v[36:39]
	v_mfma_f32_16x16x32_bf16 v[32:35], v[178:181], v[228:231], v[32:35]
	v_mfma_f32_16x16x32_bf16 v[20:23], v[170:173], v[236:239], v[20:23]
	v_mfma_f32_16x16x32_bf16 v[16:19], v[178:181], v[236:239], v[16:19]
	v_mfma_f32_16x16x32_bf16 v[4:7], v[170:173], v[244:247], v[4:7]
	v_mfma_f32_16x16x32_bf16 v[0:3], v[178:181], v[244:247], v[0:3]
	v_mfma_f32_16x16x32_bf16 v[52:55], v[174:177], v[224:227], v[52:55]
	v_mfma_f32_16x16x32_bf16 v[48:51], v[182:185], v[224:227], v[48:51]
	v_mfma_f32_16x16x32_bf16 v[36:39], v[174:177], v[232:235], v[36:39]
	v_mfma_f32_16x16x32_bf16 v[32:35], v[182:185], v[232:235], v[32:35]
	v_mfma_f32_16x16x32_bf16 v[20:23], v[174:177], v[240:243], v[20:23]
	v_mfma_f32_16x16x32_bf16 v[16:19], v[182:185], v[240:243], v[16:19]
	v_mfma_f32_16x16x32_bf16 v[4:7], v[174:177], v[248:251], v[4:7]
	v_mfma_f32_16x16x32_bf16 v[0:3], v[182:185], v[248:251], v[0:3]
	s_setprio 0
	s_waitcnt vmcnt(4)
	s_barrier
	s_add_i32 s58, s58, 2
	s_add_u32 s34, s34, 0x100
	s_addc_u32 s35, s35, 0
	s_add_u32 s56, s56, 0x100
	s_addc_u32 s57, s57, 0
	s_cmp_gt_u32 s58, 29
	s_cbranch_scc0 .LBB0_761
	s_branch .Lk64_done_p5
.Lk64_trail_p5:
	s_sub_u32 vcc_lo, s34, 0x80000
	s_subb_u32 vcc_hi, s35, 0
	s_add_i32 m0, s44, 0xa000
	s_nop 0
	global_load_lds_dwordx4 v132, vcc
	s_add_u32 vcc_lo, vcc_lo, 0x20000
	s_addc_u32 vcc_hi, vcc_hi, 0
	s_add_i32 m0, s44, 0x9000
	s_nop 0
	global_load_lds_dwordx4 v128, vcc
	s_add_u32 vcc_lo, vcc_lo, 0x60000
	s_addc_u32 vcc_hi, vcc_hi, 0
	s_add_i32 m0, s44, 0xe000
	s_nop 0
	global_load_lds_dwordx4 v132, vcc
	s_add_u32 vcc_lo, vcc_lo, 0x20000
	s_addc_u32 vcc_hi, vcc_hi, 0
	s_add_i32 m0, s44, 0xd000
	s_nop 0
	global_load_lds_dwordx4 v128, vcc
	s_add_u32 vcc_lo, s42, 0x0
	s_addc_u32 vcc_hi, s43, 0
	s_mov_b32 m0, s44
	s_nop 0
	global_load_lds_dwordx4 v128, vcc
	s_sub_u32 vcc_lo, vcc_lo, 0x20000
	s_subb_u32 vcc_hi, vcc_hi, 0
	s_sub_i32 m0, s44, 0x1000
	s_nop 0
	global_load_lds_dwordx4 v128, vcc
	s_add_u32 vcc_lo, vcc_lo, 0xa0000
	s_addc_u32 vcc_hi, vcc_hi, 0
	s_add_i32 m0, s44, 0x4000
	s_nop 0
	global_load_lds_dwordx4 v128, vcc
	s_sub_u32 vcc_lo, vcc_lo, 0x20000
	s_subb_u32 vcc_hi, vcc_hi, 0
	s_add_i32 m0, s44, 0x3000
	s_nop 0
	global_load_lds_dwordx4 v128, vcc
	ds_read_b128 v[144:147], v153 offset:0
	ds_read_b128 v[158:161], v153 offset:1024
	ds_read_b128 v[162:165], v153 offset:2048
	ds_read_b128 v[166:169], v153 offset:3072
	ds_read_b128 v[170:173], v154 offset:0
	ds_read_b128 v[174:177], v154 offset:1024
	ds_read_b128 v[178:181], v154 offset:2048
	ds_read_b128 v[182:185], v154 offset:3072
	ds_read_b128 v[186:189], v155 offset:0
	ds_read_b128 v[190:193], v155 offset:1024
	ds_read_b128 v[194:197], v155 offset:2048
	ds_read_b128 v[198:201], v155 offset:3072
	ds_read_b128 v[202:205], v155 offset:4096
	ds_read_b128 v[206:209], v155 offset:5120
	ds_read_b128 v[210:213], v155 offset:6144
	ds_read_b128 v[214:217], v155 offset:7168
	ds_read_b128 v[220:223], v155 offset:16384
	ds_read_b128 v[224:227], v155 offset:17408
	ds_read_b128 v[228:231], v155 offset:18432
	ds_read_b128 v[232:235], v155 offset:19456
	ds_read_b128 v[236:239], v155 offset:20480
	ds_read_b128 v[240:243], v155 offset:21504
	ds_read_b128 v[244:247], v155 offset:22528
	ds_read_b128 v[248:251], v155 offset:23552
	s_nop 15
	s_nop 15
	s_waitcnt vmcnt(8) lgkmcnt(0)
	s_barrier
	s_setprio 1
	v_mfma_f32_16x16x32_bf16 v[124:127], v[144:147], v[186:189], v[124:127]
	v_mfma_f32_16x16x32_bf16 v[120:123], v[162:165], v[186:189], v[120:123]
	v_mfma_f32_16x16x32_bf16 v[108:111], v[144:147], v[194:197], v[108:111]
	v_mfma_f32_16x16x32_bf16 v[104:107], v[162:165], v[194:197], v[104:107]
	v_mfma_f32_16x16x32_bf16 v[92:95], v[144:147], v[202:205], v[92:95]
	v_mfma_f32_16x16x32_bf16 v[88:91], v[162:165], v[202:205], v[88:91]
	v_mfma_f32_16x16x32_bf16 v[76:79], v[144:147], v[210:213], v[76:79]
	v_mfma_f32_16x16x32_bf16 v[72:75], v[162:165], v[210:213], v[72:75]
	v_mfma_f32_16x16x32_bf16 v[124:127], v[158:161], v[190:193], v[124:127]
	v_mfma_f32_16x16x32_bf16 v[120:123], v[166:169], v[190:193], v[120:123]
	v_mfma_f32_16x16x32_bf16 v[108:111], v[158:161], v[198:201], v[108:111]
	v_mfma_f32_16x16x32_bf16 v[104:107], v[166:169], v[198:201], v[104:107]
	v_mfma_f32_16x16x32_bf16 v[92:95], v[158:161], v[206:209], v[92:95]
	v_mfma_f32_16x16x32_bf16 v[88:91], v[166:169], v[206:209], v[88:91]
	v_mfma_f32_16x16x32_bf16 v[76:79], v[158:161], v[214:217], v[76:79]
	v_mfma_f32_16x16x32_bf16 v[72:75], v[166:169], v[214:217], v[72:75]
	s_setprio 0
	s_setprio 1
	v_mfma_f32_16x16x32_bf16 v[116:119], v[170:173], v[186:189], v[116:119]
	v_mfma_f32_16x16x32_bf16 v[112:115], v[178:181], v[186:189], v[112:115]
	v_mfma_f32_16x16x32_bf16 v[100:103], v[170:173], v[194:197], v[100:103]
	v_mfma_f32_16x16x32_bf16 v[96:99], v[178:181], v[194:197], v[96:99]
	v_mfma_f32_16x16x32_bf16 v[84:87], v[170:173], v[202:205], v[84:87]
	v_mfma_f32_16x16x32_bf16 v[80:83], v[178:181], v[202:205], v[80:83]
	v_mfma_f32_16x16x32_bf16 v[68:71], v[170:173], v[210:213], v[68:71]
	v_mfma_f32_16x16x32_bf16 v[64:67], v[178:181], v[210:213], v[64:67]
	v_mfma_f32_16x16x32_bf16 v[116:119], v[174:177], v[190:193], v[116:119]
	v_mfma_f32_16x16x32_bf16 v[112:115], v[182:185], v[190:193], v[112:115]
	v_mfma_f32_16x16x32_bf16 v[100:103], v[174:177], v[198:201], v[100:103]
	v_mfma_f32_16x16x32_bf16 v[96:99], v[182:185], v[198:201], v[96:99]
	v_mfma_f32_16x16x32_bf16 v[84:87], v[174:177], v[206:209], v[84:87]
	v_mfma_f32_16x16x32_bf16 v[80:83], v[182:185], v[206:209], v[80:83]
	v_mfma_f32_16x16x32_bf16 v[68:71], v[174:177], v[214:217], v[68:71]
	v_mfma_f32_16x16x32_bf16 v[64:67], v[182:185], v[214:217], v[64:67]
	s_setprio 0
	s_setprio 1
	v_mfma_f32_16x16x32_bf16 v[60:63], v[144:147], v[220:223], v[60:63]
	v_mfma_f32_16x16x32_bf16 v[56:59], v[162:165], v[220:223], v[56:59]
	v_mfma_f32_16x16x32_bf16 v[44:47], v[144:147], v[228:231], v[44:47]
	v_mfma_f32_16x16x32_bf16 v[40:43], v[162:165], v[228:231], v[40:43]
	v_mfma_f32_16x16x32_bf16 v[28:31], v[144:147], v[236:239], v[28:31]
	v_mfma_f32_16x16x32_bf16 v[24:27], v[162:165], v[236:239], v[24:27]
	v_mfma_f32_16x16x32_bf16 v[12:15], v[144:147], v[244:247], v[12:15]
	v_mfma_f32_16x16x32_bf16 v[8:11], v[162:165], v[244:247], v[8:11]
	v_mfma_f32_16x16x32_bf16 v[60:63], v[158:161], v[224:227], v[60:63]
	v_mfma_f32_16x16x32_bf16 v[56:59], v[166:169], v[224:227], v[56:59]
	v_mfma_f32_16x16x32_bf16 v[44:47], v[158:161], v[232:235], v[44:47]
	v_mfma_f32_16x16x32_bf16 v[40:43], v[166:169], v[232:235], v[40:43]
	v_mfma_f32_16x16x32_bf16 v[28:31], v[158:161], v[240:243], v[28:31]
	v_mfma_f32_16x16x32_bf16 v[24:27], v[166:169], v[240:243], v[24:27]
	v_mfma_f32_16x16x32_bf16 v[12:15], v[158:161], v[248:251], v[12:15]
	v_mfma_f32_16x16x32_bf16 v[8:11], v[166:169], v[248:251], v[8:11]
	s_setprio 0
	s_setprio 1
	v_mfma_f32_16x16x32_bf16 v[52:55], v[170:173], v[220:223], v[52:55]
	v_mfma_f32_16x16x32_bf16 v[48:51], v[178:181], v[220:223], v[48:51]
	v_mfma_f32_16x16x32_bf16 v[36:39], v[170:173], v[228:231], v[36:39]
	v_mfma_f32_16x16x32_bf16 v[32:35], v[178:181], v[228:231], v[32:35]
	v_mfma_f32_16x16x32_bf16 v[20:23], v[170:173], v[236:239], v[20:23]
	v_mfma_f32_16x16x32_bf16 v[16:19], v[178:181], v[236:239], v[16:19]
	v_mfma_f32_16x16x32_bf16 v[4:7], v[170:173], v[244:247], v[4:7]
	v_mfma_f32_16x16x32_bf16 v[0:3], v[178:181], v[244:247], v[0:3]
	v_mfma_f32_16x16x32_bf16 v[52:55], v[174:177], v[224:227], v[52:55]
	v_mfma_f32_16x16x32_bf16 v[48:51], v[182:185], v[224:227], v[48:51]
	v_mfma_f32_16x16x32_bf16 v[36:39], v[174:177], v[232:235], v[36:39]
	v_mfma_f32_16x16x32_bf16 v[32:35], v[182:185], v[232:235], v[32:35]
	v_mfma_f32_16x16x32_bf16 v[20:23], v[174:177], v[240:243], v[20:23]
	v_mfma_f32_16x16x32_bf16 v[16:19], v[182:185], v[240:243], v[16:19]
	v_mfma_f32_16x16x32_bf16 v[4:7], v[174:177], v[248:251], v[4:7]
	v_mfma_f32_16x16x32_bf16 v[0:3], v[182:185], v[248:251], v[0:3]
	s_setprio 0
	s_waitcnt vmcnt(4)
	s_barrier
	s_add_u32 vcc_lo, s42, 0x0
	s_addc_u32 vcc_hi, s43, 0
	s_add_i32 m0, s44, 0x2000
	s_nop 0
	global_load_lds_dwordx4 v132, vcc
	s_add_u32 vcc_lo, vcc_lo, 0x20000
	s_addc_u32 vcc_hi, vcc_hi, 0
	s_add_i32 m0, s44, 0x1000
	s_nop 0
	global_load_lds_dwordx4 v128, vcc
	s_add_u32 vcc_lo, vcc_lo, 0x60000
	s_addc_u32 vcc_hi, vcc_hi, 0
	s_add_i32 m0, s44, 0x6000
	s_nop 0
	global_load_lds_dwordx4 v132, vcc
	s_add_u32 vcc_lo, vcc_lo, 0x20000
	s_addc_u32 vcc_hi, vcc_hi, 0
	s_add_i32 m0, s44, 0x5000
	s_nop 0
	global_load_lds_dwordx4 v128, vcc
	s_add_u32 vcc_lo, s42, 0x80
	s_addc_u32 vcc_hi, s43, 0
	s_add_i32 m0, s44, 0x8000
	s_nop 0
	global_load_lds_dwordx4 v128, vcc
	s_sub_u32 vcc_lo, vcc_lo, 0x20000
	s_subb_u32 vcc_hi, vcc_hi, 0
	s_add_i32 m0, s44, 0x7000
	s_nop 0
	global_load_lds_dwordx4 v128, vcc
	s_add_u32 vcc_lo, vcc_lo, 0xa0000
	s_addc_u32 vcc_hi, vcc_hi, 0
	s_add_i32 m0, s44, 0xc000
	s_nop 0
	global_load_lds_dwordx4 v128, vcc
	s_sub_u32 vcc_lo, vcc_lo, 0x20000
	s_subb_u32 vcc_hi, vcc_hi, 0
	s_add_i32 m0, s44, 0xb000
	s_nop 0
	global_load_lds_dwordx4 v128, vcc
	ds_read_b128 v[144:147], v153 offset:32768
	ds_read_b128 v[158:161], v153 offset:33792
	ds_read_b128 v[162:165], v153 offset:34816
	ds_read_b128 v[166:169], v153 offset:35840
	ds_read_b128 v[170:173], v154 offset:32768
	ds_read_b128 v[174:177], v154 offset:33792
	ds_read_b128 v[178:181], v154 offset:34816
	ds_read_b128 v[182:185], v154 offset:35840
	ds_read_b128 v[186:189], v155 offset:32768
	ds_read_b128 v[190:193], v155 offset:33792
	ds_read_b128 v[194:197], v155 offset:34816
	ds_read_b128 v[198:201], v155 offset:35840
	ds_read_b128 v[202:205], v155 offset:36864
	ds_read_b128 v[206:209], v155 offset:37888
	ds_read_b128 v[210:213], v155 offset:38912
	ds_read_b128 v[214:217], v155 offset:39936
	ds_read_b128 v[220:223], v155 offset:49152
	ds_read_b128 v[224:227], v155 offset:50176
	ds_read_b128 v[228:231], v155 offset:51200
	ds_read_b128 v[232:235], v155 offset:52224
	ds_read_b128 v[236:239], v155 offset:53248
	ds_read_b128 v[240:243], v155 offset:54272
	ds_read_b128 v[244:247], v155 offset:55296
	ds_read_b128 v[248:251], v155 offset:56320
	s_nop 15
	s_nop 15
	s_waitcnt vmcnt(8) lgkmcnt(0)
	s_barrier
	s_setprio 1
	v_mfma_f32_16x16x32_bf16 v[124:127], v[144:147], v[186:189], v[124:127]
	v_mfma_f32_16x16x32_bf16 v[120:123], v[162:165], v[186:189], v[120:123]
	v_mfma_f32_16x16x32_bf16 v[108:111], v[144:147], v[194:197], v[108:111]
	v_mfma_f32_16x16x32_bf16 v[104:107], v[162:165], v[194:197], v[104:107]
	v_mfma_f32_16x16x32_bf16 v[92:95], v[144:147], v[202:205], v[92:95]
	v_mfma_f32_16x16x32_bf16 v[88:91], v[162:165], v[202:205], v[88:91]
	v_mfma_f32_16x16x32_bf16 v[76:79], v[144:147], v[210:213], v[76:79]
	v_mfma_f32_16x16x32_bf16 v[72:75], v[162:165], v[210:213], v[72:75]
	v_mfma_f32_16x16x32_bf16 v[124:127], v[158:161], v[190:193], v[124:127]
	v_mfma_f32_16x16x32_bf16 v[120:123], v[166:169], v[190:193], v[120:123]
	v_mfma_f32_16x16x32_bf16 v[108:111], v[158:161], v[198:201], v[108:111]
	v_mfma_f32_16x16x32_bf16 v[104:107], v[166:169], v[198:201], v[104:107]
	v_mfma_f32_16x16x32_bf16 v[92:95], v[158:161], v[206:209], v[92:95]
	v_mfma_f32_16x16x32_bf16 v[88:91], v[166:169], v[206:209], v[88:91]
	v_mfma_f32_16x16x32_bf16 v[76:79], v[158:161], v[214:217], v[76:79]
	v_mfma_f32_16x16x32_bf16 v[72:75], v[166:169], v[214:217], v[72:75]
	s_setprio 0
	s_setprio 1
	v_mfma_f32_16x16x32_bf16 v[116:119], v[170:173], v[186:189], v[116:119]
	v_mfma_f32_16x16x32_bf16 v[112:115], v[178:181], v[186:189], v[112:115]
	v_mfma_f32_16x16x32_bf16 v[100:103], v[170:173], v[194:197], v[100:103]
	v_mfma_f32_16x16x32_bf16 v[96:99], v[178:181], v[194:197], v[96:99]
	v_mfma_f32_16x16x32_bf16 v[84:87], v[170:173], v[202:205], v[84:87]
	v_mfma_f32_16x16x32_bf16 v[80:83], v[178:181], v[202:205], v[80:83]
	v_mfma_f32_16x16x32_bf16 v[68:71], v[170:173], v[210:213], v[68:71]
	v_mfma_f32_16x16x32_bf16 v[64:67], v[178:181], v[210:213], v[64:67]
	v_mfma_f32_16x16x32_bf16 v[116:119], v[174:177], v[190:193], v[116:119]
	v_mfma_f32_16x16x32_bf16 v[112:115], v[182:185], v[190:193], v[112:115]
	v_mfma_f32_16x16x32_bf16 v[100:103], v[174:177], v[198:201], v[100:103]
	v_mfma_f32_16x16x32_bf16 v[96:99], v[182:185], v[198:201], v[96:99]
	v_mfma_f32_16x16x32_bf16 v[84:87], v[174:177], v[206:209], v[84:87]
	v_mfma_f32_16x16x32_bf16 v[80:83], v[182:185], v[206:209], v[80:83]
	v_mfma_f32_16x16x32_bf16 v[68:71], v[174:177], v[214:217], v[68:71]
	v_mfma_f32_16x16x32_bf16 v[64:67], v[182:185], v[214:217], v[64:67]
	s_setprio 0
	s_setprio 1
	v_mfma_f32_16x16x32_bf16 v[60:63], v[144:147], v[220:223], v[60:63]
	v_mfma_f32_16x16x32_bf16 v[56:59], v[162:165], v[220:223], v[56:59]
	v_mfma_f32_16x16x32_bf16 v[44:47], v[144:147], v[228:231], v[44:47]
	v_mfma_f32_16x16x32_bf16 v[40:43], v[162:165], v[228:231], v[40:43]
	v_mfma_f32_16x16x32_bf16 v[28:31], v[144:147], v[236:239], v[28:31]
	v_mfma_f32_16x16x32_bf16 v[24:27], v[162:165], v[236:239], v[24:27]
	v_mfma_f32_16x16x32_bf16 v[12:15], v[144:147], v[244:247], v[12:15]
	v_mfma_f32_16x16x32_bf16 v[8:11], v[162:165], v[244:247], v[8:11]
	v_mfma_f32_16x16x32_bf16 v[60:63], v[158:161], v[224:227], v[60:63]
	v_mfma_f32_16x16x32_bf16 v[56:59], v[166:169], v[224:227], v[56:59]
	v_mfma_f32_16x16x32_bf16 v[44:47], v[158:161], v[232:235], v[44:47]
	v_mfma_f32_16x16x32_bf16 v[40:43], v[166:169], v[232:235], v[40:43]
	v_mfma_f32_16x16x32_bf16 v[28:31], v[158:161], v[240:243], v[28:31]
	v_mfma_f32_16x16x32_bf16 v[24:27], v[166:169], v[240:243], v[24:27]
	v_mfma_f32_16x16x32_bf16 v[12:15], v[158:161], v[248:251], v[12:15]
	v_mfma_f32_16x16x32_bf16 v[8:11], v[166:169], v[248:251], v[8:11]
	s_setprio 0
	s_setprio 1
	v_mfma_f32_16x16x32_bf16 v[52:55], v[170:173], v[220:223], v[52:55]
	v_mfma_f32_16x16x32_bf16 v[48:51], v[178:181], v[220:223], v[48:51]
	v_mfma_f32_16x16x32_bf16 v[36:39], v[170:173], v[228:231], v[36:39]
	v_mfma_f32_16x16x32_bf16 v[32:35], v[178:181], v[228:231], v[32:35]
	v_mfma_f32_16x16x32_bf16 v[20:23], v[170:173], v[236:239], v[20:23]
	v_mfma_f32_16x16x32_bf16 v[16:19], v[178:181], v[236:239], v[16:19]
	v_mfma_f32_16x16x32_bf16 v[4:7], v[170:173], v[244:247], v[4:7]
	v_mfma_f32_16x16x32_bf16 v[0:3], v[178:181], v[244:247], v[0:3]
	v_mfma_f32_16x16x32_bf16 v[52:55], v[174:177], v[224:227], v[52:55]
	v_mfma_f32_16x16x32_bf16 v[48:51], v[182:185], v[224:227], v[48:51]
	v_mfma_f32_16x16x32_bf16 v[36:39], v[174:177], v[232:235], v[36:39]
	v_mfma_f32_16x16x32_bf16 v[32:35], v[182:185], v[232:235], v[32:35]
	v_mfma_f32_16x16x32_bf16 v[20:23], v[174:177], v[240:243], v[20:23]
	v_mfma_f32_16x16x32_bf16 v[16:19], v[182:185], v[240:243], v[16:19]
	v_mfma_f32_16x16x32_bf16 v[4:7], v[174:177], v[248:251], v[4:7]
	v_mfma_f32_16x16x32_bf16 v[0:3], v[182:185], v[248:251], v[0:3]
	s_setprio 0
	s_waitcnt vmcnt(4)
	s_barrier
	s_add_i32 s58, s58, 2
	s_add_u32 s34, s34, 0x100
	s_addc_u32 s35, s35, 0
	s_add_u32 s56, s56, 0x100
	s_addc_u32 s57, s57, 0
	s_cmp_gt_u32 s58, 29
	s_cbranch_scc0 .LBB0_761

.Lk64_epd_p6_l:
	ds_read_b128 v[32:35], v169 offset:0
	ds_read_b128 v[36:39], v169 offset:1024
	ds_read_b128 v[40:43], v169 offset:2048
	ds_read_b128 v[44:47], v169 offset:3072
	ds_read_b128 v[186:189], v171 offset:0
	ds_read_b128 v[190:193], v171 offset:1024
	ds_read_b128 v[194:197], v171 offset:2048
	ds_read_b128 v[198:201], v171 offset:3072
	ds_read_b128 v[202:205], v171 offset:4096
	ds_read_b128 v[206:209], v171 offset:5120
	ds_read_b128 v[210:213], v171 offset:6144
	ds_read_b128 v[214:217], v171 offset:7168
	ds_read_b128 v[220:223], v171 offset:16384
	ds_read_b128 v[224:227], v171 offset:17408
	ds_read_b128 v[228:231], v171 offset:18432
	ds_read_b128 v[232:235], v171 offset:19456
	ds_read_b128 v[236:239], v171 offset:20480
	ds_read_b128 v[240:243], v171 offset:21504
	ds_read_b128 v[244:247], v171 offset:22528
	ds_read_b128 v[248:251], v171 offset:23552
	s_nop 15
	s_nop 15
	s_waitcnt vmcnt(8) lgkmcnt(0)
	s_barrier
	ds_read_b128 v[162:165], v170 offset:0
	ds_read_b128 v[174:177], v170 offset:1024
	ds_read_b128 v[178:181], v170 offset:2048
	ds_read_b128 v[182:185], v170 offset:3072
	s_setprio 1
	v_mfma_f32_16x16x32_bf16 v[140:143], v[32:35], v[186:189], v[140:143]
	v_mfma_f32_16x16x32_bf16 v[136:139], v[40:43], v[186:189], v[136:139]
	v_mfma_f32_16x16x32_bf16 v[124:127], v[32:35], v[194:197], v[124:127]
	v_mfma_f32_16x16x32_bf16 v[120:123], v[40:43], v[194:197], v[120:123]
	v_mfma_f32_16x16x32_bf16 v[108:111], v[32:35], v[202:205], v[108:111]
	v_mfma_f32_16x16x32_bf16 v[104:107], v[40:43], v[202:205], v[104:107]
	v_mfma_f32_16x16x32_bf16 v[92:95], v[32:35], v[210:213], v[92:95]
	v_mfma_f32_16x16x32_bf16 v[88:91], v[40:43], v[210:213], v[88:91]
	v_mfma_f32_16x16x32_bf16 v[140:143], v[36:39], v[190:193], v[140:143]
	v_mfma_f32_16x16x32_bf16 v[136:139], v[44:47], v[190:193], v[136:139]
	v_mfma_f32_16x16x32_bf16 v[124:127], v[36:39], v[198:201], v[124:127]
	v_mfma_f32_16x16x32_bf16 v[120:123], v[44:47], v[198:201], v[120:123]
	v_mfma_f32_16x16x32_bf16 v[108:111], v[36:39], v[206:209], v[108:111]
	v_mfma_f32_16x16x32_bf16 v[104:107], v[44:47], v[206:209], v[104:107]
	v_mfma_f32_16x16x32_bf16 v[92:95], v[36:39], v[214:217], v[92:95]
	v_mfma_f32_16x16x32_bf16 v[88:91], v[44:47], v[214:217], v[88:91]
	s_setprio 0
	s_waitcnt lgkmcnt(0)
	s_setprio 1
	v_mfma_f32_16x16x32_bf16 v[132:135], v[162:165], v[186:189], v[132:135]
	v_mfma_f32_16x16x32_bf16 v[128:131], v[178:181], v[186:189], v[128:131]
	v_mfma_f32_16x16x32_bf16 v[116:119], v[162:165], v[194:197], v[116:119]
	v_mfma_f32_16x16x32_bf16 v[112:115], v[178:181], v[194:197], v[112:115]
	v_mfma_f32_16x16x32_bf16 v[100:103], v[162:165], v[202:205], v[100:103]
	v_mfma_f32_16x16x32_bf16 v[96:99], v[178:181], v[202:205], v[96:99]
	v_mfma_f32_16x16x32_bf16 v[84:87], v[162:165], v[210:213], v[84:87]
	v_mfma_f32_16x16x32_bf16 v[80:83], v[178:181], v[210:213], v[80:83]
	v_mfma_f32_16x16x32_bf16 v[132:135], v[174:177], v[190:193], v[132:135]
	v_mfma_f32_16x16x32_bf16 v[128:131], v[182:185], v[190:193], v[128:131]
	v_mfma_f32_16x16x32_bf16 v[116:119], v[174:177], v[198:201], v[116:119]
	v_mfma_f32_16x16x32_bf16 v[112:115], v[182:185], v[198:201], v[112:115]
	v_mfma_f32_16x16x32_bf16 v[100:103], v[174:177], v[206:209], v[100:103]
	v_mfma_f32_16x16x32_bf16 v[96:99], v[182:185], v[206:209], v[96:99]
	v_mfma_f32_16x16x32_bf16 v[84:87], v[174:177], v[214:217], v[84:87]
	v_mfma_f32_16x16x32_bf16 v[80:83], v[182:185], v[214:217], v[80:83]
	s_setprio 0
	s_setprio 1
	v_mfma_f32_16x16x32_bf16 v[76:79], v[32:35], v[220:223], v[76:79]
	v_mfma_f32_16x16x32_bf16 v[72:75], v[40:43], v[220:223], v[72:75]
	v_mfma_f32_16x16x32_bf16 v[60:63], v[32:35], v[228:231], v[60:63]
	v_mfma_f32_16x16x32_bf16 v[56:59], v[40:43], v[228:231], v[56:59]
	v_mfma_f32_16x16x32_bf16 v[28:31], v[32:35], v[236:239], v[28:31]
	v_mfma_f32_16x16x32_bf16 v[24:27], v[40:43], v[236:239], v[24:27]
	v_mfma_f32_16x16x32_bf16 v[12:15], v[32:35], v[244:247], v[12:15]
	v_mfma_f32_16x16x32_bf16 v[8:11], v[40:43], v[244:247], v[8:11]
	v_mfma_f32_16x16x32_bf16 v[76:79], v[36:39], v[224:227], v[76:79]
	v_mfma_f32_16x16x32_bf16 v[72:75], v[44:47], v[224:227], v[72:75]
	v_mfma_f32_16x16x32_bf16 v[60:63], v[36:39], v[232:235], v[60:63]
	v_mfma_f32_16x16x32_bf16 v[56:59], v[44:47], v[232:235], v[56:59]
	v_mfma_f32_16x16x32_bf16 v[28:31], v[36:39], v[240:243], v[28:31]
	v_mfma_f32_16x16x32_bf16 v[24:27], v[44:47], v[240:243], v[24:27]
	v_mfma_f32_16x16x32_bf16 v[12:15], v[36:39], v[248:251], v[12:15]
	v_mfma_f32_16x16x32_bf16 v[8:11], v[44:47], v[248:251], v[8:11]
	s_setprio 0
	s_setprio 1
	v_mfma_f32_16x16x32_bf16 v[68:71], v[162:165], v[220:223], v[68:71]
	v_mfma_f32_16x16x32_bf16 v[64:67], v[178:181], v[220:223], v[64:67]
	v_mfma_f32_16x16x32_bf16 v[52:55], v[162:165], v[228:231], v[52:55]
	v_mfma_f32_16x16x32_bf16 v[48:51], v[178:181], v[228:231], v[48:51]
	v_mfma_f32_16x16x32_bf16 v[20:23], v[162:165], v[236:239], v[20:23]
	v_mfma_f32_16x16x32_bf16 v[16:19], v[178:181], v[236:239], v[16:19]
	v_mfma_f32_16x16x32_bf16 v[4:7], v[162:165], v[244:247], v[4:7]
	v_mfma_f32_16x16x32_bf16 v[0:3], v[178:181], v[244:247], v[0:3]
	v_mfma_f32_16x16x32_bf16 v[68:71], v[174:177], v[224:227], v[68:71]
	v_mfma_f32_16x16x32_bf16 v[64:67], v[182:185], v[224:227], v[64:67]
	v_mfma_f32_16x16x32_bf16 v[52:55], v[174:177], v[232:235], v[52:55]
	v_mfma_f32_16x16x32_bf16 v[48:51], v[182:185], v[232:235], v[48:51]
	v_mfma_f32_16x16x32_bf16 v[20:23], v[174:177], v[240:243], v[20:23]
	v_mfma_f32_16x16x32_bf16 v[16:19], v[182:185], v[240:243], v[16:19]
	v_mfma_f32_16x16x32_bf16 v[4:7], v[174:177], v[248:251], v[4:7]
	v_mfma_f32_16x16x32_bf16 v[0:3], v[182:185], v[248:251], v[0:3]
	s_setprio 0
	s_waitcnt vmcnt(4)
	s_barrier
	s_add_u32 vcc_lo, s30, 0x0
	s_addc_u32 vcc_hi, s31, 0
	s_add_i32 m0, s37, 0x10000
	s_nop 0
	global_load_lds_dwordx4 v148, vcc
	s_add_i32 m0, s37, 0x12000
	s_nop 0
	global_load_lds_dwordx4 v144, vcc
	s_add_u32 vcc_lo, vcc_lo, 0x20000
	s_addc_u32 vcc_hi, vcc_hi, 0
	s_add_i32 m0, s37, 0x11000
	s_nop 0
	global_load_lds_dwordx4 v148, vcc
	s_add_i32 m0, s37, 0x13000
	s_nop 0
	global_load_lds_dwordx4 v144, vcc
	s_add_u32 vcc_lo, vcc_lo, 0x60000
	s_addc_u32 vcc_hi, vcc_hi, 0
	s_add_i32 m0, s37, 0x14000
	s_nop 0
	global_load_lds_dwordx4 v148, vcc
	s_add_i32 m0, s37, 0x16000
	s_nop 0
	global_load_lds_dwordx4 v144, vcc
	s_add_u32 vcc_lo, vcc_lo, 0x20000
	s_addc_u32 vcc_hi, vcc_hi, 0
	s_add_i32 m0, s37, 0x15000
	s_nop 0
	global_load_lds_dwordx4 v148, vcc
	s_add_i32 m0, s37, 0x17000
	s_nop 0
	global_load_lds_dwordx4 v144, vcc
	ds_read_b128 v[32:35], v169 offset:32768
	ds_read_b128 v[36:39], v169 offset:33792
	ds_read_b128 v[40:43], v169 offset:34816
	ds_read_b128 v[44:47], v169 offset:35840
	ds_read_b128 v[186:189], v171 offset:32768
	ds_read_b128 v[190:193], v171 offset:33792
	ds_read_b128 v[194:197], v171 offset:34816
	ds_read_b128 v[198:201], v171 offset:35840
	ds_read_b128 v[202:205], v171 offset:36864
	ds_read_b128 v[206:209], v171 offset:37888
	ds_read_b128 v[210:213], v171 offset:38912
	ds_read_b128 v[214:217], v171 offset:39936
	ds_read_b128 v[220:223], v171 offset:49152
	ds_read_b128 v[224:227], v171 offset:50176
	ds_read_b128 v[228:231], v171 offset:51200
	ds_read_b128 v[232:235], v171 offset:52224
	ds_read_b128 v[236:239], v171 offset:53248
	ds_read_b128 v[240:243], v171 offset:54272
	ds_read_b128 v[244:247], v171 offset:55296
	ds_read_b128 v[248:251], v171 offset:56320
	s_nop 15
	s_nop 15
	s_waitcnt vmcnt(8) lgkmcnt(0)
	s_barrier
	ds_read_b128 v[162:165], v170 offset:32768
	ds_read_b128 v[174:177], v170 offset:33792
	ds_read_b128 v[178:181], v170 offset:34816
	ds_read_b128 v[182:185], v170 offset:35840
	s_setprio 1
	v_mfma_f32_16x16x32_bf16 v[140:143], v[32:35], v[186:189], v[140:143]
	v_mfma_f32_16x16x32_bf16 v[136:139], v[40:43], v[186:189], v[136:139]
	v_mfma_f32_16x16x32_bf16 v[124:127], v[32:35], v[194:197], v[124:127]
	v_mfma_f32_16x16x32_bf16 v[120:123], v[40:43], v[194:197], v[120:123]
	v_mfma_f32_16x16x32_bf16 v[108:111], v[32:35], v[202:205], v[108:111]
	v_mfma_f32_16x16x32_bf16 v[104:107], v[40:43], v[202:205], v[104:107]
	v_mfma_f32_16x16x32_bf16 v[92:95], v[32:35], v[210:213], v[92:95]
	v_mfma_f32_16x16x32_bf16 v[88:91], v[40:43], v[210:213], v[88:91]
	v_mfma_f32_16x16x32_bf16 v[140:143], v[36:39], v[190:193], v[140:143]
	v_mfma_f32_16x16x32_bf16 v[136:139], v[44:47], v[190:193], v[136:139]
	v_mfma_f32_16x16x32_bf16 v[124:127], v[36:39], v[198:201], v[124:127]
	v_mfma_f32_16x16x32_bf16 v[120:123], v[44:47], v[198:201], v[120:123]
	v_mfma_f32_16x16x32_bf16 v[108:111], v[36:39], v[206:209], v[108:111]
	v_mfma_f32_16x16x32_bf16 v[104:107], v[44:47], v[206:209], v[104:107]
	v_mfma_f32_16x16x32_bf16 v[92:95], v[36:39], v[214:217], v[92:95]
	v_mfma_f32_16x16x32_bf16 v[88:91], v[44:47], v[214:217], v[88:91]
	s_setprio 0
	s_waitcnt lgkmcnt(0)
	s_setprio 1
	v_mfma_f32_16x16x32_bf16 v[132:135], v[162:165], v[186:189], v[132:135]
	v_mfma_f32_16x16x32_bf16 v[128:131], v[178:181], v[186:189], v[128:131]
	v_mfma_f32_16x16x32_bf16 v[116:119], v[162:165], v[194:197], v[116:119]
	v_mfma_f32_16x16x32_bf16 v[112:115], v[178:181], v[194:197], v[112:115]
	v_mfma_f32_16x16x32_bf16 v[100:103], v[162:165], v[202:205], v[100:103]
	v_mfma_f32_16x16x32_bf16 v[96:99], v[178:181], v[202:205], v[96:99]
	v_mfma_f32_16x16x32_bf16 v[84:87], v[162:165], v[210:213], v[84:87]
	v_mfma_f32_16x16x32_bf16 v[80:83], v[178:181], v[210:213], v[80:83]
	v_mfma_f32_16x16x32_bf16 v[132:135], v[174:177], v[190:193], v[132:135]
	v_mfma_f32_16x16x32_bf16 v[128:131], v[182:185], v[190:193], v[128:131]
	v_mfma_f32_16x16x32_bf16 v[116:119], v[174:177], v[198:201], v[116:119]
	v_mfma_f32_16x16x32_bf16 v[112:115], v[182:185], v[198:201], v[112:115]
	v_mfma_f32_16x16x32_bf16 v[100:103], v[174:177], v[206:209], v[100:103]
	v_mfma_f32_16x16x32_bf16 v[96:99], v[182:185], v[206:209], v[96:99]
	v_mfma_f32_16x16x32_bf16 v[84:87], v[174:177], v[214:217], v[84:87]
	v_mfma_f32_16x16x32_bf16 v[80:83], v[182:185], v[214:217], v[80:83]
	s_setprio 0
	s_setprio 1
	v_mfma_f32_16x16x32_bf16 v[76:79], v[32:35], v[220:223], v[76:79]
	v_mfma_f32_16x16x32_bf16 v[72:75], v[40:43], v[220:223], v[72:75]
	v_mfma_f32_16x16x32_bf16 v[60:63], v[32:35], v[228:231], v[60:63]
	v_mfma_f32_16x16x32_bf16 v[56:59], v[40:43], v[228:231], v[56:59]
	v_mfma_f32_16x16x32_bf16 v[28:31], v[32:35], v[236:239], v[28:31]
	v_mfma_f32_16x16x32_bf16 v[24:27], v[40:43], v[236:239], v[24:27]
	v_mfma_f32_16x16x32_bf16 v[12:15], v[32:35], v[244:247], v[12:15]
	v_mfma_f32_16x16x32_bf16 v[8:11], v[40:43], v[244:247], v[8:11]
	v_mfma_f32_16x16x32_bf16 v[76:79], v[36:39], v[224:227], v[76:79]
	v_mfma_f32_16x16x32_bf16 v[72:75], v[44:47], v[224:227], v[72:75]
	v_mfma_f32_16x16x32_bf16 v[60:63], v[36:39], v[232:235], v[60:63]
	v_mfma_f32_16x16x32_bf16 v[56:59], v[44:47], v[232:235], v[56:59]
	v_mfma_f32_16x16x32_bf16 v[28:31], v[36:39], v[240:243], v[28:31]
	v_mfma_f32_16x16x32_bf16 v[24:27], v[44:47], v[240:243], v[24:27]
	v_mfma_f32_16x16x32_bf16 v[12:15], v[36:39], v[248:251], v[12:15]
	v_mfma_f32_16x16x32_bf16 v[8:11], v[44:47], v[248:251], v[8:11]
	s_setprio 0
	s_setprio 1
	v_mfma_f32_16x16x32_bf16 v[68:71], v[162:165], v[220:223], v[68:71]
	v_mfma_f32_16x16x32_bf16 v[64:67], v[178:181], v[220:223], v[64:67]
	v_mfma_f32_16x16x32_bf16 v[52:55], v[162:165], v[228:231], v[52:55]
	v_mfma_f32_16x16x32_bf16 v[48:51], v[178:181], v[228:231], v[48:51]
	v_mfma_f32_16x16x32_bf16 v[20:23], v[162:165], v[236:239], v[20:23]
	v_mfma_f32_16x16x32_bf16 v[16:19], v[178:181], v[236:239], v[16:19]
	v_mfma_f32_16x16x32_bf16 v[4:7], v[162:165], v[244:247], v[4:7]
	v_mfma_f32_16x16x32_bf16 v[0:3], v[178:181], v[244:247], v[0:3]
	v_mfma_f32_16x16x32_bf16 v[68:71], v[174:177], v[224:227], v[68:71]
	v_mfma_f32_16x16x32_bf16 v[64:67], v[182:185], v[224:227], v[64:67]
	v_mfma_f32_16x16x32_bf16 v[52:55], v[174:177], v[232:235], v[52:55]
	v_mfma_f32_16x16x32_bf16 v[48:51], v[182:185], v[232:235], v[48:51]
	v_mfma_f32_16x16x32_bf16 v[20:23], v[174:177], v[240:243], v[20:23]
	v_mfma_f32_16x16x32_bf16 v[16:19], v[182:185], v[240:243], v[16:19]
	v_mfma_f32_16x16x32_bf16 v[4:7], v[174:177], v[248:251], v[4:7]
	v_mfma_f32_16x16x32_bf16 v[0:3], v[182:185], v[248:251], v[0:3]
	s_setprio 0
	s_waitcnt vmcnt(4)
	s_barrier
	s_add_i32 s56, s56, 2
	s_add_u32 s12, s12, 0x100
	s_addc_u32 s13, s13, 0
	s_add_u32 s54, s54, 0x100
	s_addc_u32 s55, s55, 0
	s_cmp_gt_u32 s56, 29
	s_cbranch_scc0 .LBB0_846
	s_branch .Lk64_done_p6

.Lk64_epd_p6_t:
	ds_read_b128 v[32:35], v169 offset:0
	ds_read_b128 v[36:39], v169 offset:1024
	ds_read_b128 v[40:43], v169 offset:2048
	ds_read_b128 v[44:47], v169 offset:3072
	ds_read_b128 v[162:165], v170 offset:0
	ds_read_b128 v[174:177], v170 offset:1024
	ds_read_b128 v[178:181], v170 offset:2048
	ds_read_b128 v[182:185], v170 offset:3072
	ds_read_b128 v[186:189], v171 offset:0
	ds_read_b128 v[190:193], v171 offset:1024
	ds_read_b128 v[194:197], v171 offset:2048
	ds_read_b128 v[198:201], v171 offset:3072
	ds_read_b128 v[202:205], v171 offset:4096
	ds_read_b128 v[206:209], v171 offset:5120
	ds_read_b128 v[210:213], v171 offset:6144
	ds_read_b128 v[214:217], v171 offset:7168
	ds_read_b128 v[220:223], v171 offset:16384
	ds_read_b128 v[224:227], v171 offset:17408
	ds_read_b128 v[228:231], v171 offset:18432
	ds_read_b128 v[232:235], v171 offset:19456
	ds_read_b128 v[236:239], v171 offset:20480
	ds_read_b128 v[240:243], v171 offset:21504
	ds_read_b128 v[244:247], v171 offset:22528
	ds_read_b128 v[248:251], v171 offset:23552
	s_nop 15
	s_nop 15
	s_waitcnt vmcnt(8) lgkmcnt(0)
	s_barrier
	s_setprio 1
	v_mfma_f32_16x16x32_bf16 v[140:143], v[32:35], v[186:189], v[140:143]
	v_mfma_f32_16x16x32_bf16 v[136:139], v[40:43], v[186:189], v[136:139]
	v_mfma_f32_16x16x32_bf16 v[124:127], v[32:35], v[194:197], v[124:127]
	v_mfma_f32_16x16x32_bf16 v[120:123], v[40:43], v[194:197], v[120:123]
	v_mfma_f32_16x16x32_bf16 v[108:111], v[32:35], v[202:205], v[108:111]
	v_mfma_f32_16x16x32_bf16 v[104:107], v[40:43], v[202:205], v[104:107]
	v_mfma_f32_16x16x32_bf16 v[92:95], v[32:35], v[210:213], v[92:95]
	v_mfma_f32_16x16x32_bf16 v[88:91], v[40:43], v[210:213], v[88:91]
	v_mfma_f32_16x16x32_bf16 v[140:143], v[36:39], v[190:193], v[140:143]
	v_mfma_f32_16x16x32_bf16 v[136:139], v[44:47], v[190:193], v[136:139]
	v_mfma_f32_16x16x32_bf16 v[124:127], v[36:39], v[198:201], v[124:127]
	v_mfma_f32_16x16x32_bf16 v[120:123], v[44:47], v[198:201], v[120:123]
	v_mfma_f32_16x16x32_bf16 v[108:111], v[36:39], v[206:209], v[108:111]
	v_mfma_f32_16x16x32_bf16 v[104:107], v[44:47], v[206:209], v[104:107]
	v_mfma_f32_16x16x32_bf16 v[92:95], v[36:39], v[214:217], v[92:95]
	v_mfma_f32_16x16x32_bf16 v[88:91], v[44:47], v[214:217], v[88:91]
	s_setprio 0
	s_setprio 1
	v_mfma_f32_16x16x32_bf16 v[132:135], v[162:165], v[186:189], v[132:135]
	v_mfma_f32_16x16x32_bf16 v[128:131], v[178:181], v[186:189], v[128:131]
	v_mfma_f32_16x16x32_bf16 v[116:119], v[162:165], v[194:197], v[116:119]
	v_mfma_f32_16x16x32_bf16 v[112:115], v[178:181], v[194:197], v[112:115]
	v_mfma_f32_16x16x32_bf16 v[100:103], v[162:165], v[202:205], v[100:103]
	v_mfma_f32_16x16x32_bf16 v[96:99], v[178:181], v[202:205], v[96:99]
	v_mfma_f32_16x16x32_bf16 v[84:87], v[162:165], v[210:213], v[84:87]
	v_mfma_f32_16x16x32_bf16 v[80:83], v[178:181], v[210:213], v[80:83]
	v_mfma_f32_16x16x32_bf16 v[132:135], v[174:177], v[190:193], v[132:135]
	v_mfma_f32_16x16x32_bf16 v[128:131], v[182:185], v[190:193], v[128:131]
	v_mfma_f32_16x16x32_bf16 v[116:119], v[174:177], v[198:201], v[116:119]
	v_mfma_f32_16x16x32_bf16 v[112:115], v[182:185], v[198:201], v[112:115]
	v_mfma_f32_16x16x32_bf16 v[100:103], v[174:177], v[206:209], v[100:103]
	v_mfma_f32_16x16x32_bf16 v[96:99], v[182:185], v[206:209], v[96:99]
	v_mfma_f32_16x16x32_bf16 v[84:87], v[174:177], v[214:217], v[84:87]
	v_mfma_f32_16x16x32_bf16 v[80:83], v[182:185], v[214:217], v[80:83]
	s_setprio 0
	s_setprio 1
	v_mfma_f32_16x16x32_bf16 v[76:79], v[32:35], v[220:223], v[76:79]
	v_mfma_f32_16x16x32_bf16 v[72:75], v[40:43], v[220:223], v[72:75]
	v_mfma_f32_16x16x32_bf16 v[60:63], v[32:35], v[228:231], v[60:63]
	v_mfma_f32_16x16x32_bf16 v[56:59], v[40:43], v[228:231], v[56:59]
	v_mfma_f32_16x16x32_bf16 v[28:31], v[32:35], v[236:239], v[28:31]
	v_mfma_f32_16x16x32_bf16 v[24:27], v[40:43], v[236:239], v[24:27]
	v_mfma_f32_16x16x32_bf16 v[12:15], v[32:35], v[244:247], v[12:15]
	v_mfma_f32_16x16x32_bf16 v[8:11], v[40:43], v[244:247], v[8:11]
	v_mfma_f32_16x16x32_bf16 v[76:79], v[36:39], v[224:227], v[76:79]
	v_mfma_f32_16x16x32_bf16 v[72:75], v[44:47], v[224:227], v[72:75]
	v_mfma_f32_16x16x32_bf16 v[60:63], v[36:39], v[232:235], v[60:63]
	v_mfma_f32_16x16x32_bf16 v[56:59], v[44:47], v[232:235], v[56:59]
	v_mfma_f32_16x16x32_bf16 v[28:31], v[36:39], v[240:243], v[28:31]
	v_mfma_f32_16x16x32_bf16 v[24:27], v[44:47], v[240:243], v[24:27]
	v_mfma_f32_16x16x32_bf16 v[12:15], v[36:39], v[248:251], v[12:15]
	v_mfma_f32_16x16x32_bf16 v[8:11], v[44:47], v[248:251], v[8:11]
	s_setprio 0
	s_setprio 1
	v_mfma_f32_16x16x32_bf16 v[68:71], v[162:165], v[220:223], v[68:71]
	v_mfma_f32_16x16x32_bf16 v[64:67], v[178:181], v[220:223], v[64:67]
	v_mfma_f32_16x16x32_bf16 v[52:55], v[162:165], v[228:231], v[52:55]
	v_mfma_f32_16x16x32_bf16 v[48:51], v[178:181], v[228:231], v[48:51]
	v_mfma_f32_16x16x32_bf16 v[20:23], v[162:165], v[236:239], v[20:23]
	v_mfma_f32_16x16x32_bf16 v[16:19], v[178:181], v[236:239], v[16:19]
	v_mfma_f32_16x16x32_bf16 v[4:7], v[162:165], v[244:247], v[4:7]
	v_mfma_f32_16x16x32_bf16 v[0:3], v[178:181], v[244:247], v[0:3]
	v_mfma_f32_16x16x32_bf16 v[68:71], v[174:177], v[224:227], v[68:71]
	v_mfma_f32_16x16x32_bf16 v[64:67], v[182:185], v[224:227], v[64:67]
	v_mfma_f32_16x16x32_bf16 v[52:55], v[174:177], v[232:235], v[52:55]
	v_mfma_f32_16x16x32_bf16 v[48:51], v[182:185], v[232:235], v[48:51]
	v_mfma_f32_16x16x32_bf16 v[20:23], v[174:177], v[240:243], v[20:23]
	v_mfma_f32_16x16x32_bf16 v[16:19], v[182:185], v[240:243], v[16:19]
	v_mfma_f32_16x16x32_bf16 v[4:7], v[174:177], v[248:251], v[4:7]
	v_mfma_f32_16x16x32_bf16 v[0:3], v[182:185], v[248:251], v[0:3]
	s_setprio 0
	s_waitcnt vmcnt(4)
	s_barrier
	s_add_u32 vcc_lo, s34, 0x0
	s_addc_u32 vcc_hi, s35, 0
	s_add_i32 m0, s37, 0x2000
	s_nop 0
	global_load_lds_dwordx4 v146, vcc
	s_add_u32 vcc_lo, vcc_lo, 0x20000
	s_addc_u32 vcc_hi, vcc_hi, 0
	s_add_i32 m0, s37, 0x1000
	s_nop 0
	global_load_lds_dwordx4 v150, vcc
	s_add_u32 vcc_lo, vcc_lo, 0x60000
	s_addc_u32 vcc_hi, vcc_hi, 0
	s_add_i32 m0, s37, 0x6000
	s_nop 0
	global_load_lds_dwordx4 v146, vcc
	s_add_u32 vcc_lo, vcc_lo, 0x20000
	s_addc_u32 vcc_hi, vcc_hi, 0
	s_add_i32 m0, s37, 0x5000
	s_nop 0
	global_load_lds_dwordx4 v150, vcc
	s_add_u32 vcc_lo, s34, 0x80
	s_addc_u32 vcc_hi, s35, 0
	s_add_i32 m0, s37, 0x8000
	s_nop 0
	global_load_lds_dwordx4 v150, vcc
	s_sub_u32 vcc_lo, vcc_lo, 0x20000
	s_subb_u32 vcc_hi, vcc_hi, 0
	s_add_i32 m0, s37, 0x7000
	s_nop 0
	global_load_lds_dwordx4 v150, vcc
	s_add_u32 vcc_lo, vcc_lo, 0xa0000
	s_addc_u32 vcc_hi, vcc_hi, 0
	s_add_i32 m0, s37, 0xc000
	s_nop 0
	global_load_lds_dwordx4 v150, vcc
	s_sub_u32 vcc_lo, vcc_lo, 0x20000
	s_subb_u32 vcc_hi, vcc_hi, 0
	s_add_i32 m0, s37, 0xb000
	s_nop 0
	global_load_lds_dwordx4 v150, vcc
	ds_read_b128 v[32:35], v169 offset:32768
	ds_read_b128 v[36:39], v169 offset:33792
	ds_read_b128 v[40:43], v169 offset:34816
	ds_read_b128 v[44:47], v169 offset:35840
	ds_read_b128 v[162:165], v170 offset:32768
	ds_read_b128 v[174:177], v170 offset:33792
	ds_read_b128 v[178:181], v170 offset:34816
	ds_read_b128 v[182:185], v170 offset:35840
	ds_read_b128 v[186:189], v171 offset:32768
	ds_read_b128 v[190:193], v171 offset:33792
	ds_read_b128 v[194:197], v171 offset:34816
	ds_read_b128 v[198:201], v171 offset:35840
	ds_read_b128 v[202:205], v171 offset:36864
	ds_read_b128 v[206:209], v171 offset:37888
	ds_read_b128 v[210:213], v171 offset:38912
	ds_read_b128 v[214:217], v171 offset:39936
	ds_read_b128 v[220:223], v171 offset:49152
	ds_read_b128 v[224:227], v171 offset:50176
	ds_read_b128 v[228:231], v171 offset:51200
	ds_read_b128 v[232:235], v171 offset:52224
	ds_read_b128 v[236:239], v171 offset:53248
	ds_read_b128 v[240:243], v171 offset:54272
	ds_read_b128 v[244:247], v171 offset:55296
	ds_read_b128 v[248:251], v171 offset:56320
	s_nop 15
	s_nop 15
	s_waitcnt vmcnt(8) lgkmcnt(0)
	s_barrier
	s_setprio 1
	v_mfma_f32_16x16x32_bf16 v[140:143], v[32:35], v[186:189], v[140:143]
	v_mfma_f32_16x16x32_bf16 v[136:139], v[40:43], v[186:189], v[136:139]
	v_mfma_f32_16x16x32_bf16 v[124:127], v[32:35], v[194:197], v[124:127]
	v_mfma_f32_16x16x32_bf16 v[120:123], v[40:43], v[194:197], v[120:123]
	v_mfma_f32_16x16x32_bf16 v[108:111], v[32:35], v[202:205], v[108:111]
	v_mfma_f32_16x16x32_bf16 v[104:107], v[40:43], v[202:205], v[104:107]
	v_mfma_f32_16x16x32_bf16 v[92:95], v[32:35], v[210:213], v[92:95]
	v_mfma_f32_16x16x32_bf16 v[88:91], v[40:43], v[210:213], v[88:91]
	v_mfma_f32_16x16x32_bf16 v[140:143], v[36:39], v[190:193], v[140:143]
	v_mfma_f32_16x16x32_bf16 v[136:139], v[44:47], v[190:193], v[136:139]
	v_mfma_f32_16x16x32_bf16 v[124:127], v[36:39], v[198:201], v[124:127]
	v_mfma_f32_16x16x32_bf16 v[120:123], v[44:47], v[198:201], v[120:123]
	v_mfma_f32_16x16x32_bf16 v[108:111], v[36:39], v[206:209], v[108:111]
	v_mfma_f32_16x16x32_bf16 v[104:107], v[44:47], v[206:209], v[104:107]
	v_mfma_f32_16x16x32_bf16 v[92:95], v[36:39], v[214:217], v[92:95]
	v_mfma_f32_16x16x32_bf16 v[88:91], v[44:47], v[214:217], v[88:91]
	s_setprio 0
	s_setprio 1
	v_mfma_f32_16x16x32_bf16 v[132:135], v[162:165], v[186:189], v[132:135]
	v_mfma_f32_16x16x32_bf16 v[128:131], v[178:181], v[186:189], v[128:131]
	v_mfma_f32_16x16x32_bf16 v[116:119], v[162:165], v[194:197], v[116:119]
	v_mfma_f32_16x16x32_bf16 v[112:115], v[178:181], v[194:197], v[112:115]
	v_mfma_f32_16x16x32_bf16 v[100:103], v[162:165], v[202:205], v[100:103]
	v_mfma_f32_16x16x32_bf16 v[96:99], v[178:181], v[202:205], v[96:99]
	v_mfma_f32_16x16x32_bf16 v[84:87], v[162:165], v[210:213], v[84:87]
	v_mfma_f32_16x16x32_bf16 v[80:83], v[178:181], v[210:213], v[80:83]
	v_mfma_f32_16x16x32_bf16 v[132:135], v[174:177], v[190:193], v[132:135]
	v_mfma_f32_16x16x32_bf16 v[128:131], v[182:185], v[190:193], v[128:131]
	v_mfma_f32_16x16x32_bf16 v[116:119], v[174:177], v[198:201], v[116:119]
	v_mfma_f32_16x16x32_bf16 v[112:115], v[182:185], v[198:201], v[112:115]
	v_mfma_f32_16x16x32_bf16 v[100:103], v[174:177], v[206:209], v[100:103]
	v_mfma_f32_16x16x32_bf16 v[96:99], v[182:185], v[206:209], v[96:99]
	v_mfma_f32_16x16x32_bf16 v[84:87], v[174:177], v[214:217], v[84:87]
	v_mfma_f32_16x16x32_bf16 v[80:83], v[182:185], v[214:217], v[80:83]
	s_setprio 0
	s_setprio 1
	v_mfma_f32_16x16x32_bf16 v[76:79], v[32:35], v[220:223], v[76:79]
	v_mfma_f32_16x16x32_bf16 v[72:75], v[40:43], v[220:223], v[72:75]
	v_mfma_f32_16x16x32_bf16 v[60:63], v[32:35], v[228:231], v[60:63]
	v_mfma_f32_16x16x32_bf16 v[56:59], v[40:43], v[228:231], v[56:59]
	v_mfma_f32_16x16x32_bf16 v[28:31], v[32:35], v[236:239], v[28:31]
	v_mfma_f32_16x16x32_bf16 v[24:27], v[40:43], v[236:239], v[24:27]
	v_mfma_f32_16x16x32_bf16 v[12:15], v[32:35], v[244:247], v[12:15]
	v_mfma_f32_16x16x32_bf16 v[8:11], v[40:43], v[244:247], v[8:11]
	v_mfma_f32_16x16x32_bf16 v[76:79], v[36:39], v[224:227], v[76:79]
	v_mfma_f32_16x16x32_bf16 v[72:75], v[44:47], v[224:227], v[72:75]
	v_mfma_f32_16x16x32_bf16 v[60:63], v[36:39], v[232:235], v[60:63]
	v_mfma_f32_16x16x32_bf16 v[56:59], v[44:47], v[232:235], v[56:59]
	v_mfma_f32_16x16x32_bf16 v[28:31], v[36:39], v[240:243], v[28:31]
	v_mfma_f32_16x16x32_bf16 v[24:27], v[44:47], v[240:243], v[24:27]
	v_mfma_f32_16x16x32_bf16 v[12:15], v[36:39], v[248:251], v[12:15]
	v_mfma_f32_16x16x32_bf16 v[8:11], v[44:47], v[248:251], v[8:11]
	s_setprio 0
	s_setprio 1
	v_mfma_f32_16x16x32_bf16 v[68:71], v[162:165], v[220:223], v[68:71]
	v_mfma_f32_16x16x32_bf16 v[64:67], v[178:181], v[220:223], v[64:67]
	v_mfma_f32_16x16x32_bf16 v[52:55], v[162:165], v[228:231], v[52:55]
	v_mfma_f32_16x16x32_bf16 v[48:51], v[178:181], v[228:231], v[48:51]
	v_mfma_f32_16x16x32_bf16 v[20:23], v[162:165], v[236:239], v[20:23]
	v_mfma_f32_16x16x32_bf16 v[16:19], v[178:181], v[236:239], v[16:19]
	v_mfma_f32_16x16x32_bf16 v[4:7], v[162:165], v[244:247], v[4:7]
	v_mfma_f32_16x16x32_bf16 v[0:3], v[178:181], v[244:247], v[0:3]
	v_mfma_f32_16x16x32_bf16 v[68:71], v[174:177], v[224:227], v[68:71]
	v_mfma_f32_16x16x32_bf16 v[64:67], v[182:185], v[224:227], v[64:67]
	v_mfma_f32_16x16x32_bf16 v[52:55], v[174:177], v[232:235], v[52:55]
	v_mfma_f32_16x16x32_bf16 v[48:51], v[182:185], v[232:235], v[48:51]
	v_mfma_f32_16x16x32_bf16 v[20:23], v[174:177], v[240:243], v[20:23]
	v_mfma_f32_16x16x32_bf16 v[16:19], v[182:185], v[240:243], v[16:19]
	v_mfma_f32_16x16x32_bf16 v[4:7], v[174:177], v[248:251], v[4:7]
	v_mfma_f32_16x16x32_bf16 v[0:3], v[182:185], v[248:251], v[0:3]
	s_setprio 0
	s_waitcnt vmcnt(4)
	s_barrier
	s_add_i32 s56, s56, 2
	s_add_u32 s12, s12, 0x100
	s_addc_u32 s13, s13, 0
	s_add_u32 s54, s54, 0x100
	s_addc_u32 s55, s55, 0
	s_cmp_gt_u32 s56, 29
	s_cbranch_scc0 .LBB0_846

.LBB0_940:
	s_add_u32 s24, s22, 0x100
	s_addc_u32 s25, s23, 0
	s_cmpk_eq_i32 s56, 0x54
	s_cselect_b32 s29, s19, s25
	s_cselect_b32 s28, s18, s24
	s_cselect_b32 s27, s21, s47
	s_cselect_b32 s26, s20, s46
	s_and_b64 vcc, exec, s[12:13]
	s_cbranch_vccz .Lk64_trail_p7
	s_sub_u32 vcc_lo, s46, 0x80
	s_subb_u32 vcc_hi, s47, 0
	s_add_i32 m0, s30, 0x18000
	s_nop 0
	global_load_lds_dwordx4 v130, vcc
	s_add_i32 m0, s30, 0x1a000
	s_nop 0
	global_load_lds_dwordx4 v134, vcc
	s_add_u32 vcc_lo, vcc_lo, 0x58000
	s_addc_u32 vcc_hi, vcc_hi, 0
	s_add_i32 m0, s30, 0x19000
	s_nop 0
	global_load_lds_dwordx4 v130, vcc
	s_add_i32 m0, s30, 0x1b000
	s_nop 0
	global_load_lds_dwordx4 v134, vcc
	s_add_u32 vcc_lo, vcc_lo, 0x108000
	s_addc_u32 vcc_hi, vcc_hi, 0
	s_add_i32 m0, s30, 0x1c000
	s_nop 0
	global_load_lds_dwordx4 v130, vcc
	s_add_i32 m0, s30, 0x1e000
	s_nop 0
	global_load_lds_dwordx4 v134, vcc
	s_add_u32 vcc_lo, vcc_lo, 0x58000
	s_addc_u32 vcc_hi, vcc_hi, 0
	s_add_i32 m0, s30, 0x1d000
	s_nop 0
	global_load_lds_dwordx4 v130, vcc
	s_add_i32 m0, s30, 0x1f000
	s_nop 0
	global_load_lds_dwordx4 v134, vcc
	ds_read_b128 v[144:147], v185 offset:0
	ds_read_b128 v[148:151], v185 offset:1024
	ds_read_b128 v[152:155], v185 offset:2048
	ds_read_b128 v[156:159], v185 offset:3072
	ds_read_b128 v[176:179], v187 offset:0
	ds_read_b128 v[190:193], v187 offset:1024
	ds_read_b128 v[194:197], v187 offset:2048
	ds_read_b128 v[198:201], v187 offset:3072
	ds_read_b128 v[202:205], v187 offset:4096
	ds_read_b128 v[206:209], v187 offset:5120
	ds_read_b128 v[210:213], v187 offset:6144
	ds_read_b128 v[214:217], v187 offset:7168
	ds_read_b128 v[220:223], v187 offset:16384
	ds_read_b128 v[224:227], v187 offset:17408
	ds_read_b128 v[228:231], v187 offset:18432
	ds_read_b128 v[232:235], v187 offset:19456
	ds_read_b128 v[236:239], v187 offset:20480
	ds_read_b128 v[240:243], v187 offset:21504
	ds_read_b128 v[244:247], v187 offset:22528
	ds_read_b128 v[248:251], v187 offset:23552
	s_nop 15
	s_nop 15
	s_waitcnt vmcnt(8) lgkmcnt(0)
	s_barrier
	ds_read_b128 v[160:163], v186 offset:0
	ds_read_b128 v[164:167], v186 offset:1024
	ds_read_b128 v[168:171], v186 offset:2048
	ds_read_b128 v[172:175], v186 offset:3072
	s_setprio 1
	v_mfma_f32_16x16x32_bf16 v[72:75], v[144:147], v[176:179], v[72:75]
	v_mfma_f32_16x16x32_bf16 v[76:79], v[152:155], v[176:179], v[76:79]
	v_mfma_f32_16x16x32_bf16 v[96:99], v[144:147], v[194:197], v[96:99]
	v_mfma_f32_16x16x32_bf16 v[100:103], v[152:155], v[194:197], v[100:103]
	v_mfma_f32_16x16x32_bf16 v[120:123], v[144:147], v[202:205], v[120:123]
	v_mfma_f32_16x16x32_bf16 v[124:127], v[152:155], v[202:205], v[124:127]
	v_mfma_f32_16x16x32_bf16 v[92:95], v[144:147], v[210:213], v[92:95]
	v_mfma_f32_16x16x32_bf16 v[84:87], v[152:155], v[210:213], v[84:87]
	v_mfma_f32_16x16x32_bf16 v[72:75], v[148:151], v[190:193], v[72:75]
	v_mfma_f32_16x16x32_bf16 v[76:79], v[156:159], v[190:193], v[76:79]
	v_mfma_f32_16x16x32_bf16 v[96:99], v[148:151], v[198:201], v[96:99]
	v_mfma_f32_16x16x32_bf16 v[100:103], v[156:159], v[198:201], v[100:103]
	v_mfma_f32_16x16x32_bf16 v[120:123], v[148:151], v[206:209], v[120:123]
	v_mfma_f32_16x16x32_bf16 v[124:127], v[156:159], v[206:209], v[124:127]
	v_mfma_f32_16x16x32_bf16 v[92:95], v[148:151], v[214:217], v[92:95]
	v_mfma_f32_16x16x32_bf16 v[84:87], v[156:159], v[214:217], v[84:87]
	s_setprio 0
	s_waitcnt lgkmcnt(0)
	s_setprio 1
	v_mfma_f32_16x16x32_bf16 v[80:83], v[160:163], v[176:179], v[80:83]
	v_mfma_f32_16x16x32_bf16 v[88:91], v[168:171], v[176:179], v[88:91]
	v_mfma_f32_16x16x32_bf16 v[108:111], v[160:163], v[194:197], v[108:111]
	v_mfma_f32_16x16x32_bf16 v[112:115], v[168:171], v[194:197], v[112:115]
	v_mfma_f32_16x16x32_bf16 v[116:119], v[160:163], v[202:205], v[116:119]
	v_mfma_f32_16x16x32_bf16 v[104:107], v[168:171], v[202:205], v[104:107]
	v_mfma_f32_16x16x32_bf16 v[68:71], v[160:163], v[210:213], v[68:71]
	v_mfma_f32_16x16x32_bf16 v[64:67], v[168:171], v[210:213], v[64:67]
	v_mfma_f32_16x16x32_bf16 v[80:83], v[164:167], v[190:193], v[80:83]
	v_mfma_f32_16x16x32_bf16 v[88:91], v[172:175], v[190:193], v[88:91]
	v_mfma_f32_16x16x32_bf16 v[108:111], v[164:167], v[198:201], v[108:111]
	v_mfma_f32_16x16x32_bf16 v[112:115], v[172:175], v[198:201], v[112:115]
	v_mfma_f32_16x16x32_bf16 v[116:119], v[164:167], v[206:209], v[116:119]
	v_mfma_f32_16x16x32_bf16 v[104:107], v[172:175], v[206:209], v[104:107]
	v_mfma_f32_16x16x32_bf16 v[68:71], v[164:167], v[214:217], v[68:71]
	v_mfma_f32_16x16x32_bf16 v[64:67], v[172:175], v[214:217], v[64:67]
	s_setprio 0
	s_setprio 1
	v_mfma_f32_16x16x32_bf16 v[60:63], v[144:147], v[220:223], v[60:63]
	v_mfma_f32_16x16x32_bf16 v[56:59], v[152:155], v[220:223], v[56:59]
	v_mfma_f32_16x16x32_bf16 v[44:47], v[144:147], v[228:231], v[44:47]
	v_mfma_f32_16x16x32_bf16 v[40:43], v[152:155], v[228:231], v[40:43]
	v_mfma_f32_16x16x32_bf16 v[28:31], v[144:147], v[236:239], v[28:31]
	v_mfma_f32_16x16x32_bf16 v[24:27], v[152:155], v[236:239], v[24:27]
	v_mfma_f32_16x16x32_bf16 v[12:15], v[144:147], v[244:247], v[12:15]
	v_mfma_f32_16x16x32_bf16 v[8:11], v[152:155], v[244:247], v[8:11]
	v_mfma_f32_16x16x32_bf16 v[60:63], v[148:151], v[224:227], v[60:63]
	v_mfma_f32_16x16x32_bf16 v[56:59], v[156:159], v[224:227], v[56:59]
	v_mfma_f32_16x16x32_bf16 v[44:47], v[148:151], v[232:235], v[44:47]
	v_mfma_f32_16x16x32_bf16 v[40:43], v[156:159], v[232:235], v[40:43]
	v_mfma_f32_16x16x32_bf16 v[28:31], v[148:151], v[240:243], v[28:31]
	v_mfma_f32_16x16x32_bf16 v[24:27], v[156:159], v[240:243], v[24:27]
	v_mfma_f32_16x16x32_bf16 v[12:15], v[148:151], v[248:251], v[12:15]
	v_mfma_f32_16x16x32_bf16 v[8:11], v[156:159], v[248:251], v[8:11]
	s_setprio 0
	s_setprio 1
	v_mfma_f32_16x16x32_bf16 v[52:55], v[160:163], v[220:223], v[52:55]
	v_mfma_f32_16x16x32_bf16 v[48:51], v[168:171], v[220:223], v[48:51]
	v_mfma_f32_16x16x32_bf16 v[36:39], v[160:163], v[228:231], v[36:39]
	v_mfma_f32_16x16x32_bf16 v[32:35], v[168:171], v[228:231], v[32:35]
	v_mfma_f32_16x16x32_bf16 v[20:23], v[160:163], v[236:239], v[20:23]
	v_mfma_f32_16x16x32_bf16 v[16:19], v[168:171], v[236:239], v[16:19]
	v_mfma_f32_16x16x32_bf16 v[4:7], v[160:163], v[244:247], v[4:7]
	v_mfma_f32_16x16x32_bf16 v[0:3], v[168:171], v[244:247], v[0:3]
	v_mfma_f32_16x16x32_bf16 v[52:55], v[164:167], v[224:227], v[52:55]
	v_mfma_f32_16x16x32_bf16 v[48:51], v[172:175], v[224:227], v[48:51]
	v_mfma_f32_16x16x32_bf16 v[36:39], v[164:167], v[232:235], v[36:39]
	v_mfma_f32_16x16x32_bf16 v[32:35], v[172:175], v[232:235], v[32:35]
	v_mfma_f32_16x16x32_bf16 v[20:23], v[164:167], v[240:243], v[20:23]
	v_mfma_f32_16x16x32_bf16 v[16:19], v[172:175], v[240:243], v[16:19]
	v_mfma_f32_16x16x32_bf16 v[4:7], v[164:167], v[248:251], v[4:7]
	v_mfma_f32_16x16x32_bf16 v[0:3], v[172:175], v[248:251], v[0:3]
	s_setprio 0
	s_waitcnt vmcnt(4)
	s_barrier
	s_add_u32 vcc_lo, s26, 0x0
	s_addc_u32 vcc_hi, s27, 0
	s_add_i32 m0, s30, 0x10000
	s_nop 0
	global_load_lds_dwordx4 v130, vcc
	s_add_i32 m0, s30, 0x12000
	s_nop 0
	global_load_lds_dwordx4 v134, vcc
	s_add_u32 vcc_lo, vcc_lo, 0x58000
	s_addc_u32 vcc_hi, vcc_hi, 0
	s_add_i32 m0, s30, 0x11000
	s_nop 0
	global_load_lds_dwordx4 v130, vcc
	s_add_i32 m0, s30, 0x13000
	s_nop 0
	global_load_lds_dwordx4 v134, vcc
	s_add_u32 vcc_lo, vcc_lo, 0x108000
	s_addc_u32 vcc_hi, vcc_hi, 0
	s_add_i32 m0, s30, 0x14000
	s_nop 0
	global_load_lds_dwordx4 v130, vcc
	s_add_i32 m0, s30, 0x16000
	s_nop 0
	global_load_lds_dwordx4 v134, vcc
	s_add_u32 vcc_lo, vcc_lo, 0x58000
	s_addc_u32 vcc_hi, vcc_hi, 0
	s_add_i32 m0, s30, 0x15000
	s_nop 0
	global_load_lds_dwordx4 v130, vcc
	s_add_i32 m0, s30, 0x17000
	s_nop 0
	global_load_lds_dwordx4 v134, vcc
	ds_read_b128 v[144:147], v185 offset:32768
	ds_read_b128 v[148:151], v185 offset:33792
	ds_read_b128 v[152:155], v185 offset:34816
	ds_read_b128 v[156:159], v185 offset:35840
	ds_read_b128 v[176:179], v187 offset:32768
	ds_read_b128 v[190:193], v187 offset:33792
	ds_read_b128 v[194:197], v187 offset:34816
	ds_read_b128 v[198:201], v187 offset:35840
	ds_read_b128 v[202:205], v187 offset:36864
	ds_read_b128 v[206:209], v187 offset:37888
	ds_read_b128 v[210:213], v187 offset:38912
	ds_read_b128 v[214:217], v187 offset:39936
	ds_read_b128 v[220:223], v187 offset:49152
	ds_read_b128 v[224:227], v187 offset:50176
	ds_read_b128 v[228:231], v187 offset:51200
	ds_read_b128 v[232:235], v187 offset:52224
	ds_read_b128 v[236:239], v187 offset:53248
	ds_read_b128 v[240:243], v187 offset:54272
	ds_read_b128 v[244:247], v187 offset:55296
	ds_read_b128 v[248:251], v187 offset:56320
	s_nop 15
	s_nop 15
	s_waitcnt vmcnt(8) lgkmcnt(0)
	s_barrier
	ds_read_b128 v[160:163], v186 offset:32768
	ds_read_b128 v[164:167], v186 offset:33792
	ds_read_b128 v[168:171], v186 offset:34816
	ds_read_b128 v[172:175], v186 offset:35840
	s_setprio 1
	v_mfma_f32_16x16x32_bf16 v[72:75], v[144:147], v[176:179], v[72:75]
	v_mfma_f32_16x16x32_bf16 v[76:79], v[152:155], v[176:179], v[76:79]
	v_mfma_f32_16x16x32_bf16 v[96:99], v[144:147], v[194:197], v[96:99]
	v_mfma_f32_16x16x32_bf16 v[100:103], v[152:155], v[194:197], v[100:103]
	v_mfma_f32_16x16x32_bf16 v[120:123], v[144:147], v[202:205], v[120:123]
	v_mfma_f32_16x16x32_bf16 v[124:127], v[152:155], v[202:205], v[124:127]
	v_mfma_f32_16x16x32_bf16 v[92:95], v[144:147], v[210:213], v[92:95]
	v_mfma_f32_16x16x32_bf16 v[84:87], v[152:155], v[210:213], v[84:87]
	v_mfma_f32_16x16x32_bf16 v[72:75], v[148:151], v[190:193], v[72:75]
	v_mfma_f32_16x16x32_bf16 v[76:79], v[156:159], v[190:193], v[76:79]
	v_mfma_f32_16x16x32_bf16 v[96:99], v[148:151], v[198:201], v[96:99]
	v_mfma_f32_16x16x32_bf16 v[100:103], v[156:159], v[198:201], v[100:103]
	v_mfma_f32_16x16x32_bf16 v[120:123], v[148:151], v[206:209], v[120:123]
	v_mfma_f32_16x16x32_bf16 v[124:127], v[156:159], v[206:209], v[124:127]
	v_mfma_f32_16x16x32_bf16 v[92:95], v[148:151], v[214:217], v[92:95]
	v_mfma_f32_16x16x32_bf16 v[84:87], v[156:159], v[214:217], v[84:87]
	s_setprio 0
	s_waitcnt lgkmcnt(0)
	s_setprio 1
	v_mfma_f32_16x16x32_bf16 v[80:83], v[160:163], v[176:179], v[80:83]
	v_mfma_f32_16x16x32_bf16 v[88:91], v[168:171], v[176:179], v[88:91]
	v_mfma_f32_16x16x32_bf16 v[108:111], v[160:163], v[194:197], v[108:111]
	v_mfma_f32_16x16x32_bf16 v[112:115], v[168:171], v[194:197], v[112:115]
	v_mfma_f32_16x16x32_bf16 v[116:119], v[160:163], v[202:205], v[116:119]
	v_mfma_f32_16x16x32_bf16 v[104:107], v[168:171], v[202:205], v[104:107]
	v_mfma_f32_16x16x32_bf16 v[68:71], v[160:163], v[210:213], v[68:71]
	v_mfma_f32_16x16x32_bf16 v[64:67], v[168:171], v[210:213], v[64:67]
	v_mfma_f32_16x16x32_bf16 v[80:83], v[164:167], v[190:193], v[80:83]
	v_mfma_f32_16x16x32_bf16 v[88:91], v[172:175], v[190:193], v[88:91]
	v_mfma_f32_16x16x32_bf16 v[108:111], v[164:167], v[198:201], v[108:111]
	v_mfma_f32_16x16x32_bf16 v[112:115], v[172:175], v[198:201], v[112:115]
	v_mfma_f32_16x16x32_bf16 v[116:119], v[164:167], v[206:209], v[116:119]
	v_mfma_f32_16x16x32_bf16 v[104:107], v[172:175], v[206:209], v[104:107]
	v_mfma_f32_16x16x32_bf16 v[68:71], v[164:167], v[214:217], v[68:71]
	v_mfma_f32_16x16x32_bf16 v[64:67], v[172:175], v[214:217], v[64:67]
	s_setprio 0
	s_setprio 1
	v_mfma_f32_16x16x32_bf16 v[60:63], v[144:147], v[220:223], v[60:63]
	v_mfma_f32_16x16x32_bf16 v[56:59], v[152:155], v[220:223], v[56:59]
	v_mfma_f32_16x16x32_bf16 v[44:47], v[144:147], v[228:231], v[44:47]
	v_mfma_f32_16x16x32_bf16 v[40:43], v[152:155], v[228:231], v[40:43]
	v_mfma_f32_16x16x32_bf16 v[28:31], v[144:147], v[236:239], v[28:31]
	v_mfma_f32_16x16x32_bf16 v[24:27], v[152:155], v[236:239], v[24:27]
	v_mfma_f32_16x16x32_bf16 v[12:15], v[144:147], v[244:247], v[12:15]
	v_mfma_f32_16x16x32_bf16 v[8:11], v[152:155], v[244:247], v[8:11]
	v_mfma_f32_16x16x32_bf16 v[60:63], v[148:151], v[224:227], v[60:63]
	v_mfma_f32_16x16x32_bf16 v[56:59], v[156:159], v[224:227], v[56:59]
	v_mfma_f32_16x16x32_bf16 v[44:47], v[148:151], v[232:235], v[44:47]
	v_mfma_f32_16x16x32_bf16 v[40:43], v[156:159], v[232:235], v[40:43]
	v_mfma_f32_16x16x32_bf16 v[28:31], v[148:151], v[240:243], v[28:31]
	v_mfma_f32_16x16x32_bf16 v[24:27], v[156:159], v[240:243], v[24:27]
	v_mfma_f32_16x16x32_bf16 v[12:15], v[148:151], v[248:251], v[12:15]
	v_mfma_f32_16x16x32_bf16 v[8:11], v[156:159], v[248:251], v[8:11]
	s_setprio 0
	s_setprio 1
	v_mfma_f32_16x16x32_bf16 v[52:55], v[160:163], v[220:223], v[52:55]
	v_mfma_f32_16x16x32_bf16 v[48:51], v[168:171], v[220:223], v[48:51]
	v_mfma_f32_16x16x32_bf16 v[36:39], v[160:163], v[228:231], v[36:39]
	v_mfma_f32_16x16x32_bf16 v[32:35], v[168:171], v[228:231], v[32:35]
	v_mfma_f32_16x16x32_bf16 v[20:23], v[160:163], v[236:239], v[20:23]
	v_mfma_f32_16x16x32_bf16 v[16:19], v[168:171], v[236:239], v[16:19]
	v_mfma_f32_16x16x32_bf16 v[4:7], v[160:163], v[244:247], v[4:7]
	v_mfma_f32_16x16x32_bf16 v[0:3], v[168:171], v[244:247], v[0:3]
	v_mfma_f32_16x16x32_bf16 v[52:55], v[164:167], v[224:227], v[52:55]
	v_mfma_f32_16x16x32_bf16 v[48:51], v[172:175], v[224:227], v[48:51]
	v_mfma_f32_16x16x32_bf16 v[36:39], v[164:167], v[232:235], v[36:39]
	v_mfma_f32_16x16x32_bf16 v[32:35], v[172:175], v[232:235], v[32:35]
	v_mfma_f32_16x16x32_bf16 v[20:23], v[164:167], v[240:243], v[20:23]
	v_mfma_f32_16x16x32_bf16 v[16:19], v[172:175], v[240:243], v[16:19]
	v_mfma_f32_16x16x32_bf16 v[4:7], v[164:167], v[248:251], v[4:7]
	v_mfma_f32_16x16x32_bf16 v[0:3], v[172:175], v[248:251], v[0:3]
	s_setprio 0
	s_waitcnt vmcnt(4)
	s_barrier
	s_add_i32 s56, s56, 2
	s_add_u32 s46, s46, 0x100
	s_addc_u32 s47, s47, 0
	s_cmpk_gt_u32 s56, 0x55
	s_mov_b64 s[22:23], s[24:25]
	s_cbranch_scc0 .LBB0_940
	s_branch .Lk64_done_p7
.Lk64_trail_p7:
	s_add_u32 vcc_lo, s22, 0x80
	s_addc_u32 vcc_hi, s23, 0
	s_add_i32 m0, s30, 0xa000
	s_nop 0
	global_load_lds_dwordx4 v132, vcc
	s_add_u32 vcc_lo, vcc_lo, 0x58000
	s_addc_u32 vcc_hi, vcc_hi, 0
	s_add_i32 m0, s30, 0x9000
	s_nop 0
	global_load_lds_dwordx4 v128, vcc
	s_add_u32 vcc_lo, vcc_lo, 0x108000
	s_addc_u32 vcc_hi, vcc_hi, 0
	s_add_i32 m0, s30, 0xe000
	s_nop 0
	global_load_lds_dwordx4 v132, vcc
	s_add_u32 vcc_lo, vcc_lo, 0x58000
	s_addc_u32 vcc_hi, vcc_hi, 0
	s_add_i32 m0, s30, 0xd000
	s_nop 0
	global_load_lds_dwordx4 v128, vcc
	s_add_u32 vcc_lo, s28, 0x0
	s_addc_u32 vcc_hi, s29, 0
	s_mov_b32 m0, s30
	s_nop 0
	global_load_lds_dwordx4 v128, vcc
	s_sub_u32 vcc_lo, vcc_lo, 0x58000
	s_subb_u32 vcc_hi, vcc_hi, 0
	s_sub_i32 m0, s30, 0x1000
	s_nop 0
	global_load_lds_dwordx4 v128, vcc
	s_add_u32 vcc_lo, vcc_lo, 0x1b8000
	s_addc_u32 vcc_hi, vcc_hi, 0
	s_add_i32 m0, s30, 0x4000
	s_nop 0
	global_load_lds_dwordx4 v128, vcc
	s_sub_u32 vcc_lo, vcc_lo, 0x58000
	s_subb_u32 vcc_hi, vcc_hi, 0
	s_add_i32 m0, s30, 0x3000
	s_nop 0
	global_load_lds_dwordx4 v128, vcc
	ds_read_b128 v[144:147], v185 offset:0
	ds_read_b128 v[148:151], v185 offset:1024
	ds_read_b128 v[152:155], v185 offset:2048
	ds_read_b128 v[156:159], v185 offset:3072
	ds_read_b128 v[160:163], v186 offset:0
	ds_read_b128 v[164:167], v186 offset:1024
	ds_read_b128 v[168:171], v186 offset:2048
	ds_read_b128 v[172:175], v186 offset:3072
	ds_read_b128 v[176:179], v187 offset:0
	ds_read_b128 v[190:193], v187 offset:1024
	ds_read_b128 v[194:197], v187 offset:2048
	ds_read_b128 v[198:201], v187 offset:3072
	ds_read_b128 v[202:205], v187 offset:4096
	ds_read_b128 v[206:209], v187 offset:5120
	ds_read_b128 v[210:213], v187 offset:6144
	ds_read_b128 v[214:217], v187 offset:7168
	ds_read_b128 v[220:223], v187 offset:16384
	ds_read_b128 v[224:227], v187 offset:17408
	ds_read_b128 v[228:231], v187 offset:18432
	ds_read_b128 v[232:235], v187 offset:19456
	ds_read_b128 v[236:239], v187 offset:20480
	ds_read_b128 v[240:243], v187 offset:21504
	ds_read_b128 v[244:247], v187 offset:22528
	ds_read_b128 v[248:251], v187 offset:23552
	s_nop 15
	s_nop 15
	s_waitcnt vmcnt(8) lgkmcnt(0)
	s_barrier
	s_setprio 1
	v_mfma_f32_16x16x32_bf16 v[72:75], v[144:147], v[176:179], v[72:75]
	v_mfma_f32_16x16x32_bf16 v[76:79], v[152:155], v[176:179], v[76:79]
	v_mfma_f32_16x16x32_bf16 v[96:99], v[144:147], v[194:197], v[96:99]
	v_mfma_f32_16x16x32_bf16 v[100:103], v[152:155], v[194:197], v[100:103]
	v_mfma_f32_16x16x32_bf16 v[120:123], v[144:147], v[202:205], v[120:123]
	v_mfma_f32_16x16x32_bf16 v[124:127], v[152:155], v[202:205], v[124:127]
	v_mfma_f32_16x16x32_bf16 v[92:95], v[144:147], v[210:213], v[92:95]
	v_mfma_f32_16x16x32_bf16 v[84:87], v[152:155], v[210:213], v[84:87]
	v_mfma_f32_16x16x32_bf16 v[72:75], v[148:151], v[190:193], v[72:75]
	v_mfma_f32_16x16x32_bf16 v[76:79], v[156:159], v[190:193], v[76:79]
	v_mfma_f32_16x16x32_bf16 v[96:99], v[148:151], v[198:201], v[96:99]
	v_mfma_f32_16x16x32_bf16 v[100:103], v[156:159], v[198:201], v[100:103]
	v_mfma_f32_16x16x32_bf16 v[120:123], v[148:151], v[206:209], v[120:123]
	v_mfma_f32_16x16x32_bf16 v[124:127], v[156:159], v[206:209], v[124:127]
	v_mfma_f32_16x16x32_bf16 v[92:95], v[148:151], v[214:217], v[92:95]
	v_mfma_f32_16x16x32_bf16 v[84:87], v[156:159], v[214:217], v[84:87]
	s_setprio 0
	s_setprio 1
	v_mfma_f32_16x16x32_bf16 v[80:83], v[160:163], v[176:179], v[80:83]
	v_mfma_f32_16x16x32_bf16 v[88:91], v[168:171], v[176:179], v[88:91]
	v_mfma_f32_16x16x32_bf16 v[108:111], v[160:163], v[194:197], v[108:111]
	v_mfma_f32_16x16x32_bf16 v[112:115], v[168:171], v[194:197], v[112:115]
	v_mfma_f32_16x16x32_bf16 v[116:119], v[160:163], v[202:205], v[116:119]
	v_mfma_f32_16x16x32_bf16 v[104:107], v[168:171], v[202:205], v[104:107]
	v_mfma_f32_16x16x32_bf16 v[68:71], v[160:163], v[210:213], v[68:71]
	v_mfma_f32_16x16x32_bf16 v[64:67], v[168:171], v[210:213], v[64:67]
	v_mfma_f32_16x16x32_bf16 v[80:83], v[164:167], v[190:193], v[80:83]
	v_mfma_f32_16x16x32_bf16 v[88:91], v[172:175], v[190:193], v[88:91]
	v_mfma_f32_16x16x32_bf16 v[108:111], v[164:167], v[198:201], v[108:111]
	v_mfma_f32_16x16x32_bf16 v[112:115], v[172:175], v[198:201], v[112:115]
	v_mfma_f32_16x16x32_bf16 v[116:119], v[164:167], v[206:209], v[116:119]
	v_mfma_f32_16x16x32_bf16 v[104:107], v[172:175], v[206:209], v[104:107]
	v_mfma_f32_16x16x32_bf16 v[68:71], v[164:167], v[214:217], v[68:71]
	v_mfma_f32_16x16x32_bf16 v[64:67], v[172:175], v[214:217], v[64:67]
	s_setprio 0
	s_setprio 1
	v_mfma_f32_16x16x32_bf16 v[60:63], v[144:147], v[220:223], v[60:63]
	v_mfma_f32_16x16x32_bf16 v[56:59], v[152:155], v[220:223], v[56:59]
	v_mfma_f32_16x16x32_bf16 v[44:47], v[144:147], v[228:231], v[44:47]
	v_mfma_f32_16x16x32_bf16 v[40:43], v[152:155], v[228:231], v[40:43]
	v_mfma_f32_16x16x32_bf16 v[28:31], v[144:147], v[236:239], v[28:31]
	v_mfma_f32_16x16x32_bf16 v[24:27], v[152:155], v[236:239], v[24:27]
	v_mfma_f32_16x16x32_bf16 v[12:15], v[144:147], v[244:247], v[12:15]
	v_mfma_f32_16x16x32_bf16 v[8:11], v[152:155], v[244:247], v[8:11]
	v_mfma_f32_16x16x32_bf16 v[60:63], v[148:151], v[224:227], v[60:63]
	v_mfma_f32_16x16x32_bf16 v[56:59], v[156:159], v[224:227], v[56:59]
	v_mfma_f32_16x16x32_bf16 v[44:47], v[148:151], v[232:235], v[44:47]
	v_mfma_f32_16x16x32_bf16 v[40:43], v[156:159], v[232:235], v[40:43]
	v_mfma_f32_16x16x32_bf16 v[28:31], v[148:151], v[240:243], v[28:31]
	v_mfma_f32_16x16x32_bf16 v[24:27], v[156:159], v[240:243], v[24:27]
	v_mfma_f32_16x16x32_bf16 v[12:15], v[148:151], v[248:251], v[12:15]
	v_mfma_f32_16x16x32_bf16 v[8:11], v[156:159], v[248:251], v[8:11]
	s_setprio 0
	s_setprio 1
	v_mfma_f32_16x16x32_bf16 v[52:55], v[160:163], v[220:223], v[52:55]
	v_mfma_f32_16x16x32_bf16 v[48:51], v[168:171], v[220:223], v[48:51]
	v_mfma_f32_16x16x32_bf16 v[36:39], v[160:163], v[228:231], v[36:39]
	v_mfma_f32_16x16x32_bf16 v[32:35], v[168:171], v[228:231], v[32:35]
	v_mfma_f32_16x16x32_bf16 v[20:23], v[160:163], v[236:239], v[20:23]
	v_mfma_f32_16x16x32_bf16 v[16:19], v[168:171], v[236:239], v[16:19]
	v_mfma_f32_16x16x32_bf16 v[4:7], v[160:163], v[244:247], v[4:7]
	v_mfma_f32_16x16x32_bf16 v[0:3], v[168:171], v[244:247], v[0:3]
	v_mfma_f32_16x16x32_bf16 v[52:55], v[164:167], v[224:227], v[52:55]
	v_mfma_f32_16x16x32_bf16 v[48:51], v[172:175], v[224:227], v[48:51]
	v_mfma_f32_16x16x32_bf16 v[36:39], v[164:167], v[232:235], v[36:39]
	v_mfma_f32_16x16x32_bf16 v[32:35], v[172:175], v[232:235], v[32:35]
	v_mfma_f32_16x16x32_bf16 v[20:23], v[164:167], v[240:243], v[20:23]
	v_mfma_f32_16x16x32_bf16 v[16:19], v[172:175], v[240:243], v[16:19]
	v_mfma_f32_16x16x32_bf16 v[4:7], v[164:167], v[248:251], v[4:7]
	v_mfma_f32_16x16x32_bf16 v[0:3], v[172:175], v[248:251], v[0:3]
	s_setprio 0
	s_waitcnt vmcnt(4)
	s_barrier
	s_add_u32 vcc_lo, s28, 0x0
	s_addc_u32 vcc_hi, s29, 0
	s_add_i32 m0, s30, 0x2000
	s_nop 0
	global_load_lds_dwordx4 v132, vcc
	s_add_u32 vcc_lo, vcc_lo, 0x58000
	s_addc_u32 vcc_hi, vcc_hi, 0
	s_add_i32 m0, s30, 0x1000
	s_nop 0
	global_load_lds_dwordx4 v128, vcc
	s_add_u32 vcc_lo, vcc_lo, 0x108000
	s_addc_u32 vcc_hi, vcc_hi, 0
	s_add_i32 m0, s30, 0x6000
	s_nop 0
	global_load_lds_dwordx4 v132, vcc
	s_add_u32 vcc_lo, vcc_lo, 0x58000
	s_addc_u32 vcc_hi, vcc_hi, 0
	s_add_i32 m0, s30, 0x5000
	s_nop 0
	global_load_lds_dwordx4 v128, vcc
	s_add_u32 vcc_lo, s28, 0x80
	s_addc_u32 vcc_hi, s29, 0
	s_add_i32 m0, s30, 0x8000
	s_nop 0
	global_load_lds_dwordx4 v128, vcc
	s_sub_u32 vcc_lo, vcc_lo, 0x58000
	s_subb_u32 vcc_hi, vcc_hi, 0
	s_add_i32 m0, s30, 0x7000
	s_nop 0
	global_load_lds_dwordx4 v128, vcc
	s_add_u32 vcc_lo, vcc_lo, 0x1b8000
	s_addc_u32 vcc_hi, vcc_hi, 0
	s_add_i32 m0, s30, 0xc000
	s_nop 0
	global_load_lds_dwordx4 v128, vcc
	s_sub_u32 vcc_lo, vcc_lo, 0x58000
	s_subb_u32 vcc_hi, vcc_hi, 0
	s_add_i32 m0, s30, 0xb000
	s_nop 0
	global_load_lds_dwordx4 v128, vcc
	ds_read_b128 v[144:147], v185 offset:32768
	ds_read_b128 v[148:151], v185 offset:33792
	ds_read_b128 v[152:155], v185 offset:34816
	ds_read_b128 v[156:159], v185 offset:35840
	ds_read_b128 v[160:163], v186 offset:32768
	ds_read_b128 v[164:167], v186 offset:33792
	ds_read_b128 v[168:171], v186 offset:34816
	ds_read_b128 v[172:175], v186 offset:35840
	ds_read_b128 v[176:179], v187 offset:32768
	ds_read_b128 v[190:193], v187 offset:33792
	ds_read_b128 v[194:197], v187 offset:34816
	ds_read_b128 v[198:201], v187 offset:35840
	ds_read_b128 v[202:205], v187 offset:36864
	ds_read_b128 v[206:209], v187 offset:37888
	ds_read_b128 v[210:213], v187 offset:38912
	ds_read_b128 v[214:217], v187 offset:39936
	ds_read_b128 v[220:223], v187 offset:49152
	ds_read_b128 v[224:227], v187 offset:50176
	ds_read_b128 v[228:231], v187 offset:51200
	ds_read_b128 v[232:235], v187 offset:52224
	ds_read_b128 v[236:239], v187 offset:53248
	ds_read_b128 v[240:243], v187 offset:54272
	ds_read_b128 v[244:247], v187 offset:55296
	ds_read_b128 v[248:251], v187 offset:56320
	s_nop 15
	s_nop 15
	s_waitcnt vmcnt(8) lgkmcnt(0)
	s_barrier
	s_setprio 1
	v_mfma_f32_16x16x32_bf16 v[72:75], v[144:147], v[176:179], v[72:75]
	v_mfma_f32_16x16x32_bf16 v[76:79], v[152:155], v[176:179], v[76:79]
	v_mfma_f32_16x16x32_bf16 v[96:99], v[144:147], v[194:197], v[96:99]
	v_mfma_f32_16x16x32_bf16 v[100:103], v[152:155], v[194:197], v[100:103]
	v_mfma_f32_16x16x32_bf16 v[120:123], v[144:147], v[202:205], v[120:123]
	v_mfma_f32_16x16x32_bf16 v[124:127], v[152:155], v[202:205], v[124:127]
	v_mfma_f32_16x16x32_bf16 v[92:95], v[144:147], v[210:213], v[92:95]
	v_mfma_f32_16x16x32_bf16 v[84:87], v[152:155], v[210:213], v[84:87]
	v_mfma_f32_16x16x32_bf16 v[72:75], v[148:151], v[190:193], v[72:75]
	v_mfma_f32_16x16x32_bf16 v[76:79], v[156:159], v[190:193], v[76:79]
	v_mfma_f32_16x16x32_bf16 v[96:99], v[148:151], v[198:201], v[96:99]
	v_mfma_f32_16x16x32_bf16 v[100:103], v[156:159], v[198:201], v[100:103]
	v_mfma_f32_16x16x32_bf16 v[120:123], v[148:151], v[206:209], v[120:123]
	v_mfma_f32_16x16x32_bf16 v[124:127], v[156:159], v[206:209], v[124:127]
	v_mfma_f32_16x16x32_bf16 v[92:95], v[148:151], v[214:217], v[92:95]
	v_mfma_f32_16x16x32_bf16 v[84:87], v[156:159], v[214:217], v[84:87]
	s_setprio 0
	s_setprio 1
	v_mfma_f32_16x16x32_bf16 v[80:83], v[160:163], v[176:179], v[80:83]
	v_mfma_f32_16x16x32_bf16 v[88:91], v[168:171], v[176:179], v[88:91]
	v_mfma_f32_16x16x32_bf16 v[108:111], v[160:163], v[194:197], v[108:111]
	v_mfma_f32_16x16x32_bf16 v[112:115], v[168:171], v[194:197], v[112:115]
	v_mfma_f32_16x16x32_bf16 v[116:119], v[160:163], v[202:205], v[116:119]
	v_mfma_f32_16x16x32_bf16 v[104:107], v[168:171], v[202:205], v[104:107]
	v_mfma_f32_16x16x32_bf16 v[68:71], v[160:163], v[210:213], v[68:71]
	v_mfma_f32_16x16x32_bf16 v[64:67], v[168:171], v[210:213], v[64:67]
	v_mfma_f32_16x16x32_bf16 v[80:83], v[164:167], v[190:193], v[80:83]
	v_mfma_f32_16x16x32_bf16 v[88:91], v[172:175], v[190:193], v[88:91]
	v_mfma_f32_16x16x32_bf16 v[108:111], v[164:167], v[198:201], v[108:111]
	v_mfma_f32_16x16x32_bf16 v[112:115], v[172:175], v[198:201], v[112:115]
	v_mfma_f32_16x16x32_bf16 v[116:119], v[164:167], v[206:209], v[116:119]
	v_mfma_f32_16x16x32_bf16 v[104:107], v[172:175], v[206:209], v[104:107]
	v_mfma_f32_16x16x32_bf16 v[68:71], v[164:167], v[214:217], v[68:71]
	v_mfma_f32_16x16x32_bf16 v[64:67], v[172:175], v[214:217], v[64:67]
	s_setprio 0
	s_setprio 1
	v_mfma_f32_16x16x32_bf16 v[60:63], v[144:147], v[220:223], v[60:63]
	v_mfma_f32_16x16x32_bf16 v[56:59], v[152:155], v[220:223], v[56:59]
	v_mfma_f32_16x16x32_bf16 v[44:47], v[144:147], v[228:231], v[44:47]
	v_mfma_f32_16x16x32_bf16 v[40:43], v[152:155], v[228:231], v[40:43]
	v_mfma_f32_16x16x32_bf16 v[28:31], v[144:147], v[236:239], v[28:31]
	v_mfma_f32_16x16x32_bf16 v[24:27], v[152:155], v[236:239], v[24:27]
	v_mfma_f32_16x16x32_bf16 v[12:15], v[144:147], v[244:247], v[12:15]
	v_mfma_f32_16x16x32_bf16 v[8:11], v[152:155], v[244:247], v[8:11]
	v_mfma_f32_16x16x32_bf16 v[60:63], v[148:151], v[224:227], v[60:63]
	v_mfma_f32_16x16x32_bf16 v[56:59], v[156:159], v[224:227], v[56:59]
	v_mfma_f32_16x16x32_bf16 v[44:47], v[148:151], v[232:235], v[44:47]
	v_mfma_f32_16x16x32_bf16 v[40:43], v[156:159], v[232:235], v[40:43]
	v_mfma_f32_16x16x32_bf16 v[28:31], v[148:151], v[240:243], v[28:31]
	v_mfma_f32_16x16x32_bf16 v[24:27], v[156:159], v[240:243], v[24:27]
	v_mfma_f32_16x16x32_bf16 v[12:15], v[148:151], v[248:251], v[12:15]
	v_mfma_f32_16x16x32_bf16 v[8:11], v[156:159], v[248:251], v[8:11]
	s_setprio 0
	s_setprio 1
	v_mfma_f32_16x16x32_bf16 v[52:55], v[160:163], v[220:223], v[52:55]
	v_mfma_f32_16x16x32_bf16 v[48:51], v[168:171], v[220:223], v[48:51]
	v_mfma_f32_16x16x32_bf16 v[36:39], v[160:163], v[228:231], v[36:39]
	v_mfma_f32_16x16x32_bf16 v[32:35], v[168:171], v[228:231], v[32:35]
	v_mfma_f32_16x16x32_bf16 v[20:23], v[160:163], v[236:239], v[20:23]
	v_mfma_f32_16x16x32_bf16 v[16:19], v[168:171], v[236:239], v[16:19]
	v_mfma_f32_16x16x32_bf16 v[4:7], v[160:163], v[244:247], v[4:7]
	v_mfma_f32_16x16x32_bf16 v[0:3], v[168:171], v[244:247], v[0:3]
	v_mfma_f32_16x16x32_bf16 v[52:55], v[164:167], v[224:227], v[52:55]
	v_mfma_f32_16x16x32_bf16 v[48:51], v[172:175], v[224:227], v[48:51]
	v_mfma_f32_16x16x32_bf16 v[36:39], v[164:167], v[232:235], v[36:39]
	v_mfma_f32_16x16x32_bf16 v[32:35], v[172:175], v[232:235], v[32:35]
	v_mfma_f32_16x16x32_bf16 v[20:23], v[164:167], v[240:243], v[20:23]
	v_mfma_f32_16x16x32_bf16 v[16:19], v[172:175], v[240:243], v[16:19]
	v_mfma_f32_16x16x32_bf16 v[4:7], v[164:167], v[248:251], v[4:7]
	v_mfma_f32_16x16x32_bf16 v[0:3], v[172:175], v[248:251], v[0:3]
	s_setprio 0
	s_waitcnt vmcnt(4)
	s_barrier
	s_add_i32 s56, s56, 2
	s_add_u32 s46, s46, 0x100
	s_addc_u32 s47, s47, 0
	s_cmpk_gt_u32 s56, 0x55
	s_mov_b64 s[22:23], s[24:25]
	s_cbranch_scc0 .LBB0_940
